# GEMM main loops: first K-iteration peeled with srcC=0 for each accumulator's first MFMA; 128 per-tile zero-init v_mov removed (11 loops)
# speedup vs baseline: 1.0167x; 1.0034x over previous
.LBB0_136:
	s_ashr_i32 s13, s12, 31
	s_lshl_b64 s[22:23], s[12:13], 20
	s_add_u32 s22, s2, s22
	s_addc_u32 s23, s3, s23
	s_and_b64 s[24:25], s[18:19], exec
	s_cselect_b32 s13, s23, s29
	s_cselect_b32 s43, s22, s28
	s_ashr_i32 s15, s14, 31
	s_lshl_b64 s[24:25], s[14:15], 20
	s_add_u32 s24, s20, s24
	s_addc_u32 s25, s21, s25
	s_and_b64 s[34:35], s[18:19], exec
	s_cselect_b32 s15, s25, s31
	s_cselect_b32 s44, s24, s30
	s_add_u32 s28, s28, 0x80080
	s_addc_u32 s29, s29, 0
	s_add_u32 s45, s30, 0x100
	s_addc_u32 s46, s31, 0
	s_mov_b32 s47, -2
	s_add_u32 s30, s28, 0xfff80080
	s_addc_u32 s31, s29, -1
	s_add_i32 s48, 0, 0x10000
	s_cmp_eq_u32 s47, 28
	s_cselect_b32 s35, s13, s31
	s_cselect_b32 s34, s43, s30
	v_add_u32_e32 v140, s48, v143
	s_cselect_b32 s31, s15, s46
	s_cselect_b32 s30, s44, s45
	s_add_i32 s50, 0, 0x14000
	ds_read_b128 v[146:149], v140
	ds_read_b128 v[150:153], v140 offset:1024
	ds_read_b128 v[154:157], v140 offset:2048
	ds_read_b128 v[158:161], v140 offset:3072
	v_add_u32_e32 v140, s50, v143
	ds_read_b128 v[162:165], v140
	ds_read_b128 v[166:169], v140 offset:1024
	ds_read_b128 v[170:173], v140 offset:2048
	ds_read_b128 v[178:181], v140 offset:3072
	s_add_i32 m0, s27, 0xc000
	ds_read_b128 v[182:185], v144
	ds_read_b128 v[186:189], v144 offset:1024
	ds_read_b128 v[190:193], v144 offset:2048
	ds_read_b128 v[194:197], v144 offset:3072
	ds_read_b128 v[198:201], v144 offset:4096
	ds_read_b128 v[202:205], v144 offset:5120
	ds_read_b128 v[206:209], v144 offset:6144
	ds_read_b128 v[220:223], v144 offset:7168
	global_load_lds_dwordx4 v136, s[28:29]
	s_add_i32 m0, s27, 0xe000
	s_nop 0
	global_load_lds_dwordx4 v138, s[28:29]
	s_waitcnt vmcnt(8)
	s_waitcnt lgkmcnt(0)
	s_barrier
	s_setprio 1
	s_waitcnt lgkmcnt(0)
	v_mfma_f32_16x16x32_bf16 v[124:127], v[146:149], v[182:185], 0
	v_mfma_f32_16x16x32_bf16 v[120:123], v[154:157], v[182:185], 0
	v_mfma_f32_16x16x32_bf16 v[108:111], v[146:149], v[190:193], 0
	v_mfma_f32_16x16x32_bf16 v[104:107], v[154:157], v[190:193], 0
	v_mfma_f32_16x16x32_bf16 v[92:95], v[146:149], v[198:201], 0
	v_mfma_f32_16x16x32_bf16 v[88:91], v[154:157], v[198:201], 0
	v_mfma_f32_16x16x32_bf16 v[76:79], v[146:149], v[206:209], 0
	v_mfma_f32_16x16x32_bf16 v[72:75], v[154:157], v[206:209], 0
	v_mfma_f32_16x16x32_bf16 v[124:127], v[150:153], v[186:189], v[124:127]
	v_mfma_f32_16x16x32_bf16 v[120:123], v[158:161], v[186:189], v[120:123]
	v_mfma_f32_16x16x32_bf16 v[108:111], v[150:153], v[194:197], v[108:111]
	v_mfma_f32_16x16x32_bf16 v[104:107], v[158:161], v[194:197], v[104:107]
	v_mfma_f32_16x16x32_bf16 v[92:95], v[150:153], v[202:205], v[92:95]
	v_mfma_f32_16x16x32_bf16 v[88:91], v[158:161], v[202:205], v[88:91]
	v_mfma_f32_16x16x32_bf16 v[76:79], v[150:153], v[220:223], v[76:79]
	v_mfma_f32_16x16x32_bf16 v[72:75], v[158:161], v[220:223], v[72:75]
	s_setprio 0
	s_setprio 1
	v_mfma_f32_16x16x32_bf16 v[116:119], v[162:165], v[182:185], 0
	v_mfma_f32_16x16x32_bf16 v[112:115], v[170:173], v[182:185], 0
	v_mfma_f32_16x16x32_bf16 v[100:103], v[162:165], v[190:193], 0
	v_mfma_f32_16x16x32_bf16 v[96:99], v[170:173], v[190:193], 0
	v_mfma_f32_16x16x32_bf16 v[84:87], v[162:165], v[198:201], 0
	v_mfma_f32_16x16x32_bf16 v[80:83], v[170:173], v[198:201], 0
	v_mfma_f32_16x16x32_bf16 v[68:71], v[162:165], v[206:209], 0
	v_mfma_f32_16x16x32_bf16 v[64:67], v[170:173], v[206:209], 0
	v_mfma_f32_16x16x32_bf16 v[116:119], v[166:169], v[186:189], v[116:119]
	v_mfma_f32_16x16x32_bf16 v[112:115], v[178:181], v[186:189], v[112:115]
	v_mfma_f32_16x16x32_bf16 v[100:103], v[166:169], v[194:197], v[100:103]
	v_mfma_f32_16x16x32_bf16 v[96:99], v[178:181], v[194:197], v[96:99]
	v_mfma_f32_16x16x32_bf16 v[84:87], v[166:169], v[202:205], v[84:87]
	v_mfma_f32_16x16x32_bf16 v[80:83], v[178:181], v[202:205], v[80:83]
	v_mfma_f32_16x16x32_bf16 v[68:71], v[166:169], v[220:223], v[68:71]
	v_mfma_f32_16x16x32_bf16 v[64:67], v[178:181], v[220:223], v[64:67]
	s_setprio 0
	s_barrier
	s_add_i32 s48, s48, s26
	s_mov_b32 m0, s48
	ds_read_b128 v[182:185], v144 offset:16384
	ds_read_b128 v[186:189], v144 offset:17408
	ds_read_b128 v[190:193], v144 offset:18432
	ds_read_b128 v[194:197], v144 offset:19456
	ds_read_b128 v[198:201], v144 offset:20480
	ds_read_b128 v[202:205], v144 offset:21504
	ds_read_b128 v[206:209], v144 offset:22528
	ds_read_b128 v[220:223], v144 offset:23552
	global_load_lds_dwordx4 v132, s[30:31]
	s_add_i32 m0, s48, 0x2000
	s_add_u32 s48, s30, 0x80000
	s_addc_u32 s49, s31, 0
	s_add_i32 s50, s50, s26
	global_load_lds_dwordx4 v128, s[30:31]
	s_mov_b32 m0, s50
	s_nop 0
	global_load_lds_dwordx4 v132, s[48:49]
	s_add_i32 m0, s50, 0x2000
	s_nop 0
	global_load_lds_dwordx4 v128, s[48:49]
	s_add_u32 s60, s34, 0x80
	s_addc_u32 s61, s35, 0
	s_mov_b32 m0, s27
	s_nop 0
	global_load_lds_dwordx4 v134, s[34:35]
	s_mov_b32 m0, s33
	s_nop 0
	global_load_lds_dwordx4 v130, s[34:35]
	s_waitcnt vmcnt(8)
	s_waitcnt lgkmcnt(0)
	s_barrier
	s_setprio 1
	s_waitcnt lgkmcnt(0)
	v_mfma_f32_16x16x32_bf16 v[60:63], v[146:149], v[182:185], 0
	v_mfma_f32_16x16x32_bf16 v[56:59], v[154:157], v[182:185], 0
	v_mfma_f32_16x16x32_bf16 v[44:47], v[146:149], v[190:193], 0
	v_mfma_f32_16x16x32_bf16 v[40:43], v[154:157], v[190:193], 0
	v_mfma_f32_16x16x32_bf16 v[28:31], v[146:149], v[198:201], 0
	v_mfma_f32_16x16x32_bf16 v[24:27], v[154:157], v[198:201], 0
	v_mfma_f32_16x16x32_bf16 v[12:15], v[146:149], v[206:209], 0
	v_mfma_f32_16x16x32_bf16 v[8:11], v[154:157], v[206:209], 0
	v_mfma_f32_16x16x32_bf16 v[60:63], v[150:153], v[186:189], v[60:63]
	v_mfma_f32_16x16x32_bf16 v[56:59], v[158:161], v[186:189], v[56:59]
	v_mfma_f32_16x16x32_bf16 v[44:47], v[150:153], v[194:197], v[44:47]
	v_mfma_f32_16x16x32_bf16 v[40:43], v[158:161], v[194:197], v[40:43]
	v_mfma_f32_16x16x32_bf16 v[28:31], v[150:153], v[202:205], v[28:31]
	v_mfma_f32_16x16x32_bf16 v[24:27], v[158:161], v[202:205], v[24:27]
	v_mfma_f32_16x16x32_bf16 v[12:15], v[150:153], v[220:223], v[12:15]
	v_mfma_f32_16x16x32_bf16 v[8:11], v[158:161], v[220:223], v[8:11]
	s_setprio 0
	s_setprio 1
	v_mfma_f32_16x16x32_bf16 v[52:55], v[162:165], v[182:185], 0
	v_mfma_f32_16x16x32_bf16 v[48:51], v[170:173], v[182:185], 0
	v_mfma_f32_16x16x32_bf16 v[36:39], v[162:165], v[190:193], 0
	v_mfma_f32_16x16x32_bf16 v[32:35], v[170:173], v[190:193], 0
	v_mfma_f32_16x16x32_bf16 v[20:23], v[162:165], v[198:201], 0
	v_mfma_f32_16x16x32_bf16 v[16:19], v[170:173], v[198:201], 0
	v_mfma_f32_16x16x32_bf16 v[4:7], v[162:165], v[206:209], 0
	v_mfma_f32_16x16x32_bf16 v[0:3], v[170:173], v[206:209], 0
	v_mfma_f32_16x16x32_bf16 v[52:55], v[166:169], v[186:189], v[52:55]
	v_mfma_f32_16x16x32_bf16 v[48:51], v[178:181], v[186:189], v[48:51]
	v_mfma_f32_16x16x32_bf16 v[36:39], v[166:169], v[194:197], v[36:39]
	v_mfma_f32_16x16x32_bf16 v[32:35], v[178:181], v[194:197], v[32:35]
	v_mfma_f32_16x16x32_bf16 v[20:23], v[166:169], v[202:205], v[20:23]
	v_mfma_f32_16x16x32_bf16 v[16:19], v[178:181], v[202:205], v[16:19]
	v_mfma_f32_16x16x32_bf16 v[4:7], v[166:169], v[220:223], v[4:7]
	v_mfma_f32_16x16x32_bf16 v[0:3], v[178:181], v[220:223], v[0:3]
	s_setprio 0
	s_barrier
	s_add_i32 s48, 0, 0x18000
	v_add_u32_e32 v145, s48, v143
	s_add_i32 s49, 0, 0x1c000
	ds_read_b128 v[146:149], v145
	ds_read_b128 v[150:153], v145 offset:1024
	ds_read_b128 v[154:157], v145 offset:2048
	ds_read_b128 v[158:161], v145 offset:3072
	v_add_u32_e32 v145, s49, v143
	ds_read_b128 v[162:165], v145
	ds_read_b128 v[166:169], v145 offset:1024
	ds_read_b128 v[170:173], v145 offset:2048
	ds_read_b128 v[178:181], v145 offset:3072
	s_add_u32 s34, s34, 0x80000
	s_addc_u32 s35, s35, 0
	s_mov_b32 m0, s36
	ds_read_b128 v[182:185], v144 offset:32768
	ds_read_b128 v[186:189], v144 offset:33792
	ds_read_b128 v[190:193], v144 offset:34816
	ds_read_b128 v[194:197], v144 offset:35840
	ds_read_b128 v[198:201], v144 offset:36864
	ds_read_b128 v[202:205], v144 offset:37888
	ds_read_b128 v[206:209], v144 offset:38912
	ds_read_b128 v[220:223], v144 offset:39936
	global_load_lds_dwordx4 v134, s[34:35]
	s_mov_b32 m0, s37
	s_nop 0
	global_load_lds_dwordx4 v130, s[34:35]
	s_waitcnt vmcnt(8)
	s_waitcnt lgkmcnt(0)
	s_barrier
	s_setprio 1
	s_waitcnt lgkmcnt(0)
	v_mfma_f32_16x16x32_bf16 v[124:127], v[146:149], v[182:185], v[124:127]
	v_mfma_f32_16x16x32_bf16 v[120:123], v[154:157], v[182:185], v[120:123]
	v_mfma_f32_16x16x32_bf16 v[108:111], v[146:149], v[190:193], v[108:111]
	v_mfma_f32_16x16x32_bf16 v[104:107], v[154:157], v[190:193], v[104:107]
	v_mfma_f32_16x16x32_bf16 v[92:95], v[146:149], v[198:201], v[92:95]
	v_mfma_f32_16x16x32_bf16 v[88:91], v[154:157], v[198:201], v[88:91]
	v_mfma_f32_16x16x32_bf16 v[76:79], v[146:149], v[206:209], v[76:79]
	v_mfma_f32_16x16x32_bf16 v[72:75], v[154:157], v[206:209], v[72:75]
	v_mfma_f32_16x16x32_bf16 v[124:127], v[150:153], v[186:189], v[124:127]
	v_mfma_f32_16x16x32_bf16 v[120:123], v[158:161], v[186:189], v[120:123]
	v_mfma_f32_16x16x32_bf16 v[108:111], v[150:153], v[194:197], v[108:111]
	v_mfma_f32_16x16x32_bf16 v[104:107], v[158:161], v[194:197], v[104:107]
	v_mfma_f32_16x16x32_bf16 v[92:95], v[150:153], v[202:205], v[92:95]
	v_mfma_f32_16x16x32_bf16 v[88:91], v[158:161], v[202:205], v[88:91]
	v_mfma_f32_16x16x32_bf16 v[76:79], v[150:153], v[220:223], v[76:79]
	v_mfma_f32_16x16x32_bf16 v[72:75], v[158:161], v[220:223], v[72:75]
	s_setprio 0
	s_setprio 1
	v_mfma_f32_16x16x32_bf16 v[116:119], v[162:165], v[182:185], v[116:119]
	v_mfma_f32_16x16x32_bf16 v[112:115], v[170:173], v[182:185], v[112:115]
	v_mfma_f32_16x16x32_bf16 v[100:103], v[162:165], v[190:193], v[100:103]
	v_mfma_f32_16x16x32_bf16 v[96:99], v[170:173], v[190:193], v[96:99]
	v_mfma_f32_16x16x32_bf16 v[84:87], v[162:165], v[198:201], v[84:87]
	v_mfma_f32_16x16x32_bf16 v[80:83], v[170:173], v[198:201], v[80:83]
	v_mfma_f32_16x16x32_bf16 v[68:71], v[162:165], v[206:209], v[68:71]
	v_mfma_f32_16x16x32_bf16 v[64:67], v[170:173], v[206:209], v[64:67]
	v_mfma_f32_16x16x32_bf16 v[116:119], v[166:169], v[186:189], v[116:119]
	v_mfma_f32_16x16x32_bf16 v[112:115], v[178:181], v[186:189], v[112:115]
	v_mfma_f32_16x16x32_bf16 v[100:103], v[166:169], v[194:197], v[100:103]
	v_mfma_f32_16x16x32_bf16 v[96:99], v[178:181], v[194:197], v[96:99]
	v_mfma_f32_16x16x32_bf16 v[84:87], v[166:169], v[202:205], v[84:87]
	v_mfma_f32_16x16x32_bf16 v[80:83], v[178:181], v[202:205], v[80:83]
	v_mfma_f32_16x16x32_bf16 v[68:71], v[166:169], v[220:223], v[68:71]
	v_mfma_f32_16x16x32_bf16 v[64:67], v[178:181], v[220:223], v[64:67]
	s_setprio 0
	s_barrier
	s_add_i32 s34, s48, s26
	s_mov_b32 m0, s34
	ds_read_b128 v[182:185], v144 offset:49152
	ds_read_b128 v[186:189], v144 offset:50176
	ds_read_b128 v[190:193], v144 offset:51200
	ds_read_b128 v[194:197], v144 offset:52224
	ds_read_b128 v[198:201], v144 offset:53248
	ds_read_b128 v[202:205], v144 offset:54272
	ds_read_b128 v[206:209], v144 offset:55296
	ds_read_b128 v[220:223], v144 offset:56320
	s_add_u32 s98, s30, 0x80
	s_addc_u32 s99, s31, 0
	global_load_lds_dwordx4 v132, s[98:99]
	s_add_i32 m0, s34, 0x2000
	s_add_u32 s30, s30, 0x80080
	s_addc_u32 s31, s31, 0
	s_add_i32 s34, s49, s26
	s_add_u32 s98, s30, 0xfff80000
	s_addc_u32 s99, s31, -1
	global_load_lds_dwordx4 v128, s[98:99]
	s_mov_b32 m0, s34
	s_nop 0
	global_load_lds_dwordx4 v132, s[30:31]
	s_add_i32 m0, s34, 0x2000
	s_nop 0
	global_load_lds_dwordx4 v128, s[30:31]
	s_mov_b32 m0, s38
	s_nop 0
	global_load_lds_dwordx4 v134, s[60:61]
	s_mov_b32 m0, s39
	s_nop 0
	global_load_lds_dwordx4 v130, s[60:61]
	s_waitcnt vmcnt(8)
	s_waitcnt lgkmcnt(0)
	s_barrier
	s_setprio 1
	s_waitcnt lgkmcnt(0)
	v_mfma_f32_16x16x32_bf16 v[60:63], v[146:149], v[182:185], v[60:63]
	v_mfma_f32_16x16x32_bf16 v[56:59], v[154:157], v[182:185], v[56:59]
	v_mfma_f32_16x16x32_bf16 v[44:47], v[146:149], v[190:193], v[44:47]
	v_mfma_f32_16x16x32_bf16 v[40:43], v[154:157], v[190:193], v[40:43]
	v_mfma_f32_16x16x32_bf16 v[28:31], v[146:149], v[198:201], v[28:31]
	v_mfma_f32_16x16x32_bf16 v[24:27], v[154:157], v[198:201], v[24:27]
	v_mfma_f32_16x16x32_bf16 v[12:15], v[146:149], v[206:209], v[12:15]
	v_mfma_f32_16x16x32_bf16 v[8:11], v[154:157], v[206:209], v[8:11]
	v_mfma_f32_16x16x32_bf16 v[60:63], v[150:153], v[186:189], v[60:63]
	v_mfma_f32_16x16x32_bf16 v[56:59], v[158:161], v[186:189], v[56:59]
	v_mfma_f32_16x16x32_bf16 v[44:47], v[150:153], v[194:197], v[44:47]
	v_mfma_f32_16x16x32_bf16 v[40:43], v[158:161], v[194:197], v[40:43]
	v_mfma_f32_16x16x32_bf16 v[28:31], v[150:153], v[202:205], v[28:31]
	v_mfma_f32_16x16x32_bf16 v[24:27], v[158:161], v[202:205], v[24:27]
	v_mfma_f32_16x16x32_bf16 v[12:15], v[150:153], v[220:223], v[12:15]
	v_mfma_f32_16x16x32_bf16 v[8:11], v[158:161], v[220:223], v[8:11]
	s_setprio 0
	s_setprio 1
	v_mfma_f32_16x16x32_bf16 v[52:55], v[162:165], v[182:185], v[52:55]
	v_mfma_f32_16x16x32_bf16 v[48:51], v[170:173], v[182:185], v[48:51]
	v_mfma_f32_16x16x32_bf16 v[36:39], v[162:165], v[190:193], v[36:39]
	v_mfma_f32_16x16x32_bf16 v[32:35], v[170:173], v[190:193], v[32:35]
	v_mfma_f32_16x16x32_bf16 v[20:23], v[162:165], v[198:201], v[20:23]
	v_mfma_f32_16x16x32_bf16 v[16:19], v[170:173], v[198:201], v[16:19]
	v_mfma_f32_16x16x32_bf16 v[4:7], v[162:165], v[206:209], v[4:7]
	v_mfma_f32_16x16x32_bf16 v[0:3], v[170:173], v[206:209], v[0:3]
	v_mfma_f32_16x16x32_bf16 v[52:55], v[166:169], v[186:189], v[52:55]
	v_mfma_f32_16x16x32_bf16 v[48:51], v[178:181], v[186:189], v[48:51]
	v_mfma_f32_16x16x32_bf16 v[36:39], v[166:169], v[194:197], v[36:39]
	v_mfma_f32_16x16x32_bf16 v[32:35], v[178:181], v[194:197], v[32:35]
	v_mfma_f32_16x16x32_bf16 v[20:23], v[166:169], v[202:205], v[20:23]
	v_mfma_f32_16x16x32_bf16 v[16:19], v[178:181], v[202:205], v[16:19]
	v_mfma_f32_16x16x32_bf16 v[4:7], v[166:169], v[220:223], v[4:7]
	v_mfma_f32_16x16x32_bf16 v[0:3], v[178:181], v[220:223], v[0:3]
	s_setprio 0
	s_barrier
	s_add_i32 s47, s47, 2
	s_add_u32 s28, s28, 0x100
	s_addc_u32 s29, s29, 0
	s_add_u32 s45, s45, 0x100
	s_addc_u32 s46, s46, 0
	s_cmp_gt_u32 s47, 29

.LBB0_207:
	s_ashr_i32 s53, s52, 31
	s_lshl_b64 s[14:15], s[52:53], 20
	s_add_u32 s68, s3, s14
	s_addc_u32 s69, s20, s15
	s_and_b64 s[14:15], s[56:57], exec
	s_cselect_b32 s23, s69, s1
	s_cselect_b32 s26, s68, s0
	s_ashr_i32 s55, s54, 31
	s_lshl_b64 s[14:15], s[54:55], 20
	s_add_u32 s70, s21, s14
	s_addc_u32 s71, s24, s15
	s_and_b64 s[14:15], s[56:57], exec
	s_cselect_b32 s33, s71, s13
	s_cselect_b32 s45, s70, s12
	s_add_u32 s0, s0, 0x80080
	s_addc_u32 s1, s1, 0
	s_add_u32 s50, s12, 0x100
	s_addc_u32 s51, s13, 0
	s_mov_b32 s53, -2
	s_add_u32 s12, s0, 0xfff80080
	s_addc_u32 s13, s1, -1
	s_add_i32 s55, 0, 0x10000
	s_cmp_eq_u32 s53, 28
	s_cselect_b32 s15, s23, s13
	s_cselect_b32 s14, s26, s12
	s_cselect_b32 s13, s33, s51
	s_cselect_b32 s12, s45, s50
	s_add_i32 s60, 0, 0x14000
	v_add_u32_e32 v136, s55, v197
	v_add_u32_e32 v156, s60, v197
	ds_read_b128 v[120:123], v136
	ds_read_b128 v[124:127], v136 offset:1024
	ds_read_b128 v[132:135], v136 offset:2048
	ds_read_b128 v[136:139], v136 offset:3072
	ds_read_b128 v[140:143], v156
	ds_read_b128 v[144:147], v156 offset:1024
	ds_read_b128 v[152:155], v156 offset:2048
	ds_read_b128 v[156:159], v156 offset:3072
	s_add_i32 m0, s27, 0xc000
	ds_read_b128 v[160:163], v199
	ds_read_b128 v[178:181], v199 offset:1024
	ds_read_b128 v[182:185], v199 offset:2048
	ds_read_b128 v[186:189], v199 offset:3072
	ds_read_b128 v[190:193], v199 offset:4096
	ds_read_b128 v[200:203], v199 offset:5120
	ds_read_b128 v[204:207], v199 offset:6144
	ds_read_b128 v[220:223], v199 offset:7168
	global_load_lds_dwordx4 v170, s[0:1]
	s_add_i32 m0, s27, 0xe000
	s_nop 0
	global_load_lds_dwordx4 v172, s[0:1]
	s_waitcnt vmcnt(8)
	s_waitcnt lgkmcnt(0)
	s_barrier
	s_setprio 1
	s_waitcnt lgkmcnt(0)
	v_mfma_f32_16x16x32_bf16 v[148:151], v[120:123], v[160:163], 0
	v_mfma_f32_16x16x32_bf16 v[128:131], v[132:135], v[160:163], 0
	v_mfma_f32_16x16x32_bf16 v[116:119], v[120:123], v[182:185], 0
	v_mfma_f32_16x16x32_bf16 v[112:115], v[132:135], v[182:185], 0
	v_mfma_f32_16x16x32_bf16 v[108:111], v[120:123], v[190:193], 0
	v_mfma_f32_16x16x32_bf16 v[104:107], v[132:135], v[190:193], 0
	v_mfma_f32_16x16x32_bf16 v[100:103], v[120:123], v[204:207], 0
	v_mfma_f32_16x16x32_bf16 v[96:99], v[132:135], v[204:207], 0
	v_mfma_f32_16x16x32_bf16 v[148:151], v[124:127], v[178:181], v[148:151]
	v_mfma_f32_16x16x32_bf16 v[128:131], v[136:139], v[178:181], v[128:131]
	v_mfma_f32_16x16x32_bf16 v[116:119], v[124:127], v[186:189], v[116:119]
	v_mfma_f32_16x16x32_bf16 v[112:115], v[136:139], v[186:189], v[112:115]
	v_mfma_f32_16x16x32_bf16 v[108:111], v[124:127], v[200:203], v[108:111]
	v_mfma_f32_16x16x32_bf16 v[104:107], v[136:139], v[200:203], v[104:107]
	v_mfma_f32_16x16x32_bf16 v[100:103], v[124:127], v[220:223], v[100:103]
	v_mfma_f32_16x16x32_bf16 v[96:99], v[136:139], v[220:223], v[96:99]
	s_setprio 0
	s_setprio 1
	v_mfma_f32_16x16x32_bf16 v[60:63], v[140:143], v[160:163], 0
	v_mfma_f32_16x16x32_bf16 v[56:59], v[152:155], v[160:163], 0
	v_mfma_f32_16x16x32_bf16 v[52:55], v[140:143], v[182:185], 0
	v_mfma_f32_16x16x32_bf16 v[48:51], v[152:155], v[182:185], 0
	v_mfma_f32_16x16x32_bf16 v[44:47], v[140:143], v[190:193], 0
	v_mfma_f32_16x16x32_bf16 v[40:43], v[152:155], v[190:193], 0
	v_mfma_f32_16x16x32_bf16 v[36:39], v[140:143], v[204:207], 0
	v_mfma_f32_16x16x32_bf16 v[32:35], v[152:155], v[204:207], 0
	v_mfma_f32_16x16x32_bf16 v[60:63], v[144:147], v[178:181], v[60:63]
	v_mfma_f32_16x16x32_bf16 v[56:59], v[156:159], v[178:181], v[56:59]
	v_mfma_f32_16x16x32_bf16 v[52:55], v[144:147], v[186:189], v[52:55]
	v_mfma_f32_16x16x32_bf16 v[48:51], v[156:159], v[186:189], v[48:51]
	v_mfma_f32_16x16x32_bf16 v[44:47], v[144:147], v[200:203], v[44:47]
	v_mfma_f32_16x16x32_bf16 v[40:43], v[156:159], v[200:203], v[40:43]
	v_mfma_f32_16x16x32_bf16 v[36:39], v[144:147], v[220:223], v[36:39]
	v_mfma_f32_16x16x32_bf16 v[32:35], v[156:159], v[220:223], v[32:35]
	s_setprio 0
	s_barrier
	s_add_i32 s55, s55, s25
	s_mov_b32 m0, s55
	ds_read_b128 v[160:163], v199 offset:16384
	ds_read_b128 v[178:181], v199 offset:17408
	ds_read_b128 v[182:185], v199 offset:18432
	ds_read_b128 v[186:189], v199 offset:19456
	ds_read_b128 v[190:193], v199 offset:20480
	ds_read_b128 v[200:203], v199 offset:21504
	ds_read_b128 v[204:207], v199 offset:22528
	ds_read_b128 v[220:223], v199 offset:23552
	global_load_lds_dwordx4 v176, s[12:13]
	s_add_i32 m0, s55, 0x2000
	s_add_u32 s58, s12, 0x80000
	s_addc_u32 s59, s13, 0
	s_add_i32 s55, s60, s25
	global_load_lds_dwordx4 v164, s[12:13]
	s_mov_b32 m0, s55
	v_lshl_add_u64 v[224:225], s[14:15], 0, v[166:167]
	global_load_lds_dwordx4 v176, s[58:59]
	s_add_i32 m0, s55, 0x2000
	s_nop 0
	global_load_lds_dwordx4 v164, s[58:59]
	v_lshl_add_u64 v[208:209], s[14:15], 0, v[168:169]
	s_mov_b32 m0, s27
	s_nop 0
	global_load_lds_dwordx4 v168, s[14:15]
	s_mov_b32 m0, s28
	s_nop 0
	global_load_lds_dwordx4 v166, s[14:15]
	s_waitcnt vmcnt(8)
	s_waitcnt lgkmcnt(0)
	s_barrier
	s_setprio 1
	s_waitcnt lgkmcnt(0)
	v_mfma_f32_16x16x32_bf16 v[92:95], v[120:123], v[160:163], 0
	v_mfma_f32_16x16x32_bf16 v[88:91], v[132:135], v[160:163], 0
	v_mfma_f32_16x16x32_bf16 v[84:87], v[120:123], v[182:185], 0
	v_mfma_f32_16x16x32_bf16 v[80:83], v[132:135], v[182:185], 0
	v_mfma_f32_16x16x32_bf16 v[76:79], v[120:123], v[190:193], 0
	v_mfma_f32_16x16x32_bf16 v[72:75], v[132:135], v[190:193], 0
	v_mfma_f32_16x16x32_bf16 v[68:71], v[120:123], v[204:207], 0
	v_mfma_f32_16x16x32_bf16 v[64:67], v[132:135], v[204:207], 0
	v_mfma_f32_16x16x32_bf16 v[92:95], v[124:127], v[178:181], v[92:95]
	v_mfma_f32_16x16x32_bf16 v[88:91], v[136:139], v[178:181], v[88:91]
	v_mfma_f32_16x16x32_bf16 v[84:87], v[124:127], v[186:189], v[84:87]
	v_mfma_f32_16x16x32_bf16 v[80:83], v[136:139], v[186:189], v[80:83]
	v_mfma_f32_16x16x32_bf16 v[76:79], v[124:127], v[200:203], v[76:79]
	v_mfma_f32_16x16x32_bf16 v[72:75], v[136:139], v[200:203], v[72:75]
	v_mfma_f32_16x16x32_bf16 v[68:71], v[124:127], v[220:223], v[68:71]
	v_mfma_f32_16x16x32_bf16 v[64:67], v[136:139], v[220:223], v[64:67]
	s_setprio 0
	s_setprio 1
	v_mfma_f32_16x16x32_bf16 v[28:31], v[140:143], v[160:163], 0
	v_mfma_f32_16x16x32_bf16 v[24:27], v[152:155], v[160:163], 0
	v_mfma_f32_16x16x32_bf16 v[20:23], v[140:143], v[182:185], 0
	v_mfma_f32_16x16x32_bf16 v[16:19], v[152:155], v[182:185], 0
	v_mfma_f32_16x16x32_bf16 v[12:15], v[140:143], v[190:193], 0
	v_mfma_f32_16x16x32_bf16 v[8:11], v[152:155], v[190:193], 0
	v_mfma_f32_16x16x32_bf16 v[4:7], v[140:143], v[204:207], 0
	v_mfma_f32_16x16x32_bf16 v[0:3], v[152:155], v[204:207], 0
	v_mfma_f32_16x16x32_bf16 v[28:31], v[144:147], v[178:181], v[28:31]
	v_mfma_f32_16x16x32_bf16 v[24:27], v[156:159], v[178:181], v[24:27]
	v_mfma_f32_16x16x32_bf16 v[20:23], v[144:147], v[186:189], v[20:23]
	v_mfma_f32_16x16x32_bf16 v[16:19], v[156:159], v[186:189], v[16:19]
	v_mfma_f32_16x16x32_bf16 v[12:15], v[144:147], v[200:203], v[12:15]
	v_mfma_f32_16x16x32_bf16 v[8:11], v[156:159], v[200:203], v[8:11]
	v_mfma_f32_16x16x32_bf16 v[4:7], v[144:147], v[220:223], v[4:7]
	v_mfma_f32_16x16x32_bf16 v[0:3], v[156:159], v[220:223], v[0:3]
	s_setprio 0
	s_barrier
	s_add_i32 s55, 0, 0x18000
	s_add_i32 s58, 0, 0x1c000
	v_add_u32_e32 v136, s55, v197
	v_add_u32_e32 v156, s58, v197
	ds_read_b128 v[120:123], v136
	ds_read_b128 v[124:127], v136 offset:1024
	ds_read_b128 v[132:135], v136 offset:2048
	ds_read_b128 v[136:139], v136 offset:3072
	ds_read_b128 v[140:143], v156
	ds_read_b128 v[144:147], v156 offset:1024
	ds_read_b128 v[152:155], v156 offset:2048
	ds_read_b128 v[156:159], v156 offset:3072
	s_add_u32 s14, s14, 0x80000
	s_addc_u32 s15, s15, 0
	s_mov_b32 m0, s29
	ds_read_b128 v[160:163], v199 offset:32768
	ds_read_b128 v[178:181], v199 offset:33792
	ds_read_b128 v[182:185], v199 offset:34816
	ds_read_b128 v[186:189], v199 offset:35840
	ds_read_b128 v[190:193], v199 offset:36864
	ds_read_b128 v[200:203], v199 offset:37888
	ds_read_b128 v[204:207], v199 offset:38912
	ds_read_b128 v[220:223], v199 offset:39936
	global_load_lds_dwordx4 v168, s[14:15]
	s_mov_b32 m0, s38
	s_nop 0
	global_load_lds_dwordx4 v166, s[14:15]
	s_waitcnt vmcnt(8)
	s_waitcnt lgkmcnt(0)
	s_barrier
	s_setprio 1
	s_waitcnt lgkmcnt(0)
	v_mfma_f32_16x16x32_bf16 v[148:151], v[120:123], v[160:163], v[148:151]
	v_mfma_f32_16x16x32_bf16 v[128:131], v[132:135], v[160:163], v[128:131]
	v_mfma_f32_16x16x32_bf16 v[116:119], v[120:123], v[182:185], v[116:119]
	v_mfma_f32_16x16x32_bf16 v[112:115], v[132:135], v[182:185], v[112:115]
	v_mfma_f32_16x16x32_bf16 v[108:111], v[120:123], v[190:193], v[108:111]
	v_mfma_f32_16x16x32_bf16 v[104:107], v[132:135], v[190:193], v[104:107]
	v_mfma_f32_16x16x32_bf16 v[100:103], v[120:123], v[204:207], v[100:103]
	v_mfma_f32_16x16x32_bf16 v[96:99], v[132:135], v[204:207], v[96:99]
	v_mfma_f32_16x16x32_bf16 v[148:151], v[124:127], v[178:181], v[148:151]
	v_mfma_f32_16x16x32_bf16 v[128:131], v[136:139], v[178:181], v[128:131]
	v_mfma_f32_16x16x32_bf16 v[116:119], v[124:127], v[186:189], v[116:119]
	v_mfma_f32_16x16x32_bf16 v[112:115], v[136:139], v[186:189], v[112:115]
	v_mfma_f32_16x16x32_bf16 v[108:111], v[124:127], v[200:203], v[108:111]
	v_mfma_f32_16x16x32_bf16 v[104:107], v[136:139], v[200:203], v[104:107]
	v_mfma_f32_16x16x32_bf16 v[100:103], v[124:127], v[220:223], v[100:103]
	v_mfma_f32_16x16x32_bf16 v[96:99], v[136:139], v[220:223], v[96:99]
	s_setprio 0
	s_setprio 1
	v_mfma_f32_16x16x32_bf16 v[60:63], v[140:143], v[160:163], v[60:63]
	v_mfma_f32_16x16x32_bf16 v[56:59], v[152:155], v[160:163], v[56:59]
	v_mfma_f32_16x16x32_bf16 v[52:55], v[140:143], v[182:185], v[52:55]
	v_mfma_f32_16x16x32_bf16 v[48:51], v[152:155], v[182:185], v[48:51]
	v_mfma_f32_16x16x32_bf16 v[44:47], v[140:143], v[190:193], v[44:47]
	v_mfma_f32_16x16x32_bf16 v[40:43], v[152:155], v[190:193], v[40:43]
	v_mfma_f32_16x16x32_bf16 v[36:39], v[140:143], v[204:207], v[36:39]
	v_mfma_f32_16x16x32_bf16 v[32:35], v[152:155], v[204:207], v[32:35]
	v_mfma_f32_16x16x32_bf16 v[60:63], v[144:147], v[178:181], v[60:63]
	v_mfma_f32_16x16x32_bf16 v[56:59], v[156:159], v[178:181], v[56:59]
	v_mfma_f32_16x16x32_bf16 v[52:55], v[144:147], v[186:189], v[52:55]
	v_mfma_f32_16x16x32_bf16 v[48:51], v[156:159], v[186:189], v[48:51]
	v_mfma_f32_16x16x32_bf16 v[44:47], v[144:147], v[200:203], v[44:47]
	v_mfma_f32_16x16x32_bf16 v[40:43], v[156:159], v[200:203], v[40:43]
	v_mfma_f32_16x16x32_bf16 v[36:39], v[144:147], v[220:223], v[36:39]
	v_mfma_f32_16x16x32_bf16 v[32:35], v[156:159], v[220:223], v[32:35]
	s_setprio 0
	s_barrier
	s_add_i32 s14, s55, s25
	s_mov_b32 m0, s14
	ds_read_b128 v[160:163], v199 offset:49152
	ds_read_b128 v[178:181], v199 offset:50176
	ds_read_b128 v[182:185], v199 offset:51200
	ds_read_b128 v[186:189], v199 offset:52224
	ds_read_b128 v[190:193], v199 offset:53248
	ds_read_b128 v[200:203], v199 offset:54272
	ds_read_b128 v[204:207], v199 offset:55296
	ds_read_b128 v[220:223], v199 offset:56320
	s_add_u32 s98, s12, 0x80
	s_addc_u32 s99, s13, 0
	global_load_lds_dwordx4 v176, s[98:99]
	s_add_i32 m0, s14, 0x2000
	s_add_u32 s12, s12, 0x80080
	s_addc_u32 s13, s13, 0
	s_add_i32 s14, s58, s25
	s_add_u32 s98, s12, 0xfff80000
	s_addc_u32 s99, s13, -1
	global_load_lds_dwordx4 v164, s[98:99]
	s_mov_b32 m0, s14
	s_nop 0
	global_load_lds_dwordx4 v176, s[12:13]
	s_add_i32 m0, s14, 0x2000
	s_nop 0
	global_load_lds_dwordx4 v164, s[12:13]
	v_lshl_add_u64 v[174:175], v[208:209], 0, s[74:75]
	s_mov_b32 m0, s42
	s_nop 0
	global_load_lds_dwordx4 v[174:175], off
	v_lshl_add_u64 v[174:175], v[224:225], 0, s[74:75]
	s_mov_b32 m0, s43
	s_nop 0
	global_load_lds_dwordx4 v[174:175], off
	s_waitcnt vmcnt(8)
	s_waitcnt lgkmcnt(0)
	s_barrier
	s_setprio 1
	s_waitcnt lgkmcnt(0)
	v_mfma_f32_16x16x32_bf16 v[92:95], v[120:123], v[160:163], v[92:95]
	v_mfma_f32_16x16x32_bf16 v[88:91], v[132:135], v[160:163], v[88:91]
	v_mfma_f32_16x16x32_bf16 v[84:87], v[120:123], v[182:185], v[84:87]
	v_mfma_f32_16x16x32_bf16 v[80:83], v[132:135], v[182:185], v[80:83]
	v_mfma_f32_16x16x32_bf16 v[76:79], v[120:123], v[190:193], v[76:79]
	v_mfma_f32_16x16x32_bf16 v[72:75], v[132:135], v[190:193], v[72:75]
	v_mfma_f32_16x16x32_bf16 v[68:71], v[120:123], v[204:207], v[68:71]
	v_mfma_f32_16x16x32_bf16 v[64:67], v[132:135], v[204:207], v[64:67]
	v_mfma_f32_16x16x32_bf16 v[92:95], v[124:127], v[178:181], v[92:95]
	v_mfma_f32_16x16x32_bf16 v[88:91], v[136:139], v[178:181], v[88:91]
	v_mfma_f32_16x16x32_bf16 v[84:87], v[124:127], v[186:189], v[84:87]
	v_mfma_f32_16x16x32_bf16 v[80:83], v[136:139], v[186:189], v[80:83]
	v_mfma_f32_16x16x32_bf16 v[76:79], v[124:127], v[200:203], v[76:79]
	v_mfma_f32_16x16x32_bf16 v[72:75], v[136:139], v[200:203], v[72:75]
	v_mfma_f32_16x16x32_bf16 v[68:71], v[124:127], v[220:223], v[68:71]
	v_mfma_f32_16x16x32_bf16 v[64:67], v[136:139], v[220:223], v[64:67]
	s_setprio 0
	s_setprio 1
	v_mfma_f32_16x16x32_bf16 v[28:31], v[140:143], v[160:163], v[28:31]
	v_mfma_f32_16x16x32_bf16 v[24:27], v[152:155], v[160:163], v[24:27]
	v_mfma_f32_16x16x32_bf16 v[20:23], v[140:143], v[182:185], v[20:23]
	v_mfma_f32_16x16x32_bf16 v[16:19], v[152:155], v[182:185], v[16:19]
	v_mfma_f32_16x16x32_bf16 v[12:15], v[140:143], v[190:193], v[12:15]
	v_mfma_f32_16x16x32_bf16 v[8:11], v[152:155], v[190:193], v[8:11]
	v_mfma_f32_16x16x32_bf16 v[4:7], v[140:143], v[204:207], v[4:7]
	v_mfma_f32_16x16x32_bf16 v[0:3], v[152:155], v[204:207], v[0:3]
	v_mfma_f32_16x16x32_bf16 v[28:31], v[144:147], v[178:181], v[28:31]
	v_mfma_f32_16x16x32_bf16 v[24:27], v[156:159], v[178:181], v[24:27]
	v_mfma_f32_16x16x32_bf16 v[20:23], v[144:147], v[186:189], v[20:23]
	v_mfma_f32_16x16x32_bf16 v[16:19], v[156:159], v[186:189], v[16:19]
	v_mfma_f32_16x16x32_bf16 v[12:15], v[144:147], v[200:203], v[12:15]
	v_mfma_f32_16x16x32_bf16 v[8:11], v[156:159], v[200:203], v[8:11]
	v_mfma_f32_16x16x32_bf16 v[4:7], v[144:147], v[220:223], v[4:7]
	v_mfma_f32_16x16x32_bf16 v[0:3], v[156:159], v[220:223], v[0:3]
	s_setprio 0
	s_barrier
	s_add_i32 s53, s53, 2
	s_add_u32 s0, s0, 0x100
	s_addc_u32 s1, s1, 0
	s_add_u32 s50, s50, 0x100
	s_addc_u32 s51, s51, 0
	s_cmp_gt_u32 s53, 29

.LBB0_289:
	s_mov_b32 s61, s60
	s_add_i32 s60, s60, 1
	s_cmp_lt_u32 s61, 2
	s_cselect_b64 s[12:13], -1, 0
	s_lshl_b32 s1, s60, 5
	s_add_i32 s1, s90, s1
	s_and_b64 s[14:15], s[12:13], exec
	s_mov_b32 s2, s70
	s_cselect_b32 s70, s1, s70
	s_mov_b32 s0, s68
	s_cselect_b32 s68, s94, s68
	s_ashr_i32 s71, s70, 31
	s_lshl_b64 s[14:15], s[70:71], 20
	s_add_u32 s1, s24, s14
	s_addc_u32 s3, s25, s15
	s_mov_b64 s[8:9], s[34:35]
	s_and_b64 s[14:15], s[12:13], exec
	s_cselect_b32 s35, s3, s9
	s_cselect_b32 s34, s1, s8
	s_ashr_i32 s69, s68, 31
	s_lshl_b64 s[14:15], s[68:69], 20
	s_add_u32 s1, s27, s14
	s_addc_u32 s3, s28, s15
	s_mov_b64 s[10:11], s[30:31]
	s_and_b64 s[12:13], s[12:13], exec
	s_cselect_b32 s31, s3, s11
	s_cselect_b32 s30, s1, s10
	s_add_u32 s8, s8, 0x80080
	s_addc_u32 s9, s9, 0
	s_add_u32 s1, s10, 0x100
	s_addc_u32 s3, s11, 0
	s_mov_b32 s14, -2
	s_waitcnt lgkmcnt(0)
	s_add_u32 s10, s8, 0xfff80080
	s_addc_u32 s11, s9, -1
	s_add_i32 s15, 0, 0x10000
	s_cmp_eq_u32 s14, 28
	s_cselect_b32 s13, s35, s11
	s_cselect_b32 s12, s34, s10
	s_cselect_b32 s11, s31, s3
	s_cselect_b32 s10, s30, s1
	s_add_i32 s22, 0, 0x14000
	v_add_u32_e32 v124, s15, v209
	v_add_u32_e32 v156, s22, v209
	ds_read_b128 v[112:115], v124
	ds_read_b128 v[116:119], v124 offset:1024
	ds_read_b128 v[120:123], v124 offset:2048
	ds_read_b128 v[124:127], v124 offset:3072
	ds_read_b128 v[136:139], v156
	ds_read_b128 v[140:143], v156 offset:1024
	ds_read_b128 v[152:155], v156 offset:2048
	ds_read_b128 v[156:159], v156 offset:3072
	s_add_i32 m0, s38, 0xc000
	ds_read_b128 v[160:163], v228
	ds_read_b128 v[164:167], v228 offset:1024
	ds_read_b128 v[168:171], v228 offset:2048
	ds_read_b128 v[172:175], v228 offset:3072
	ds_read_b128 v[230:233], v228 offset:4096
	ds_read_b128 v[234:237], v228 offset:5120
	ds_read_b128 v[238:241], v228 offset:6144
	ds_read_b128 v[242:245], v228 offset:7168
	global_load_lds_dwordx4 v202, s[8:9]
	s_add_i32 m0, s38, 0xe000
	s_nop 0
	global_load_lds_dwordx4 v204, s[8:9]
	s_waitcnt vmcnt(8)
	s_waitcnt lgkmcnt(0)
	s_barrier
	s_setprio 1
	s_waitcnt lgkmcnt(0)
	v_mfma_f32_16x16x32_bf16 v[148:151], v[112:115], v[160:163], 0
	v_mfma_f32_16x16x32_bf16 v[144:147], v[120:123], v[160:163], 0
	v_mfma_f32_16x16x32_bf16 v[108:111], v[112:115], v[168:171], 0
	v_mfma_f32_16x16x32_bf16 v[104:107], v[120:123], v[168:171], 0
	v_mfma_f32_16x16x32_bf16 v[92:95], v[112:115], v[230:233], 0
	v_mfma_f32_16x16x32_bf16 v[88:91], v[120:123], v[230:233], 0
	v_mfma_f32_16x16x32_bf16 v[76:79], v[112:115], v[238:241], 0
	v_mfma_f32_16x16x32_bf16 v[72:75], v[120:123], v[238:241], 0
	v_mfma_f32_16x16x32_bf16 v[148:151], v[116:119], v[164:167], v[148:151]
	v_mfma_f32_16x16x32_bf16 v[144:147], v[124:127], v[164:167], v[144:147]
	v_mfma_f32_16x16x32_bf16 v[108:111], v[116:119], v[172:175], v[108:111]
	v_mfma_f32_16x16x32_bf16 v[104:107], v[124:127], v[172:175], v[104:107]
	v_mfma_f32_16x16x32_bf16 v[92:95], v[116:119], v[234:237], v[92:95]
	v_mfma_f32_16x16x32_bf16 v[88:91], v[124:127], v[234:237], v[88:91]
	v_mfma_f32_16x16x32_bf16 v[76:79], v[116:119], v[242:245], v[76:79]
	v_mfma_f32_16x16x32_bf16 v[72:75], v[124:127], v[242:245], v[72:75]
	s_setprio 0
	s_setprio 1
	v_mfma_f32_16x16x32_bf16 v[132:135], v[136:139], v[160:163], 0
	v_mfma_f32_16x16x32_bf16 v[128:131], v[152:155], v[160:163], 0
	v_mfma_f32_16x16x32_bf16 v[100:103], v[136:139], v[168:171], 0
	v_mfma_f32_16x16x32_bf16 v[96:99], v[152:155], v[168:171], 0
	v_mfma_f32_16x16x32_bf16 v[84:87], v[136:139], v[230:233], 0
	v_mfma_f32_16x16x32_bf16 v[80:83], v[152:155], v[230:233], 0
	v_mfma_f32_16x16x32_bf16 v[68:71], v[136:139], v[238:241], 0
	v_mfma_f32_16x16x32_bf16 v[64:67], v[152:155], v[238:241], 0
	v_mfma_f32_16x16x32_bf16 v[132:135], v[140:143], v[164:167], v[132:135]
	v_mfma_f32_16x16x32_bf16 v[128:131], v[156:159], v[164:167], v[128:131]
	v_mfma_f32_16x16x32_bf16 v[100:103], v[140:143], v[172:175], v[100:103]
	v_mfma_f32_16x16x32_bf16 v[96:99], v[156:159], v[172:175], v[96:99]
	v_mfma_f32_16x16x32_bf16 v[84:87], v[140:143], v[234:237], v[84:87]
	v_mfma_f32_16x16x32_bf16 v[80:83], v[156:159], v[234:237], v[80:83]
	v_mfma_f32_16x16x32_bf16 v[68:71], v[140:143], v[242:245], v[68:71]
	v_mfma_f32_16x16x32_bf16 v[64:67], v[156:159], v[242:245], v[64:67]
	s_setprio 0
	s_barrier
	s_add_i32 s15, s15, s29
	s_mov_b32 m0, s15
	ds_read_b128 v[160:163], v228 offset:16384
	ds_read_b128 v[164:167], v228 offset:17408
	ds_read_b128 v[168:171], v228 offset:18432
	ds_read_b128 v[172:175], v228 offset:19456
	ds_read_b128 v[230:233], v228 offset:20480
	ds_read_b128 v[234:237], v228 offset:21504
	ds_read_b128 v[238:241], v228 offset:22528
	ds_read_b128 v[242:245], v228 offset:23552
	global_load_lds_dwordx4 v176, s[10:11]
	s_add_i32 m0, s15, 0x2000
	s_add_u32 s20, s10, 0x80000
	s_addc_u32 s21, s11, 0
	s_add_i32 s15, s22, s29
	global_load_lds_dwordx4 v182, s[10:11]
	s_mov_b32 m0, s15
	s_nop 0
	global_load_lds_dwordx4 v176, s[20:21]
	s_add_i32 m0, s15, 0x2000
	s_nop 0
	global_load_lds_dwordx4 v182, s[20:21]
	s_add_u32 s50, s12, 0x80
	s_addc_u32 s51, s13, 0
	s_mov_b32 m0, s38
	s_nop 0
	global_load_lds_dwordx4 v178, s[12:13]
	s_mov_b32 m0, s39
	s_nop 0
	global_load_lds_dwordx4 v180, s[12:13]
	s_waitcnt vmcnt(8)
	s_waitcnt lgkmcnt(0)
	s_barrier
	s_setprio 1
	s_waitcnt lgkmcnt(0)
	v_mfma_f32_16x16x32_bf16 v[60:63], v[112:115], v[160:163], 0
	v_mfma_f32_16x16x32_bf16 v[56:59], v[120:123], v[160:163], 0
	v_mfma_f32_16x16x32_bf16 v[44:47], v[112:115], v[168:171], 0
	v_mfma_f32_16x16x32_bf16 v[40:43], v[120:123], v[168:171], 0
	v_mfma_f32_16x16x32_bf16 v[28:31], v[112:115], v[230:233], 0
	v_mfma_f32_16x16x32_bf16 v[24:27], v[120:123], v[230:233], 0
	v_mfma_f32_16x16x32_bf16 v[12:15], v[112:115], v[238:241], 0
	v_mfma_f32_16x16x32_bf16 v[8:11], v[120:123], v[238:241], 0
	v_mfma_f32_16x16x32_bf16 v[60:63], v[116:119], v[164:167], v[60:63]
	v_mfma_f32_16x16x32_bf16 v[56:59], v[124:127], v[164:167], v[56:59]
	v_mfma_f32_16x16x32_bf16 v[44:47], v[116:119], v[172:175], v[44:47]
	v_mfma_f32_16x16x32_bf16 v[40:43], v[124:127], v[172:175], v[40:43]
	v_mfma_f32_16x16x32_bf16 v[28:31], v[116:119], v[234:237], v[28:31]
	v_mfma_f32_16x16x32_bf16 v[24:27], v[124:127], v[234:237], v[24:27]
	v_mfma_f32_16x16x32_bf16 v[12:15], v[116:119], v[242:245], v[12:15]
	v_mfma_f32_16x16x32_bf16 v[8:11], v[124:127], v[242:245], v[8:11]
	s_setprio 0
	s_setprio 1
	v_mfma_f32_16x16x32_bf16 v[52:55], v[136:139], v[160:163], 0
	v_mfma_f32_16x16x32_bf16 v[48:51], v[152:155], v[160:163], 0
	v_mfma_f32_16x16x32_bf16 v[36:39], v[136:139], v[168:171], 0
	v_mfma_f32_16x16x32_bf16 v[32:35], v[152:155], v[168:171], 0
	v_mfma_f32_16x16x32_bf16 v[20:23], v[136:139], v[230:233], 0
	v_mfma_f32_16x16x32_bf16 v[16:19], v[152:155], v[230:233], 0
	v_mfma_f32_16x16x32_bf16 v[4:7], v[136:139], v[238:241], 0
	v_mfma_f32_16x16x32_bf16 v[0:3], v[152:155], v[238:241], 0
	v_mfma_f32_16x16x32_bf16 v[52:55], v[140:143], v[164:167], v[52:55]
	v_mfma_f32_16x16x32_bf16 v[48:51], v[156:159], v[164:167], v[48:51]
	v_mfma_f32_16x16x32_bf16 v[36:39], v[140:143], v[172:175], v[36:39]
	v_mfma_f32_16x16x32_bf16 v[32:35], v[156:159], v[172:175], v[32:35]
	v_mfma_f32_16x16x32_bf16 v[20:23], v[140:143], v[234:237], v[20:23]
	v_mfma_f32_16x16x32_bf16 v[16:19], v[156:159], v[234:237], v[16:19]
	v_mfma_f32_16x16x32_bf16 v[4:7], v[140:143], v[242:245], v[4:7]
	v_mfma_f32_16x16x32_bf16 v[0:3], v[156:159], v[242:245], v[0:3]
	s_setprio 0
	s_barrier
	s_add_i32 s15, 0, 0x18000
	s_add_i32 s20, 0, 0x1c000
	v_add_u32_e32 v124, s15, v209
	v_add_u32_e32 v156, s20, v209
	ds_read_b128 v[112:115], v124
	ds_read_b128 v[116:119], v124 offset:1024
	ds_read_b128 v[120:123], v124 offset:2048
	ds_read_b128 v[124:127], v124 offset:3072
	ds_read_b128 v[136:139], v156
	ds_read_b128 v[140:143], v156 offset:1024
	ds_read_b128 v[152:155], v156 offset:2048
	ds_read_b128 v[156:159], v156 offset:3072
	s_add_u32 s12, s12, 0x80000
	s_addc_u32 s13, s13, 0
	s_mov_b32 m0, s42
	ds_read_b128 v[160:163], v228 offset:32768
	ds_read_b128 v[164:167], v228 offset:33792
	ds_read_b128 v[168:171], v228 offset:34816
	ds_read_b128 v[172:175], v228 offset:35840
	ds_read_b128 v[230:233], v228 offset:36864
	ds_read_b128 v[234:237], v228 offset:37888
	ds_read_b128 v[238:241], v228 offset:38912
	ds_read_b128 v[242:245], v228 offset:39936
	global_load_lds_dwordx4 v178, s[12:13]
	s_mov_b32 m0, s43
	s_nop 0
	global_load_lds_dwordx4 v180, s[12:13]
	s_waitcnt vmcnt(8)
	s_waitcnt lgkmcnt(0)
	s_barrier
	s_setprio 1
	s_waitcnt lgkmcnt(0)
	v_mfma_f32_16x16x32_bf16 v[148:151], v[112:115], v[160:163], v[148:151]
	v_mfma_f32_16x16x32_bf16 v[144:147], v[120:123], v[160:163], v[144:147]
	v_mfma_f32_16x16x32_bf16 v[108:111], v[112:115], v[168:171], v[108:111]
	v_mfma_f32_16x16x32_bf16 v[104:107], v[120:123], v[168:171], v[104:107]
	v_mfma_f32_16x16x32_bf16 v[92:95], v[112:115], v[230:233], v[92:95]
	v_mfma_f32_16x16x32_bf16 v[88:91], v[120:123], v[230:233], v[88:91]
	v_mfma_f32_16x16x32_bf16 v[76:79], v[112:115], v[238:241], v[76:79]
	v_mfma_f32_16x16x32_bf16 v[72:75], v[120:123], v[238:241], v[72:75]
	v_mfma_f32_16x16x32_bf16 v[148:151], v[116:119], v[164:167], v[148:151]
	v_mfma_f32_16x16x32_bf16 v[144:147], v[124:127], v[164:167], v[144:147]
	v_mfma_f32_16x16x32_bf16 v[108:111], v[116:119], v[172:175], v[108:111]
	v_mfma_f32_16x16x32_bf16 v[104:107], v[124:127], v[172:175], v[104:107]
	v_mfma_f32_16x16x32_bf16 v[92:95], v[116:119], v[234:237], v[92:95]
	v_mfma_f32_16x16x32_bf16 v[88:91], v[124:127], v[234:237], v[88:91]
	v_mfma_f32_16x16x32_bf16 v[76:79], v[116:119], v[242:245], v[76:79]
	v_mfma_f32_16x16x32_bf16 v[72:75], v[124:127], v[242:245], v[72:75]
	s_setprio 0
	s_setprio 1
	v_mfma_f32_16x16x32_bf16 v[132:135], v[136:139], v[160:163], v[132:135]
	v_mfma_f32_16x16x32_bf16 v[128:131], v[152:155], v[160:163], v[128:131]
	v_mfma_f32_16x16x32_bf16 v[100:103], v[136:139], v[168:171], v[100:103]
	v_mfma_f32_16x16x32_bf16 v[96:99], v[152:155], v[168:171], v[96:99]
	v_mfma_f32_16x16x32_bf16 v[84:87], v[136:139], v[230:233], v[84:87]
	v_mfma_f32_16x16x32_bf16 v[80:83], v[152:155], v[230:233], v[80:83]
	v_mfma_f32_16x16x32_bf16 v[68:71], v[136:139], v[238:241], v[68:71]
	v_mfma_f32_16x16x32_bf16 v[64:67], v[152:155], v[238:241], v[64:67]
	v_mfma_f32_16x16x32_bf16 v[132:135], v[140:143], v[164:167], v[132:135]
	v_mfma_f32_16x16x32_bf16 v[128:131], v[156:159], v[164:167], v[128:131]
	v_mfma_f32_16x16x32_bf16 v[100:103], v[140:143], v[172:175], v[100:103]
	v_mfma_f32_16x16x32_bf16 v[96:99], v[156:159], v[172:175], v[96:99]
	v_mfma_f32_16x16x32_bf16 v[84:87], v[140:143], v[234:237], v[84:87]
	v_mfma_f32_16x16x32_bf16 v[80:83], v[156:159], v[234:237], v[80:83]
	v_mfma_f32_16x16x32_bf16 v[68:71], v[140:143], v[242:245], v[68:71]
	v_mfma_f32_16x16x32_bf16 v[64:67], v[156:159], v[242:245], v[64:67]
	s_setprio 0
	s_barrier
	s_add_i32 s12, s15, s29
	s_mov_b32 m0, s12
	ds_read_b128 v[160:163], v228 offset:49152
	ds_read_b128 v[164:167], v228 offset:50176
	ds_read_b128 v[168:171], v228 offset:51200
	ds_read_b128 v[172:175], v228 offset:52224
	ds_read_b128 v[230:233], v228 offset:53248
	ds_read_b128 v[234:237], v228 offset:54272
	ds_read_b128 v[238:241], v228 offset:55296
	ds_read_b128 v[242:245], v228 offset:56320
	s_add_u32 s98, s10, 0x80
	s_addc_u32 s99, s11, 0
	global_load_lds_dwordx4 v176, s[98:99]
	s_add_i32 m0, s12, 0x2000
	s_add_u32 s10, s10, 0x80080
	s_addc_u32 s11, s11, 0
	s_add_i32 s12, s20, s29
	s_add_u32 s98, s10, 0xfff80000
	s_addc_u32 s99, s11, -1
	global_load_lds_dwordx4 v182, s[98:99]
	s_mov_b32 m0, s12
	s_nop 0
	global_load_lds_dwordx4 v176, s[10:11]
	s_add_i32 m0, s12, 0x2000
	s_nop 0
	global_load_lds_dwordx4 v182, s[10:11]
	s_mov_b32 m0, s58
	s_nop 0
	global_load_lds_dwordx4 v178, s[50:51]
	s_mov_b32 m0, s59
	s_nop 0
	global_load_lds_dwordx4 v180, s[50:51]
	s_waitcnt vmcnt(8)
	s_waitcnt lgkmcnt(0)
	s_barrier
	s_setprio 1
	s_waitcnt lgkmcnt(0)
	v_mfma_f32_16x16x32_bf16 v[60:63], v[112:115], v[160:163], v[60:63]
	v_mfma_f32_16x16x32_bf16 v[56:59], v[120:123], v[160:163], v[56:59]
	v_mfma_f32_16x16x32_bf16 v[44:47], v[112:115], v[168:171], v[44:47]
	v_mfma_f32_16x16x32_bf16 v[40:43], v[120:123], v[168:171], v[40:43]
	v_mfma_f32_16x16x32_bf16 v[28:31], v[112:115], v[230:233], v[28:31]
	v_mfma_f32_16x16x32_bf16 v[24:27], v[120:123], v[230:233], v[24:27]
	v_mfma_f32_16x16x32_bf16 v[12:15], v[112:115], v[238:241], v[12:15]
	v_mfma_f32_16x16x32_bf16 v[8:11], v[120:123], v[238:241], v[8:11]
	v_mfma_f32_16x16x32_bf16 v[60:63], v[116:119], v[164:167], v[60:63]
	v_mfma_f32_16x16x32_bf16 v[56:59], v[124:127], v[164:167], v[56:59]
	v_mfma_f32_16x16x32_bf16 v[44:47], v[116:119], v[172:175], v[44:47]
	v_mfma_f32_16x16x32_bf16 v[40:43], v[124:127], v[172:175], v[40:43]
	v_mfma_f32_16x16x32_bf16 v[28:31], v[116:119], v[234:237], v[28:31]
	v_mfma_f32_16x16x32_bf16 v[24:27], v[124:127], v[234:237], v[24:27]
	v_mfma_f32_16x16x32_bf16 v[12:15], v[116:119], v[242:245], v[12:15]
	v_mfma_f32_16x16x32_bf16 v[8:11], v[124:127], v[242:245], v[8:11]
	s_setprio 0
	s_setprio 1
	v_mfma_f32_16x16x32_bf16 v[52:55], v[136:139], v[160:163], v[52:55]
	v_mfma_f32_16x16x32_bf16 v[48:51], v[152:155], v[160:163], v[48:51]
	v_mfma_f32_16x16x32_bf16 v[36:39], v[136:139], v[168:171], v[36:39]
	v_mfma_f32_16x16x32_bf16 v[32:35], v[152:155], v[168:171], v[32:35]
	v_mfma_f32_16x16x32_bf16 v[20:23], v[136:139], v[230:233], v[20:23]
	v_mfma_f32_16x16x32_bf16 v[16:19], v[152:155], v[230:233], v[16:19]
	v_mfma_f32_16x16x32_bf16 v[4:7], v[136:139], v[238:241], v[4:7]
	v_mfma_f32_16x16x32_bf16 v[0:3], v[152:155], v[238:241], v[0:3]
	v_mfma_f32_16x16x32_bf16 v[52:55], v[140:143], v[164:167], v[52:55]
	v_mfma_f32_16x16x32_bf16 v[48:51], v[156:159], v[164:167], v[48:51]
	v_mfma_f32_16x16x32_bf16 v[36:39], v[140:143], v[172:175], v[36:39]
	v_mfma_f32_16x16x32_bf16 v[32:35], v[156:159], v[172:175], v[32:35]
	v_mfma_f32_16x16x32_bf16 v[20:23], v[140:143], v[234:237], v[20:23]
	v_mfma_f32_16x16x32_bf16 v[16:19], v[156:159], v[234:237], v[16:19]
	v_mfma_f32_16x16x32_bf16 v[4:7], v[140:143], v[242:245], v[4:7]
	v_mfma_f32_16x16x32_bf16 v[0:3], v[156:159], v[242:245], v[0:3]
	s_setprio 0
	s_barrier
	s_add_i32 s14, s14, 2
	s_add_u32 s8, s8, 0x100
	s_addc_u32 s9, s9, 0
	s_add_u32 s1, s1, 0x100
	s_addc_u32 s3, s3, 0
	s_cmp_gt_u32 s14, 29

.LBB0_419:
	s_ashr_i32 s15, s14, 31
	s_lshl_b64 s[8:9], s[14:15], 20
	s_cmp_eq_u32 s53, 0
	s_cselect_b32 s19, s2, s26
	s_cselect_b32 s15, s3, s27
	s_cselect_b32 s29, s21, s3
	s_cselect_b32 s28, s20, s2
	s_add_u32 s24, s19, s8
	s_addc_u32 s25, s15, s9
	s_and_b64 s[8:9], s[22:23], exec
	s_cselect_b32 s15, s25, s5
	s_cselect_b32 s30, s24, s4
	s_ashr_i32 s19, s18, 31
	s_lshl_b64 s[8:9], s[18:19], 20
	s_add_u32 s28, s28, s8
	s_addc_u32 s29, s29, s9
	s_and_b64 s[8:9], s[22:23], exec
	s_cselect_b32 s19, s29, s7
	s_cselect_b32 s31, s28, s6
	s_add_u32 s4, s4, 0x80080
	s_addc_u32 s5, s5, 0
	s_add_u32 s34, s6, 0x100
	s_addc_u32 s35, s7, 0
	s_mov_b32 s36, -2
	s_add_u32 s6, s4, 0xfff80080
	s_addc_u32 s7, s5, -1
	s_add_i32 s37, 0, 0x10000
	s_cmp_eq_u32 s36, 28
	s_cselect_b32 s9, s15, s7
	s_cselect_b32 s8, s30, s6
	v_add_u32_e32 v129, s37, v149
	s_cselect_b32 s7, s19, s35
	s_cselect_b32 s6, s31, s34
	s_add_i32 s56, 0, 0x14000
	ds_read_b128 v[130:133], v129
	ds_read_b128 v[134:137], v129 offset:1024
	ds_read_b128 v[154:157], v129 offset:2048
	ds_read_b128 v[162:165], v129 offset:3072
	v_add_u32_e32 v129, s56, v149
	ds_read_b128 v[166:169], v129
	ds_read_b128 v[170:173], v129 offset:1024
	ds_read_b128 v[178:181], v129 offset:2048
	ds_read_b128 v[182:185], v129 offset:3072
	s_add_i32 m0, s38, 0xc000
	ds_read_b128 v[186:189], v161
	ds_read_b128 v[190:193], v161 offset:1024
	ds_read_b128 v[194:197], v161 offset:2048
	ds_read_b128 v[198:201], v161 offset:3072
	ds_read_b128 v[202:205], v161 offset:4096
	ds_read_b128 v[206:209], v161 offset:5120
	ds_read_b128 v[220:223], v161 offset:6144
	ds_read_b128 v[224:227], v161 offset:7168
	global_load_lds_dwordx4 v150, s[4:5]
	s_add_i32 m0, s38, 0xe000
	s_nop 0
	global_load_lds_dwordx4 v152, s[4:5]
	s_waitcnt vmcnt(8)
	s_waitcnt lgkmcnt(0)
	s_barrier
	s_setprio 1
	s_waitcnt lgkmcnt(0)
	v_mfma_f32_16x16x32_bf16 v[124:127], v[130:133], v[186:189], 0
	v_mfma_f32_16x16x32_bf16 v[120:123], v[154:157], v[186:189], 0
	v_mfma_f32_16x16x32_bf16 v[108:111], v[130:133], v[194:197], 0
	v_mfma_f32_16x16x32_bf16 v[104:107], v[154:157], v[194:197], 0
	v_mfma_f32_16x16x32_bf16 v[92:95], v[130:133], v[202:205], 0
	v_mfma_f32_16x16x32_bf16 v[88:91], v[154:157], v[202:205], 0
	v_mfma_f32_16x16x32_bf16 v[76:79], v[130:133], v[220:223], 0
	v_mfma_f32_16x16x32_bf16 v[72:75], v[154:157], v[220:223], 0
	v_mfma_f32_16x16x32_bf16 v[124:127], v[134:137], v[190:193], v[124:127]
	v_mfma_f32_16x16x32_bf16 v[120:123], v[162:165], v[190:193], v[120:123]
	v_mfma_f32_16x16x32_bf16 v[108:111], v[134:137], v[198:201], v[108:111]
	v_mfma_f32_16x16x32_bf16 v[104:107], v[162:165], v[198:201], v[104:107]
	v_mfma_f32_16x16x32_bf16 v[92:95], v[134:137], v[206:209], v[92:95]
	v_mfma_f32_16x16x32_bf16 v[88:91], v[162:165], v[206:209], v[88:91]
	v_mfma_f32_16x16x32_bf16 v[76:79], v[134:137], v[224:227], v[76:79]
	v_mfma_f32_16x16x32_bf16 v[72:75], v[162:165], v[224:227], v[72:75]
	s_setprio 0
	s_setprio 1
	v_mfma_f32_16x16x32_bf16 v[116:119], v[166:169], v[186:189], 0
	v_mfma_f32_16x16x32_bf16 v[112:115], v[178:181], v[186:189], 0
	v_mfma_f32_16x16x32_bf16 v[100:103], v[166:169], v[194:197], 0
	v_mfma_f32_16x16x32_bf16 v[96:99], v[178:181], v[194:197], 0
	v_mfma_f32_16x16x32_bf16 v[84:87], v[166:169], v[202:205], 0
	v_mfma_f32_16x16x32_bf16 v[80:83], v[178:181], v[202:205], 0
	v_mfma_f32_16x16x32_bf16 v[68:71], v[166:169], v[220:223], 0
	v_mfma_f32_16x16x32_bf16 v[64:67], v[178:181], v[220:223], 0
	v_mfma_f32_16x16x32_bf16 v[116:119], v[170:173], v[190:193], v[116:119]
	v_mfma_f32_16x16x32_bf16 v[112:115], v[182:185], v[190:193], v[112:115]
	v_mfma_f32_16x16x32_bf16 v[100:103], v[170:173], v[198:201], v[100:103]
	v_mfma_f32_16x16x32_bf16 v[96:99], v[182:185], v[198:201], v[96:99]
	v_mfma_f32_16x16x32_bf16 v[84:87], v[170:173], v[206:209], v[84:87]
	v_mfma_f32_16x16x32_bf16 v[80:83], v[182:185], v[206:209], v[80:83]
	v_mfma_f32_16x16x32_bf16 v[68:71], v[170:173], v[224:227], v[68:71]
	v_mfma_f32_16x16x32_bf16 v[64:67], v[182:185], v[224:227], v[64:67]
	s_setprio 0
	s_barrier
	s_add_i32 s37, s37, s33
	s_mov_b32 m0, s37
	ds_read_b128 v[186:189], v161 offset:16384
	ds_read_b128 v[190:193], v161 offset:17408
	ds_read_b128 v[194:197], v161 offset:18432
	ds_read_b128 v[198:201], v161 offset:19456
	ds_read_b128 v[202:205], v161 offset:20480
	ds_read_b128 v[206:209], v161 offset:21504
	ds_read_b128 v[220:223], v161 offset:22528
	ds_read_b128 v[224:227], v161 offset:23552
	global_load_lds_dwordx4 v142, s[6:7]
	s_add_i32 m0, s37, 0x2000
	s_add_u32 s54, s6, 0x80000
	s_addc_u32 s55, s7, 0
	s_add_i32 s37, s56, s33
	global_load_lds_dwordx4 v138, s[6:7]
	s_mov_b32 m0, s37
	s_nop 0
	global_load_lds_dwordx4 v142, s[54:55]
	s_add_i32 m0, s37, 0x2000
	s_nop 0
	global_load_lds_dwordx4 v138, s[54:55]
	s_add_u32 s60, s8, 0x80
	s_addc_u32 s61, s9, 0
	s_mov_b32 m0, s38
	s_nop 0
	global_load_lds_dwordx4 v144, s[8:9]
	s_mov_b32 m0, s39
	s_nop 0
	global_load_lds_dwordx4 v140, s[8:9]
	s_waitcnt vmcnt(8)
	s_waitcnt lgkmcnt(0)
	s_barrier
	s_setprio 1
	s_waitcnt lgkmcnt(0)
	v_mfma_f32_16x16x32_bf16 v[60:63], v[130:133], v[186:189], 0
	v_mfma_f32_16x16x32_bf16 v[56:59], v[154:157], v[186:189], 0
	v_mfma_f32_16x16x32_bf16 v[44:47], v[130:133], v[194:197], 0
	v_mfma_f32_16x16x32_bf16 v[40:43], v[154:157], v[194:197], 0
	v_mfma_f32_16x16x32_bf16 v[28:31], v[130:133], v[202:205], 0
	v_mfma_f32_16x16x32_bf16 v[24:27], v[154:157], v[202:205], 0
	v_mfma_f32_16x16x32_bf16 v[12:15], v[130:133], v[220:223], 0
	v_mfma_f32_16x16x32_bf16 v[8:11], v[154:157], v[220:223], 0
	v_mfma_f32_16x16x32_bf16 v[60:63], v[134:137], v[190:193], v[60:63]
	v_mfma_f32_16x16x32_bf16 v[56:59], v[162:165], v[190:193], v[56:59]
	v_mfma_f32_16x16x32_bf16 v[44:47], v[134:137], v[198:201], v[44:47]
	v_mfma_f32_16x16x32_bf16 v[40:43], v[162:165], v[198:201], v[40:43]
	v_mfma_f32_16x16x32_bf16 v[28:31], v[134:137], v[206:209], v[28:31]
	v_mfma_f32_16x16x32_bf16 v[24:27], v[162:165], v[206:209], v[24:27]
	v_mfma_f32_16x16x32_bf16 v[12:15], v[134:137], v[224:227], v[12:15]
	v_mfma_f32_16x16x32_bf16 v[8:11], v[162:165], v[224:227], v[8:11]
	s_setprio 0
	s_setprio 1
	v_mfma_f32_16x16x32_bf16 v[52:55], v[166:169], v[186:189], 0
	v_mfma_f32_16x16x32_bf16 v[48:51], v[178:181], v[186:189], 0
	v_mfma_f32_16x16x32_bf16 v[36:39], v[166:169], v[194:197], 0
	v_mfma_f32_16x16x32_bf16 v[32:35], v[178:181], v[194:197], 0
	v_mfma_f32_16x16x32_bf16 v[20:23], v[166:169], v[202:205], 0
	v_mfma_f32_16x16x32_bf16 v[16:19], v[178:181], v[202:205], 0
	v_mfma_f32_16x16x32_bf16 v[4:7], v[166:169], v[220:223], 0
	v_mfma_f32_16x16x32_bf16 v[0:3], v[178:181], v[220:223], 0
	v_mfma_f32_16x16x32_bf16 v[52:55], v[170:173], v[190:193], v[52:55]
	v_mfma_f32_16x16x32_bf16 v[48:51], v[182:185], v[190:193], v[48:51]
	v_mfma_f32_16x16x32_bf16 v[36:39], v[170:173], v[198:201], v[36:39]
	v_mfma_f32_16x16x32_bf16 v[32:35], v[182:185], v[198:201], v[32:35]
	v_mfma_f32_16x16x32_bf16 v[20:23], v[170:173], v[206:209], v[20:23]
	v_mfma_f32_16x16x32_bf16 v[16:19], v[182:185], v[206:209], v[16:19]
	v_mfma_f32_16x16x32_bf16 v[4:7], v[170:173], v[224:227], v[4:7]
	v_mfma_f32_16x16x32_bf16 v[0:3], v[182:185], v[224:227], v[0:3]
	s_setprio 0
	s_barrier
	s_add_i32 s37, 0, 0x18000
	v_add_u32_e32 v129, s37, v149
	s_add_i32 s54, 0, 0x1c000
	ds_read_b128 v[130:133], v129
	ds_read_b128 v[134:137], v129 offset:1024
	ds_read_b128 v[154:157], v129 offset:2048
	ds_read_b128 v[162:165], v129 offset:3072
	v_add_u32_e32 v129, s54, v149
	ds_read_b128 v[166:169], v129
	ds_read_b128 v[170:173], v129 offset:1024
	ds_read_b128 v[178:181], v129 offset:2048
	ds_read_b128 v[182:185], v129 offset:3072
	s_add_u32 s8, s8, 0x80000
	s_addc_u32 s9, s9, 0
	s_mov_b32 m0, s40
	ds_read_b128 v[186:189], v161 offset:32768
	ds_read_b128 v[190:193], v161 offset:33792
	ds_read_b128 v[194:197], v161 offset:34816
	ds_read_b128 v[198:201], v161 offset:35840
	ds_read_b128 v[202:205], v161 offset:36864
	ds_read_b128 v[206:209], v161 offset:37888
	ds_read_b128 v[220:223], v161 offset:38912
	ds_read_b128 v[224:227], v161 offset:39936
	global_load_lds_dwordx4 v144, s[8:9]
	s_mov_b32 m0, s41
	s_nop 0
	global_load_lds_dwordx4 v140, s[8:9]
	s_waitcnt vmcnt(8)
	s_waitcnt lgkmcnt(0)
	s_barrier
	s_setprio 1
	s_waitcnt lgkmcnt(0)
	v_mfma_f32_16x16x32_bf16 v[124:127], v[130:133], v[186:189], v[124:127]
	v_mfma_f32_16x16x32_bf16 v[120:123], v[154:157], v[186:189], v[120:123]
	v_mfma_f32_16x16x32_bf16 v[108:111], v[130:133], v[194:197], v[108:111]
	v_mfma_f32_16x16x32_bf16 v[104:107], v[154:157], v[194:197], v[104:107]
	v_mfma_f32_16x16x32_bf16 v[92:95], v[130:133], v[202:205], v[92:95]
	v_mfma_f32_16x16x32_bf16 v[88:91], v[154:157], v[202:205], v[88:91]
	v_mfma_f32_16x16x32_bf16 v[76:79], v[130:133], v[220:223], v[76:79]
	v_mfma_f32_16x16x32_bf16 v[72:75], v[154:157], v[220:223], v[72:75]
	v_mfma_f32_16x16x32_bf16 v[124:127], v[134:137], v[190:193], v[124:127]
	v_mfma_f32_16x16x32_bf16 v[120:123], v[162:165], v[190:193], v[120:123]
	v_mfma_f32_16x16x32_bf16 v[108:111], v[134:137], v[198:201], v[108:111]
	v_mfma_f32_16x16x32_bf16 v[104:107], v[162:165], v[198:201], v[104:107]
	v_mfma_f32_16x16x32_bf16 v[92:95], v[134:137], v[206:209], v[92:95]
	v_mfma_f32_16x16x32_bf16 v[88:91], v[162:165], v[206:209], v[88:91]
	v_mfma_f32_16x16x32_bf16 v[76:79], v[134:137], v[224:227], v[76:79]
	v_mfma_f32_16x16x32_bf16 v[72:75], v[162:165], v[224:227], v[72:75]
	s_setprio 0
	s_setprio 1
	v_mfma_f32_16x16x32_bf16 v[116:119], v[166:169], v[186:189], v[116:119]
	v_mfma_f32_16x16x32_bf16 v[112:115], v[178:181], v[186:189], v[112:115]
	v_mfma_f32_16x16x32_bf16 v[100:103], v[166:169], v[194:197], v[100:103]
	v_mfma_f32_16x16x32_bf16 v[96:99], v[178:181], v[194:197], v[96:99]
	v_mfma_f32_16x16x32_bf16 v[84:87], v[166:169], v[202:205], v[84:87]
	v_mfma_f32_16x16x32_bf16 v[80:83], v[178:181], v[202:205], v[80:83]
	v_mfma_f32_16x16x32_bf16 v[68:71], v[166:169], v[220:223], v[68:71]
	v_mfma_f32_16x16x32_bf16 v[64:67], v[178:181], v[220:223], v[64:67]
	v_mfma_f32_16x16x32_bf16 v[116:119], v[170:173], v[190:193], v[116:119]
	v_mfma_f32_16x16x32_bf16 v[112:115], v[182:185], v[190:193], v[112:115]
	v_mfma_f32_16x16x32_bf16 v[100:103], v[170:173], v[198:201], v[100:103]
	v_mfma_f32_16x16x32_bf16 v[96:99], v[182:185], v[198:201], v[96:99]
	v_mfma_f32_16x16x32_bf16 v[84:87], v[170:173], v[206:209], v[84:87]
	v_mfma_f32_16x16x32_bf16 v[80:83], v[182:185], v[206:209], v[80:83]
	v_mfma_f32_16x16x32_bf16 v[68:71], v[170:173], v[224:227], v[68:71]
	v_mfma_f32_16x16x32_bf16 v[64:67], v[182:185], v[224:227], v[64:67]
	s_setprio 0
	s_barrier
	s_add_i32 s8, s37, s33
	s_mov_b32 m0, s8
	ds_read_b128 v[186:189], v161 offset:49152
	ds_read_b128 v[190:193], v161 offset:50176
	ds_read_b128 v[194:197], v161 offset:51200
	ds_read_b128 v[198:201], v161 offset:52224
	ds_read_b128 v[202:205], v161 offset:53248
	ds_read_b128 v[206:209], v161 offset:54272
	ds_read_b128 v[220:223], v161 offset:55296
	ds_read_b128 v[224:227], v161 offset:56320
	s_add_u32 s98, s6, 0x80
	s_addc_u32 s99, s7, 0
	global_load_lds_dwordx4 v142, s[98:99]
	s_add_i32 m0, s8, 0x2000
	s_add_u32 s6, s6, 0x80080
	s_addc_u32 s7, s7, 0
	s_add_i32 s8, s54, s33
	s_add_u32 s98, s6, 0xfff80000
	s_addc_u32 s99, s7, -1
	global_load_lds_dwordx4 v138, s[98:99]
	s_mov_b32 m0, s8
	s_nop 0
	global_load_lds_dwordx4 v142, s[6:7]
	s_add_i32 m0, s8, 0x2000
	s_nop 0
	global_load_lds_dwordx4 v138, s[6:7]
	s_mov_b32 m0, s49
	s_nop 0
	global_load_lds_dwordx4 v144, s[60:61]
	s_mov_b32 m0, s50
	s_nop 0
	global_load_lds_dwordx4 v140, s[60:61]
	s_waitcnt vmcnt(8)
	s_waitcnt lgkmcnt(0)
	s_barrier
	s_setprio 1
	s_waitcnt lgkmcnt(0)
	v_mfma_f32_16x16x32_bf16 v[60:63], v[130:133], v[186:189], v[60:63]
	v_mfma_f32_16x16x32_bf16 v[56:59], v[154:157], v[186:189], v[56:59]
	v_mfma_f32_16x16x32_bf16 v[44:47], v[130:133], v[194:197], v[44:47]
	v_mfma_f32_16x16x32_bf16 v[40:43], v[154:157], v[194:197], v[40:43]
	v_mfma_f32_16x16x32_bf16 v[28:31], v[130:133], v[202:205], v[28:31]
	v_mfma_f32_16x16x32_bf16 v[24:27], v[154:157], v[202:205], v[24:27]
	v_mfma_f32_16x16x32_bf16 v[12:15], v[130:133], v[220:223], v[12:15]
	v_mfma_f32_16x16x32_bf16 v[8:11], v[154:157], v[220:223], v[8:11]
	v_mfma_f32_16x16x32_bf16 v[60:63], v[134:137], v[190:193], v[60:63]
	v_mfma_f32_16x16x32_bf16 v[56:59], v[162:165], v[190:193], v[56:59]
	v_mfma_f32_16x16x32_bf16 v[44:47], v[134:137], v[198:201], v[44:47]
	v_mfma_f32_16x16x32_bf16 v[40:43], v[162:165], v[198:201], v[40:43]
	v_mfma_f32_16x16x32_bf16 v[28:31], v[134:137], v[206:209], v[28:31]
	v_mfma_f32_16x16x32_bf16 v[24:27], v[162:165], v[206:209], v[24:27]
	v_mfma_f32_16x16x32_bf16 v[12:15], v[134:137], v[224:227], v[12:15]
	v_mfma_f32_16x16x32_bf16 v[8:11], v[162:165], v[224:227], v[8:11]
	s_setprio 0
	s_setprio 1
	v_mfma_f32_16x16x32_bf16 v[52:55], v[166:169], v[186:189], v[52:55]
	v_mfma_f32_16x16x32_bf16 v[48:51], v[178:181], v[186:189], v[48:51]
	v_mfma_f32_16x16x32_bf16 v[36:39], v[166:169], v[194:197], v[36:39]
	v_mfma_f32_16x16x32_bf16 v[32:35], v[178:181], v[194:197], v[32:35]
	v_mfma_f32_16x16x32_bf16 v[20:23], v[166:169], v[202:205], v[20:23]
	v_mfma_f32_16x16x32_bf16 v[16:19], v[178:181], v[202:205], v[16:19]
	v_mfma_f32_16x16x32_bf16 v[4:7], v[166:169], v[220:223], v[4:7]
	v_mfma_f32_16x16x32_bf16 v[0:3], v[178:181], v[220:223], v[0:3]
	v_mfma_f32_16x16x32_bf16 v[52:55], v[170:173], v[190:193], v[52:55]
	v_mfma_f32_16x16x32_bf16 v[48:51], v[182:185], v[190:193], v[48:51]
	v_mfma_f32_16x16x32_bf16 v[36:39], v[170:173], v[198:201], v[36:39]
	v_mfma_f32_16x16x32_bf16 v[32:35], v[182:185], v[198:201], v[32:35]
	v_mfma_f32_16x16x32_bf16 v[20:23], v[170:173], v[206:209], v[20:23]
	v_mfma_f32_16x16x32_bf16 v[16:19], v[182:185], v[206:209], v[16:19]
	v_mfma_f32_16x16x32_bf16 v[4:7], v[170:173], v[224:227], v[4:7]
	v_mfma_f32_16x16x32_bf16 v[0:3], v[182:185], v[224:227], v[0:3]
	s_setprio 0
	s_barrier
	s_add_i32 s36, s36, 2
	s_add_u32 s4, s4, 0x100
	s_addc_u32 s5, s5, 0
	s_add_u32 s34, s34, 0x100
	s_addc_u32 s35, s35, 0
	s_cmp_gt_u32 s36, 29

.LBB0_523:
	s_ashr_i32 s15, s14, 31
	s_lshl_b64 s[18:19], s[14:15], 17
	s_add_u32 s18, s2, s18
	s_addc_u32 s19, s3, s19
	s_and_b64 s[30:31], s[30:31], exec
	s_cselect_b32 s13, s19, s25
	s_cselect_b32 s15, s18, s24
	s_mov_b32 s36, 0
	s_mov_b64 s[30:31], -1
	s_mov_b64 s[34:35], 0
	s_add_u32 s37, s24, s36
	s_addc_u32 s42, s25, 0
	s_add_u32 s40, s37, 0x100
	s_addc_u32 s41, s42, 0
	s_and_b64 s[38:39], s[34:35], exec
	s_cselect_b32 s39, s13, s41
	s_cselect_b32 s38, s15, s40
	s_add_u32 s36, s22, s36
	s_addc_u32 s40, s23, 0
	s_add_u32 s36, s36, 0x100
	s_addc_u32 s40, s40, 0
	s_add_i32 s65, 0, 0x10000
	s_and_b64 s[34:35], s[34:35], exec
	s_cselect_b32 s41, s17, s40
	s_cselect_b32 s40, s16, s36
	s_add_i32 s35, 0, 0x14000
	s_add_u32 s46, s37, 0x10080
	s_addc_u32 s47, s42, 0
	s_add_i32 s64, s65, s26
	s_add_i32 m0, s27, 0xc000
	s_add_i32 s67, s27, 0xe000
	s_add_i32 s60, s64, 0x2000
	v_add_u32_e32 v139, s65, v137
	s_add_u32 s42, s40, 0xc0000
	ds_read_b128 v[140:143], v139
	ds_read_b128 v[144:147], v139 offset:1024
	ds_read_b128 v[148:151], v139 offset:2048
	ds_read_b128 v[152:155], v139 offset:3072
	v_add_u32_e32 v139, s35, v137
	s_addc_u32 s43, s41, 0
	s_add_i32 s63, s35, s26
	ds_read_b128 v[156:159], v139
	ds_read_b128 v[160:163], v139 offset:1024
	ds_read_b128 v[164:167], v139 offset:2048
	ds_read_b128 v[168:171], v139 offset:3072
	s_add_i32 s61, s63, 0x2000
	s_add_i32 s59, 0, 0x18000
	s_add_i32 s58, 0, 0x1c000
	s_add_u32 s36, s38, 0x10000
	s_addc_u32 s37, s39, 0
	s_add_i32 s57, s59, s26
	s_add_i32 s56, s57, 0x2000
	s_add_u32 s34, s40, 0xc0080
	s_addc_u32 s35, s41, 0
	s_add_i32 s66, s58, s26
	s_add_i32 s65, s66, 0x2000
	ds_read_b128 v[172:175], v138
	ds_read_b128 v[178:181], v138 offset:1024
	ds_read_b128 v[182:185], v138 offset:2048
	ds_read_b128 v[186:189], v138 offset:3072
	ds_read_b128 v[190:193], v138 offset:4096
	ds_read_b128 v[194:197], v138 offset:5120
	ds_read_b128 v[198:201], v138 offset:6144
	ds_read_b128 v[202:205], v138 offset:7168
	global_load_lds_dwordx4 v134, s[46:47]
	s_mov_b32 m0, s67
	s_nop 0
	global_load_lds_dwordx4 v130, s[46:47]
	s_waitcnt vmcnt(8)
	s_waitcnt lgkmcnt(0)
	s_barrier
	s_setprio 1
	s_waitcnt lgkmcnt(0)
	v_mfma_f32_16x16x32_bf16 v[124:127], v[140:143], v[172:175], 0
	v_mfma_f32_16x16x32_bf16 v[120:123], v[148:151], v[172:175], 0
	v_mfma_f32_16x16x32_bf16 v[116:119], v[140:143], v[182:185], 0
	v_mfma_f32_16x16x32_bf16 v[112:115], v[148:151], v[182:185], 0
	v_mfma_f32_16x16x32_bf16 v[100:103], v[140:143], v[190:193], 0
	v_mfma_f32_16x16x32_bf16 v[96:99], v[148:151], v[190:193], 0
	v_mfma_f32_16x16x32_bf16 v[84:87], v[140:143], v[198:201], 0
	v_mfma_f32_16x16x32_bf16 v[80:83], v[148:151], v[198:201], 0
	v_mfma_f32_16x16x32_bf16 v[124:127], v[144:147], v[178:181], v[124:127]
	v_mfma_f32_16x16x32_bf16 v[120:123], v[152:155], v[178:181], v[120:123]
	v_mfma_f32_16x16x32_bf16 v[116:119], v[144:147], v[186:189], v[116:119]
	v_mfma_f32_16x16x32_bf16 v[112:115], v[152:155], v[186:189], v[112:115]
	v_mfma_f32_16x16x32_bf16 v[100:103], v[144:147], v[194:197], v[100:103]
	v_mfma_f32_16x16x32_bf16 v[96:99], v[152:155], v[194:197], v[96:99]
	v_mfma_f32_16x16x32_bf16 v[84:87], v[144:147], v[202:205], v[84:87]
	v_mfma_f32_16x16x32_bf16 v[80:83], v[152:155], v[202:205], v[80:83]
	s_setprio 0
	s_setprio 1
	v_mfma_f32_16x16x32_bf16 v[108:111], v[156:159], v[172:175], 0
	v_mfma_f32_16x16x32_bf16 v[104:107], v[164:167], v[172:175], 0
	v_mfma_f32_16x16x32_bf16 v[92:95], v[156:159], v[182:185], 0
	v_mfma_f32_16x16x32_bf16 v[88:91], v[164:167], v[182:185], 0
	v_mfma_f32_16x16x32_bf16 v[76:79], v[156:159], v[190:193], 0
	v_mfma_f32_16x16x32_bf16 v[72:75], v[164:167], v[190:193], 0
	v_mfma_f32_16x16x32_bf16 v[68:71], v[156:159], v[198:201], 0
	v_mfma_f32_16x16x32_bf16 v[64:67], v[164:167], v[198:201], 0
	v_mfma_f32_16x16x32_bf16 v[108:111], v[160:163], v[178:181], v[108:111]
	v_mfma_f32_16x16x32_bf16 v[104:107], v[168:171], v[178:181], v[104:107]
	v_mfma_f32_16x16x32_bf16 v[92:95], v[160:163], v[186:189], v[92:95]
	v_mfma_f32_16x16x32_bf16 v[88:91], v[168:171], v[186:189], v[88:91]
	v_mfma_f32_16x16x32_bf16 v[76:79], v[160:163], v[194:197], v[76:79]
	v_mfma_f32_16x16x32_bf16 v[72:75], v[168:171], v[194:197], v[72:75]
	v_mfma_f32_16x16x32_bf16 v[68:71], v[160:163], v[202:205], v[68:71]
	v_mfma_f32_16x16x32_bf16 v[64:67], v[168:171], v[202:205], v[64:67]
	s_setprio 0
	s_barrier
	s_mov_b32 m0, s64
	ds_read_b128 v[172:175], v138 offset:16384
	ds_read_b128 v[178:181], v138 offset:17408
	ds_read_b128 v[182:185], v138 offset:18432
	ds_read_b128 v[186:189], v138 offset:19456
	ds_read_b128 v[190:193], v138 offset:20480
	ds_read_b128 v[194:197], v138 offset:21504
	ds_read_b128 v[198:201], v138 offset:22528
	ds_read_b128 v[202:205], v138 offset:23552
	global_load_lds_dwordx4 v132, s[40:41]
	s_mov_b32 m0, s60
	s_nop 0
	global_load_lds_dwordx4 v128, s[40:41]
	s_mov_b32 m0, s63
	s_nop 0
	global_load_lds_dwordx4 v132, s[42:43]
	s_mov_b32 m0, s61
	s_nop 0
	global_load_lds_dwordx4 v128, s[42:43]
	s_mov_b32 m0, s27
	s_nop 0
	global_load_lds_dwordx4 v134, s[38:39]
	s_mov_b32 m0, s33
	s_nop 0
	global_load_lds_dwordx4 v130, s[38:39]
	s_waitcnt vmcnt(8)
	s_waitcnt lgkmcnt(0)
	s_barrier
	s_setprio 1
	s_waitcnt lgkmcnt(0)
	v_mfma_f32_16x16x32_bf16 v[60:63], v[140:143], v[172:175], 0
	v_mfma_f32_16x16x32_bf16 v[56:59], v[148:151], v[172:175], 0
	v_mfma_f32_16x16x32_bf16 v[52:55], v[140:143], v[182:185], 0
	v_mfma_f32_16x16x32_bf16 v[48:51], v[148:151], v[182:185], 0
	v_mfma_f32_16x16x32_bf16 v[36:39], v[140:143], v[190:193], 0
	v_mfma_f32_16x16x32_bf16 v[32:35], v[148:151], v[190:193], 0
	v_mfma_f32_16x16x32_bf16 v[20:23], v[140:143], v[198:201], 0
	v_mfma_f32_16x16x32_bf16 v[16:19], v[148:151], v[198:201], 0
	v_mfma_f32_16x16x32_bf16 v[60:63], v[144:147], v[178:181], v[60:63]
	v_mfma_f32_16x16x32_bf16 v[56:59], v[152:155], v[178:181], v[56:59]
	v_mfma_f32_16x16x32_bf16 v[52:55], v[144:147], v[186:189], v[52:55]
	v_mfma_f32_16x16x32_bf16 v[48:51], v[152:155], v[186:189], v[48:51]
	v_mfma_f32_16x16x32_bf16 v[36:39], v[144:147], v[194:197], v[36:39]
	v_mfma_f32_16x16x32_bf16 v[32:35], v[152:155], v[194:197], v[32:35]
	v_mfma_f32_16x16x32_bf16 v[20:23], v[144:147], v[202:205], v[20:23]
	v_mfma_f32_16x16x32_bf16 v[16:19], v[152:155], v[202:205], v[16:19]
	s_setprio 0
	s_setprio 1
	v_mfma_f32_16x16x32_bf16 v[44:47], v[156:159], v[172:175], 0
	v_mfma_f32_16x16x32_bf16 v[40:43], v[164:167], v[172:175], 0
	v_mfma_f32_16x16x32_bf16 v[28:31], v[156:159], v[182:185], 0
	v_mfma_f32_16x16x32_bf16 v[24:27], v[164:167], v[182:185], 0
	v_mfma_f32_16x16x32_bf16 v[12:15], v[156:159], v[190:193], 0
	v_mfma_f32_16x16x32_bf16 v[8:11], v[164:167], v[190:193], 0
	v_mfma_f32_16x16x32_bf16 v[4:7], v[156:159], v[198:201], 0
	v_mfma_f32_16x16x32_bf16 v[0:3], v[164:167], v[198:201], 0
	v_mfma_f32_16x16x32_bf16 v[44:47], v[160:163], v[178:181], v[44:47]
	v_mfma_f32_16x16x32_bf16 v[40:43], v[168:171], v[178:181], v[40:43]
	v_mfma_f32_16x16x32_bf16 v[28:31], v[160:163], v[186:189], v[28:31]
	v_mfma_f32_16x16x32_bf16 v[24:27], v[168:171], v[186:189], v[24:27]
	v_mfma_f32_16x16x32_bf16 v[12:15], v[160:163], v[194:197], v[12:15]
	v_mfma_f32_16x16x32_bf16 v[8:11], v[168:171], v[194:197], v[8:11]
	v_mfma_f32_16x16x32_bf16 v[4:7], v[160:163], v[202:205], v[4:7]
	v_mfma_f32_16x16x32_bf16 v[0:3], v[168:171], v[202:205], v[0:3]
	s_setprio 0
	s_barrier
	v_add_u32_e32 v139, s59, v137
	ds_read_b128 v[140:143], v139
	ds_read_b128 v[144:147], v139 offset:1024
	ds_read_b128 v[148:151], v139 offset:2048
	ds_read_b128 v[152:155], v139 offset:3072
	v_add_u32_e32 v139, s58, v137
	ds_read_b128 v[156:159], v139
	ds_read_b128 v[160:163], v139 offset:1024
	ds_read_b128 v[164:167], v139 offset:2048
	ds_read_b128 v[168:171], v139 offset:3072
	s_mov_b32 m0, s44
	ds_read_b128 v[172:175], v138 offset:32768
	ds_read_b128 v[178:181], v138 offset:33792
	ds_read_b128 v[182:185], v138 offset:34816
	ds_read_b128 v[186:189], v138 offset:35840
	ds_read_b128 v[190:193], v138 offset:36864
	ds_read_b128 v[194:197], v138 offset:37888
	ds_read_b128 v[198:201], v138 offset:38912
	ds_read_b128 v[202:205], v138 offset:39936
	global_load_lds_dwordx4 v134, s[36:37]
	s_mov_b32 m0, s45
	s_nop 0
	global_load_lds_dwordx4 v130, s[36:37]
	s_waitcnt vmcnt(8)
	s_waitcnt lgkmcnt(0)
	s_barrier
	s_setprio 1
	s_waitcnt lgkmcnt(0)
	v_mfma_f32_16x16x32_bf16 v[124:127], v[140:143], v[172:175], v[124:127]
	v_mfma_f32_16x16x32_bf16 v[120:123], v[148:151], v[172:175], v[120:123]
	v_mfma_f32_16x16x32_bf16 v[116:119], v[140:143], v[182:185], v[116:119]
	v_mfma_f32_16x16x32_bf16 v[112:115], v[148:151], v[182:185], v[112:115]
	v_mfma_f32_16x16x32_bf16 v[100:103], v[140:143], v[190:193], v[100:103]
	v_mfma_f32_16x16x32_bf16 v[96:99], v[148:151], v[190:193], v[96:99]
	v_mfma_f32_16x16x32_bf16 v[84:87], v[140:143], v[198:201], v[84:87]
	v_mfma_f32_16x16x32_bf16 v[80:83], v[148:151], v[198:201], v[80:83]
	v_mfma_f32_16x16x32_bf16 v[124:127], v[144:147], v[178:181], v[124:127]
	v_mfma_f32_16x16x32_bf16 v[120:123], v[152:155], v[178:181], v[120:123]
	v_mfma_f32_16x16x32_bf16 v[116:119], v[144:147], v[186:189], v[116:119]
	v_mfma_f32_16x16x32_bf16 v[112:115], v[152:155], v[186:189], v[112:115]
	v_mfma_f32_16x16x32_bf16 v[100:103], v[144:147], v[194:197], v[100:103]
	v_mfma_f32_16x16x32_bf16 v[96:99], v[152:155], v[194:197], v[96:99]
	v_mfma_f32_16x16x32_bf16 v[84:87], v[144:147], v[202:205], v[84:87]
	v_mfma_f32_16x16x32_bf16 v[80:83], v[152:155], v[202:205], v[80:83]
	s_setprio 0
	s_setprio 1
	v_mfma_f32_16x16x32_bf16 v[108:111], v[156:159], v[172:175], v[108:111]
	v_mfma_f32_16x16x32_bf16 v[104:107], v[164:167], v[172:175], v[104:107]
	v_mfma_f32_16x16x32_bf16 v[92:95], v[156:159], v[182:185], v[92:95]
	v_mfma_f32_16x16x32_bf16 v[88:91], v[164:167], v[182:185], v[88:91]
	v_mfma_f32_16x16x32_bf16 v[76:79], v[156:159], v[190:193], v[76:79]
	v_mfma_f32_16x16x32_bf16 v[72:75], v[164:167], v[190:193], v[72:75]
	v_mfma_f32_16x16x32_bf16 v[68:71], v[156:159], v[198:201], v[68:71]
	v_mfma_f32_16x16x32_bf16 v[64:67], v[164:167], v[198:201], v[64:67]
	v_mfma_f32_16x16x32_bf16 v[108:111], v[160:163], v[178:181], v[108:111]
	v_mfma_f32_16x16x32_bf16 v[104:107], v[168:171], v[178:181], v[104:107]
	v_mfma_f32_16x16x32_bf16 v[92:95], v[160:163], v[186:189], v[92:95]
	v_mfma_f32_16x16x32_bf16 v[88:91], v[168:171], v[186:189], v[88:91]
	v_mfma_f32_16x16x32_bf16 v[76:79], v[160:163], v[194:197], v[76:79]
	v_mfma_f32_16x16x32_bf16 v[72:75], v[168:171], v[194:197], v[72:75]
	v_mfma_f32_16x16x32_bf16 v[68:71], v[160:163], v[202:205], v[68:71]
	v_mfma_f32_16x16x32_bf16 v[64:67], v[168:171], v[202:205], v[64:67]
	s_setprio 0
	s_barrier
	s_mov_b32 m0, s57
	ds_read_b128 v[172:175], v138 offset:49152
	ds_read_b128 v[178:181], v138 offset:50176
	ds_read_b128 v[182:185], v138 offset:51200
	ds_read_b128 v[186:189], v138 offset:52224
	ds_read_b128 v[190:193], v138 offset:53248
	ds_read_b128 v[194:197], v138 offset:54272
	ds_read_b128 v[198:201], v138 offset:55296
	ds_read_b128 v[202:205], v138 offset:56320
	s_add_u32 s98, s40, 0x80
	s_addc_u32 s99, s41, 0
	global_load_lds_dwordx4 v132, s[98:99]
	s_mov_b32 m0, s56
	s_nop 0
	s_add_u32 s98, s40, 0x80
	s_addc_u32 s99, s41, 0
	global_load_lds_dwordx4 v128, s[98:99]
	s_mov_b32 m0, s66
	s_nop 0
	global_load_lds_dwordx4 v132, s[34:35]
	s_mov_b32 m0, s65
	s_nop 0
	global_load_lds_dwordx4 v128, s[34:35]
	s_mov_b32 m0, s50
	s_nop 0
	s_add_u32 s98, s38, 0x80
	s_addc_u32 s99, s39, 0
	global_load_lds_dwordx4 v134, s[98:99]
	s_mov_b32 m0, s51
	s_nop 0
	s_add_u32 s98, s38, 0x80
	s_addc_u32 s99, s39, 0
	global_load_lds_dwordx4 v130, s[98:99]
	s_waitcnt vmcnt(8)
	s_waitcnt lgkmcnt(0)
	s_barrier
	s_setprio 1
	s_waitcnt lgkmcnt(0)
	v_mfma_f32_16x16x32_bf16 v[60:63], v[140:143], v[172:175], v[60:63]
	v_mfma_f32_16x16x32_bf16 v[56:59], v[148:151], v[172:175], v[56:59]
	v_mfma_f32_16x16x32_bf16 v[52:55], v[140:143], v[182:185], v[52:55]
	v_mfma_f32_16x16x32_bf16 v[48:51], v[148:151], v[182:185], v[48:51]
	v_mfma_f32_16x16x32_bf16 v[36:39], v[140:143], v[190:193], v[36:39]
	v_mfma_f32_16x16x32_bf16 v[32:35], v[148:151], v[190:193], v[32:35]
	v_mfma_f32_16x16x32_bf16 v[20:23], v[140:143], v[198:201], v[20:23]
	v_mfma_f32_16x16x32_bf16 v[16:19], v[148:151], v[198:201], v[16:19]
	v_mfma_f32_16x16x32_bf16 v[60:63], v[144:147], v[178:181], v[60:63]
	v_mfma_f32_16x16x32_bf16 v[56:59], v[152:155], v[178:181], v[56:59]
	v_mfma_f32_16x16x32_bf16 v[52:55], v[144:147], v[186:189], v[52:55]
	v_mfma_f32_16x16x32_bf16 v[48:51], v[152:155], v[186:189], v[48:51]
	v_mfma_f32_16x16x32_bf16 v[36:39], v[144:147], v[194:197], v[36:39]
	v_mfma_f32_16x16x32_bf16 v[32:35], v[152:155], v[194:197], v[32:35]
	v_mfma_f32_16x16x32_bf16 v[20:23], v[144:147], v[202:205], v[20:23]
	v_mfma_f32_16x16x32_bf16 v[16:19], v[152:155], v[202:205], v[16:19]
	s_setprio 0
	s_setprio 1
	v_mfma_f32_16x16x32_bf16 v[44:47], v[156:159], v[172:175], v[44:47]
	v_mfma_f32_16x16x32_bf16 v[40:43], v[164:167], v[172:175], v[40:43]
	v_mfma_f32_16x16x32_bf16 v[28:31], v[156:159], v[182:185], v[28:31]
	v_mfma_f32_16x16x32_bf16 v[24:27], v[164:167], v[182:185], v[24:27]
	v_mfma_f32_16x16x32_bf16 v[12:15], v[156:159], v[190:193], v[12:15]
	v_mfma_f32_16x16x32_bf16 v[8:11], v[164:167], v[190:193], v[8:11]
	v_mfma_f32_16x16x32_bf16 v[4:7], v[156:159], v[198:201], v[4:7]
	v_mfma_f32_16x16x32_bf16 v[0:3], v[164:167], v[198:201], v[0:3]
	v_mfma_f32_16x16x32_bf16 v[44:47], v[160:163], v[178:181], v[44:47]
	v_mfma_f32_16x16x32_bf16 v[40:43], v[168:171], v[178:181], v[40:43]
	v_mfma_f32_16x16x32_bf16 v[28:31], v[160:163], v[186:189], v[28:31]
	v_mfma_f32_16x16x32_bf16 v[24:27], v[168:171], v[186:189], v[24:27]
	v_mfma_f32_16x16x32_bf16 v[12:15], v[160:163], v[194:197], v[12:15]
	v_mfma_f32_16x16x32_bf16 v[8:11], v[168:171], v[194:197], v[8:11]
	v_mfma_f32_16x16x32_bf16 v[4:7], v[160:163], v[202:205], v[4:7]
	v_mfma_f32_16x16x32_bf16 v[0:3], v[168:171], v[202:205], v[0:3]
	s_setprio 0
	s_barrier
	s_movk_i32 s36, 0x100
	s_andn2_b64 vcc, exec, s[30:31]
	s_mov_b64 s[34:35], -1
	s_mov_b64 s[30:31], 0

.LBB0_729:
	s_ashr_i32 s7, s6, 31
	s_lshl_b64 s[24:25], s[6:7], 22
	s_add_u32 s7, s26, s24
	s_addc_u32 s16, s27, s25
	s_and_b64 s[14:15], s[14:15], exec
	s_cselect_b32 s15, s16, s19
	s_cselect_b32 s14, s7, s18
	s_add_u32 s18, s18, 0x200080
	s_addc_u32 s19, s19, 0
	s_add_u32 s7, s22, 0x100
	s_addc_u32 s40, s23, 0
	s_mov_b32 s41, -2
	s_add_u32 s16, s18, 0xffe00080
	s_addc_u32 s17, s19, -1
	s_add_i32 s42, 0, 0x10000
	s_cmpk_eq_i32 s41, 0x7c
	s_cselect_b32 s25, s15, s17
	s_cselect_b32 s24, s14, s16
	s_cselect_b32 s23, s13, s40
	s_cselect_b32 s22, s12, s7
	s_add_i32 s16, 0, 0x14000
	v_add_u32_e32 v156, s42, v142
	v_add_u32_e32 v172, s16, v142
	ds_read_b128 v[144:147], v156
	ds_read_b128 v[148:151], v156 offset:1024
	ds_read_b128 v[152:155], v156 offset:2048
	ds_read_b128 v[156:159], v156 offset:3072
	ds_read_b128 v[160:163], v172
	ds_read_b128 v[164:167], v172 offset:1024
	ds_read_b128 v[168:171], v172 offset:2048
	ds_read_b128 v[172:175], v172 offset:3072
	s_add_i32 m0, s31, 0xc000
	ds_read_b128 v[178:181], v143
	ds_read_b128 v[182:185], v143 offset:1024
	ds_read_b128 v[186:189], v143 offset:2048
	ds_read_b128 v[190:193], v143 offset:3072
	ds_read_b128 v[194:197], v143 offset:4096
	ds_read_b128 v[198:201], v143 offset:5120
	ds_read_b128 v[202:205], v143 offset:6144
	ds_read_b128 v[206:209], v143 offset:7168
	global_load_lds_dwordx4 v138, s[18:19]
	s_add_i32 m0, s31, 0xe000
	s_nop 0
	global_load_lds_dwordx4 v140, s[18:19]
	s_waitcnt vmcnt(8)
	s_waitcnt lgkmcnt(0)
	s_barrier
	s_setprio 1
	s_waitcnt lgkmcnt(0)
	v_mfma_f32_16x16x32_bf16 v[124:127], v[144:147], v[178:181], 0
	v_mfma_f32_16x16x32_bf16 v[120:123], v[152:155], v[178:181], 0
	v_mfma_f32_16x16x32_bf16 v[116:119], v[144:147], v[186:189], 0
	v_mfma_f32_16x16x32_bf16 v[112:115], v[152:155], v[186:189], 0
	v_mfma_f32_16x16x32_bf16 v[100:103], v[144:147], v[194:197], 0
	v_mfma_f32_16x16x32_bf16 v[96:99], v[152:155], v[194:197], 0
	v_mfma_f32_16x16x32_bf16 v[84:87], v[144:147], v[202:205], 0
	v_mfma_f32_16x16x32_bf16 v[80:83], v[152:155], v[202:205], 0
	v_mfma_f32_16x16x32_bf16 v[124:127], v[148:151], v[182:185], v[124:127]
	v_mfma_f32_16x16x32_bf16 v[120:123], v[156:159], v[182:185], v[120:123]
	v_mfma_f32_16x16x32_bf16 v[116:119], v[148:151], v[190:193], v[116:119]
	v_mfma_f32_16x16x32_bf16 v[112:115], v[156:159], v[190:193], v[112:115]
	v_mfma_f32_16x16x32_bf16 v[100:103], v[148:151], v[198:201], v[100:103]
	v_mfma_f32_16x16x32_bf16 v[96:99], v[156:159], v[198:201], v[96:99]
	v_mfma_f32_16x16x32_bf16 v[84:87], v[148:151], v[206:209], v[84:87]
	v_mfma_f32_16x16x32_bf16 v[80:83], v[156:159], v[206:209], v[80:83]
	s_setprio 0
	s_setprio 1
	v_mfma_f32_16x16x32_bf16 v[108:111], v[160:163], v[178:181], 0
	v_mfma_f32_16x16x32_bf16 v[104:107], v[168:171], v[178:181], 0
	v_mfma_f32_16x16x32_bf16 v[92:95], v[160:163], v[186:189], 0
	v_mfma_f32_16x16x32_bf16 v[88:91], v[168:171], v[186:189], 0
	v_mfma_f32_16x16x32_bf16 v[76:79], v[160:163], v[194:197], 0
	v_mfma_f32_16x16x32_bf16 v[72:75], v[168:171], v[194:197], 0
	v_mfma_f32_16x16x32_bf16 v[68:71], v[160:163], v[202:205], 0
	v_mfma_f32_16x16x32_bf16 v[64:67], v[168:171], v[202:205], 0
	v_mfma_f32_16x16x32_bf16 v[108:111], v[164:167], v[182:185], v[108:111]
	v_mfma_f32_16x16x32_bf16 v[104:107], v[172:175], v[182:185], v[104:107]
	v_mfma_f32_16x16x32_bf16 v[92:95], v[164:167], v[190:193], v[92:95]
	v_mfma_f32_16x16x32_bf16 v[88:91], v[172:175], v[190:193], v[88:91]
	v_mfma_f32_16x16x32_bf16 v[76:79], v[164:167], v[198:201], v[76:79]
	v_mfma_f32_16x16x32_bf16 v[72:75], v[172:175], v[198:201], v[72:75]
	v_mfma_f32_16x16x32_bf16 v[68:71], v[164:167], v[206:209], v[68:71]
	v_mfma_f32_16x16x32_bf16 v[64:67], v[172:175], v[206:209], v[64:67]
	s_setprio 0
	s_barrier
	s_add_i32 s17, s42, s28
	s_mov_b32 m0, s17
	ds_read_b128 v[178:181], v143 offset:16384
	ds_read_b128 v[182:185], v143 offset:17408
	ds_read_b128 v[186:189], v143 offset:18432
	ds_read_b128 v[190:193], v143 offset:19456
	ds_read_b128 v[194:197], v143 offset:20480
	ds_read_b128 v[198:201], v143 offset:21504
	ds_read_b128 v[202:205], v143 offset:22528
	ds_read_b128 v[206:209], v143 offset:23552
	global_load_lds_dwordx4 v132, s[22:23]
	s_add_i32 m0, s17, 0x2000
	s_add_u32 s42, s22, 0x400000
	s_addc_u32 s43, s23, 0
	s_add_i32 s16, s16, s28
	global_load_lds_dwordx4 v128, s[22:23]
	s_mov_b32 m0, s16
	s_nop 0
	global_load_lds_dwordx4 v132, s[42:43]
	s_add_i32 m0, s16, 0x2000
	s_nop 0
	global_load_lds_dwordx4 v128, s[42:43]
	s_mov_b32 m0, s31
	s_nop 0
	global_load_lds_dwordx4 v134, s[24:25]
	s_mov_b32 m0, s8
	s_nop 0
	global_load_lds_dwordx4 v130, s[24:25]
	s_waitcnt vmcnt(8)
	s_waitcnt lgkmcnt(0)
	s_barrier
	s_setprio 1
	s_waitcnt lgkmcnt(0)
	v_mfma_f32_16x16x32_bf16 v[60:63], v[144:147], v[178:181], 0
	v_mfma_f32_16x16x32_bf16 v[56:59], v[152:155], v[178:181], 0
	v_mfma_f32_16x16x32_bf16 v[52:55], v[144:147], v[186:189], 0
	v_mfma_f32_16x16x32_bf16 v[48:51], v[152:155], v[186:189], 0
	v_mfma_f32_16x16x32_bf16 v[36:39], v[144:147], v[194:197], 0
	v_mfma_f32_16x16x32_bf16 v[32:35], v[152:155], v[194:197], 0
	v_mfma_f32_16x16x32_bf16 v[20:23], v[144:147], v[202:205], 0
	v_mfma_f32_16x16x32_bf16 v[16:19], v[152:155], v[202:205], 0
	v_mfma_f32_16x16x32_bf16 v[60:63], v[148:151], v[182:185], v[60:63]
	v_mfma_f32_16x16x32_bf16 v[56:59], v[156:159], v[182:185], v[56:59]
	v_mfma_f32_16x16x32_bf16 v[52:55], v[148:151], v[190:193], v[52:55]
	v_mfma_f32_16x16x32_bf16 v[48:51], v[156:159], v[190:193], v[48:51]
	v_mfma_f32_16x16x32_bf16 v[36:39], v[148:151], v[198:201], v[36:39]
	v_mfma_f32_16x16x32_bf16 v[32:35], v[156:159], v[198:201], v[32:35]
	v_mfma_f32_16x16x32_bf16 v[20:23], v[148:151], v[206:209], v[20:23]
	v_mfma_f32_16x16x32_bf16 v[16:19], v[156:159], v[206:209], v[16:19]
	s_setprio 0
	s_setprio 1
	v_mfma_f32_16x16x32_bf16 v[44:47], v[160:163], v[178:181], 0
	v_mfma_f32_16x16x32_bf16 v[40:43], v[168:171], v[178:181], 0
	v_mfma_f32_16x16x32_bf16 v[28:31], v[160:163], v[186:189], 0
	v_mfma_f32_16x16x32_bf16 v[24:27], v[168:171], v[186:189], 0
	v_mfma_f32_16x16x32_bf16 v[12:15], v[160:163], v[194:197], 0
	v_mfma_f32_16x16x32_bf16 v[8:11], v[168:171], v[194:197], 0
	v_mfma_f32_16x16x32_bf16 v[4:7], v[160:163], v[202:205], 0
	v_mfma_f32_16x16x32_bf16 v[0:3], v[168:171], v[202:205], 0
	v_mfma_f32_16x16x32_bf16 v[44:47], v[164:167], v[182:185], v[44:47]
	v_mfma_f32_16x16x32_bf16 v[40:43], v[172:175], v[182:185], v[40:43]
	v_mfma_f32_16x16x32_bf16 v[28:31], v[164:167], v[190:193], v[28:31]
	v_mfma_f32_16x16x32_bf16 v[24:27], v[172:175], v[190:193], v[24:27]
	v_mfma_f32_16x16x32_bf16 v[12:15], v[164:167], v[198:201], v[12:15]
	v_mfma_f32_16x16x32_bf16 v[8:11], v[172:175], v[198:201], v[8:11]
	v_mfma_f32_16x16x32_bf16 v[4:7], v[164:167], v[206:209], v[4:7]
	v_mfma_f32_16x16x32_bf16 v[0:3], v[172:175], v[206:209], v[0:3]
	s_setprio 0
	s_barrier
	s_add_i32 s16, 0, 0x18000
	s_add_i32 s17, 0, 0x1c000
	v_add_u32_e32 v156, s16, v142
	v_add_u32_e32 v172, s17, v142
	ds_read_b128 v[144:147], v156
	ds_read_b128 v[148:151], v156 offset:1024
	ds_read_b128 v[152:155], v156 offset:2048
	ds_read_b128 v[156:159], v156 offset:3072
	ds_read_b128 v[160:163], v172
	ds_read_b128 v[164:167], v172 offset:1024
	ds_read_b128 v[168:171], v172 offset:2048
	ds_read_b128 v[172:175], v172 offset:3072
	s_add_u32 s24, s24, 0x200000
	s_addc_u32 s25, s25, 0
	s_mov_b32 m0, s9
	ds_read_b128 v[178:181], v143 offset:32768
	ds_read_b128 v[182:185], v143 offset:33792
	ds_read_b128 v[186:189], v143 offset:34816
	ds_read_b128 v[190:193], v143 offset:35840
	ds_read_b128 v[194:197], v143 offset:36864
	ds_read_b128 v[198:201], v143 offset:37888
	ds_read_b128 v[202:205], v143 offset:38912
	ds_read_b128 v[206:209], v143 offset:39936
	global_load_lds_dwordx4 v134, s[24:25]
	s_mov_b32 m0, s33
	s_nop 0
	global_load_lds_dwordx4 v130, s[24:25]
	s_waitcnt vmcnt(8)
	s_waitcnt lgkmcnt(0)
	s_barrier
	s_setprio 1
	s_waitcnt lgkmcnt(0)
	v_mfma_f32_16x16x32_bf16 v[124:127], v[144:147], v[178:181], v[124:127]
	v_mfma_f32_16x16x32_bf16 v[120:123], v[152:155], v[178:181], v[120:123]
	v_mfma_f32_16x16x32_bf16 v[116:119], v[144:147], v[186:189], v[116:119]
	v_mfma_f32_16x16x32_bf16 v[112:115], v[152:155], v[186:189], v[112:115]
	v_mfma_f32_16x16x32_bf16 v[100:103], v[144:147], v[194:197], v[100:103]
	v_mfma_f32_16x16x32_bf16 v[96:99], v[152:155], v[194:197], v[96:99]
	v_mfma_f32_16x16x32_bf16 v[84:87], v[144:147], v[202:205], v[84:87]
	v_mfma_f32_16x16x32_bf16 v[80:83], v[152:155], v[202:205], v[80:83]
	v_mfma_f32_16x16x32_bf16 v[124:127], v[148:151], v[182:185], v[124:127]
	v_mfma_f32_16x16x32_bf16 v[120:123], v[156:159], v[182:185], v[120:123]
	v_mfma_f32_16x16x32_bf16 v[116:119], v[148:151], v[190:193], v[116:119]
	v_mfma_f32_16x16x32_bf16 v[112:115], v[156:159], v[190:193], v[112:115]
	v_mfma_f32_16x16x32_bf16 v[100:103], v[148:151], v[198:201], v[100:103]
	v_mfma_f32_16x16x32_bf16 v[96:99], v[156:159], v[198:201], v[96:99]
	v_mfma_f32_16x16x32_bf16 v[84:87], v[148:151], v[206:209], v[84:87]
	v_mfma_f32_16x16x32_bf16 v[80:83], v[156:159], v[206:209], v[80:83]
	s_setprio 0
	s_setprio 1
	v_mfma_f32_16x16x32_bf16 v[108:111], v[160:163], v[178:181], v[108:111]
	v_mfma_f32_16x16x32_bf16 v[104:107], v[168:171], v[178:181], v[104:107]
	v_mfma_f32_16x16x32_bf16 v[92:95], v[160:163], v[186:189], v[92:95]
	v_mfma_f32_16x16x32_bf16 v[88:91], v[168:171], v[186:189], v[88:91]
	v_mfma_f32_16x16x32_bf16 v[76:79], v[160:163], v[194:197], v[76:79]
	v_mfma_f32_16x16x32_bf16 v[72:75], v[168:171], v[194:197], v[72:75]
	v_mfma_f32_16x16x32_bf16 v[68:71], v[160:163], v[202:205], v[68:71]
	v_mfma_f32_16x16x32_bf16 v[64:67], v[168:171], v[202:205], v[64:67]
	v_mfma_f32_16x16x32_bf16 v[108:111], v[164:167], v[182:185], v[108:111]
	v_mfma_f32_16x16x32_bf16 v[104:107], v[172:175], v[182:185], v[104:107]
	v_mfma_f32_16x16x32_bf16 v[92:95], v[164:167], v[190:193], v[92:95]
	v_mfma_f32_16x16x32_bf16 v[88:91], v[172:175], v[190:193], v[88:91]
	v_mfma_f32_16x16x32_bf16 v[76:79], v[164:167], v[198:201], v[76:79]
	v_mfma_f32_16x16x32_bf16 v[72:75], v[172:175], v[198:201], v[72:75]
	v_mfma_f32_16x16x32_bf16 v[68:71], v[164:167], v[206:209], v[68:71]
	v_mfma_f32_16x16x32_bf16 v[64:67], v[172:175], v[206:209], v[64:67]
	s_setprio 0
	s_barrier
	s_add_i32 s16, s16, s28
	s_mov_b32 m0, s16
	ds_read_b128 v[178:181], v143 offset:49152
	ds_read_b128 v[182:185], v143 offset:50176
	ds_read_b128 v[186:189], v143 offset:51200
	ds_read_b128 v[190:193], v143 offset:52224
	ds_read_b128 v[194:197], v143 offset:53248
	ds_read_b128 v[198:201], v143 offset:54272
	ds_read_b128 v[202:205], v143 offset:55296
	ds_read_b128 v[206:209], v143 offset:56320
	s_add_u32 s98, s22, 0x80
	s_addc_u32 s99, s23, 0
	global_load_lds_dwordx4 v132, s[98:99]
	s_add_i32 m0, s16, 0x2000
	s_add_u32 s22, s22, 0x400080
	s_addc_u32 s23, s23, 0
	s_add_i32 s16, s17, s28
	s_add_u32 s98, s42, 0xffc00080
	s_addc_u32 s99, s43, -1
	global_load_lds_dwordx4 v128, s[98:99]
	s_mov_b32 m0, s16
	s_nop 0
	global_load_lds_dwordx4 v132, s[22:23]
	s_add_i32 m0, s16, 0x2000
	s_nop 0
	global_load_lds_dwordx4 v128, s[22:23]
	s_mov_b32 m0, s34
	s_nop 0
	s_add_u32 s98, s24, 0xffe00080
	s_addc_u32 s99, s25, -1
	global_load_lds_dwordx4 v134, s[98:99]
	s_mov_b32 m0, s35
	s_nop 0
	s_add_u32 s98, s24, 0xffe00080
	s_addc_u32 s99, s25, -1
	global_load_lds_dwordx4 v130, s[98:99]
	s_waitcnt vmcnt(8)
	s_waitcnt lgkmcnt(0)
	s_barrier
	s_setprio 1
	s_waitcnt lgkmcnt(0)
	v_mfma_f32_16x16x32_bf16 v[60:63], v[144:147], v[178:181], v[60:63]
	v_mfma_f32_16x16x32_bf16 v[56:59], v[152:155], v[178:181], v[56:59]
	v_mfma_f32_16x16x32_bf16 v[52:55], v[144:147], v[186:189], v[52:55]
	v_mfma_f32_16x16x32_bf16 v[48:51], v[152:155], v[186:189], v[48:51]
	v_mfma_f32_16x16x32_bf16 v[36:39], v[144:147], v[194:197], v[36:39]
	v_mfma_f32_16x16x32_bf16 v[32:35], v[152:155], v[194:197], v[32:35]
	v_mfma_f32_16x16x32_bf16 v[20:23], v[144:147], v[202:205], v[20:23]
	v_mfma_f32_16x16x32_bf16 v[16:19], v[152:155], v[202:205], v[16:19]
	v_mfma_f32_16x16x32_bf16 v[60:63], v[148:151], v[182:185], v[60:63]
	v_mfma_f32_16x16x32_bf16 v[56:59], v[156:159], v[182:185], v[56:59]
	v_mfma_f32_16x16x32_bf16 v[52:55], v[148:151], v[190:193], v[52:55]
	v_mfma_f32_16x16x32_bf16 v[48:51], v[156:159], v[190:193], v[48:51]
	v_mfma_f32_16x16x32_bf16 v[36:39], v[148:151], v[198:201], v[36:39]
	v_mfma_f32_16x16x32_bf16 v[32:35], v[156:159], v[198:201], v[32:35]
	v_mfma_f32_16x16x32_bf16 v[20:23], v[148:151], v[206:209], v[20:23]
	v_mfma_f32_16x16x32_bf16 v[16:19], v[156:159], v[206:209], v[16:19]
	s_setprio 0
	s_setprio 1
	v_mfma_f32_16x16x32_bf16 v[44:47], v[160:163], v[178:181], v[44:47]
	v_mfma_f32_16x16x32_bf16 v[40:43], v[168:171], v[178:181], v[40:43]
	v_mfma_f32_16x16x32_bf16 v[28:31], v[160:163], v[186:189], v[28:31]
	v_mfma_f32_16x16x32_bf16 v[24:27], v[168:171], v[186:189], v[24:27]
	v_mfma_f32_16x16x32_bf16 v[12:15], v[160:163], v[194:197], v[12:15]
	v_mfma_f32_16x16x32_bf16 v[8:11], v[168:171], v[194:197], v[8:11]
	v_mfma_f32_16x16x32_bf16 v[4:7], v[160:163], v[202:205], v[4:7]
	v_mfma_f32_16x16x32_bf16 v[0:3], v[168:171], v[202:205], v[0:3]
	v_mfma_f32_16x16x32_bf16 v[44:47], v[164:167], v[182:185], v[44:47]
	v_mfma_f32_16x16x32_bf16 v[40:43], v[172:175], v[182:185], v[40:43]
	v_mfma_f32_16x16x32_bf16 v[28:31], v[164:167], v[190:193], v[28:31]
	v_mfma_f32_16x16x32_bf16 v[24:27], v[172:175], v[190:193], v[24:27]
	v_mfma_f32_16x16x32_bf16 v[12:15], v[164:167], v[198:201], v[12:15]
	v_mfma_f32_16x16x32_bf16 v[8:11], v[172:175], v[198:201], v[8:11]
	v_mfma_f32_16x16x32_bf16 v[4:7], v[164:167], v[206:209], v[4:7]
	v_mfma_f32_16x16x32_bf16 v[0:3], v[172:175], v[206:209], v[0:3]
	s_setprio 0
	s_barrier
	s_add_i32 s41, s41, 2
	s_add_u32 s18, s18, 0x100
	s_addc_u32 s19, s19, 0
	s_add_u32 s7, s7, 0x100
	s_addc_u32 s40, s40, 0
	s_cmpk_gt_u32 s41, 0x7d

.LBB0_747:
	s_ashr_i32 s7, s6, 31
	s_lshl_b64 s[22:23], s[6:7], 21
	s_add_u32 s7, s2, s22
	s_addc_u32 s22, s21, s23
	s_and_b64 s[14:15], s[14:15], exec
	s_cselect_b32 s15, s22, s17
	s_cselect_b32 s14, s7, s16
	s_add_u32 s16, s16, 0x100080
	s_addc_u32 s17, s17, 0
	s_add_u32 s7, s18, 0x100
	s_addc_u32 s36, s19, 0
	s_mov_b32 s37, -2
	s_add_u32 s18, s16, 0xfff00080
	s_addc_u32 s19, s17, -1
	s_add_i32 s38, 0, 0x10000
	s_cmp_eq_u32 s37, 60
	s_cselect_b32 s23, s15, s19
	s_cselect_b32 s22, s14, s18
	s_cselect_b32 s19, s13, s36
	s_cselect_b32 s18, s12, s7
	s_add_i32 s40, 0, 0x14000
	v_add_u32_e32 v156, s38, v142
	v_add_u32_e32 v172, s40, v142
	ds_read_b128 v[144:147], v156
	ds_read_b128 v[148:151], v156 offset:1024
	ds_read_b128 v[152:155], v156 offset:2048
	ds_read_b128 v[156:159], v156 offset:3072
	ds_read_b128 v[160:163], v172
	ds_read_b128 v[164:167], v172 offset:1024
	ds_read_b128 v[168:171], v172 offset:2048
	ds_read_b128 v[172:175], v172 offset:3072
	s_add_i32 m0, s27, 0xc000
	ds_read_b128 v[178:181], v143
	ds_read_b128 v[182:185], v143 offset:1024
	ds_read_b128 v[186:189], v143 offset:2048
	ds_read_b128 v[190:193], v143 offset:3072
	ds_read_b128 v[194:197], v143 offset:4096
	ds_read_b128 v[198:201], v143 offset:5120
	ds_read_b128 v[202:205], v143 offset:6144
	ds_read_b128 v[206:209], v143 offset:7168
	global_load_lds_dwordx4 v138, s[16:17]
	s_add_i32 m0, s27, 0xe000
	s_nop 0
	global_load_lds_dwordx4 v140, s[16:17]
	s_waitcnt vmcnt(8)
	s_waitcnt lgkmcnt(0)
	s_barrier
	s_setprio 1
	s_waitcnt lgkmcnt(0)
	v_mfma_f32_16x16x32_bf16 v[124:127], v[144:147], v[178:181], 0
	v_mfma_f32_16x16x32_bf16 v[120:123], v[152:155], v[178:181], 0
	v_mfma_f32_16x16x32_bf16 v[116:119], v[144:147], v[186:189], 0
	v_mfma_f32_16x16x32_bf16 v[112:115], v[152:155], v[186:189], 0
	v_mfma_f32_16x16x32_bf16 v[100:103], v[144:147], v[194:197], 0
	v_mfma_f32_16x16x32_bf16 v[96:99], v[152:155], v[194:197], 0
	v_mfma_f32_16x16x32_bf16 v[84:87], v[144:147], v[202:205], 0
	v_mfma_f32_16x16x32_bf16 v[80:83], v[152:155], v[202:205], 0
	v_mfma_f32_16x16x32_bf16 v[124:127], v[148:151], v[182:185], v[124:127]
	v_mfma_f32_16x16x32_bf16 v[120:123], v[156:159], v[182:185], v[120:123]
	v_mfma_f32_16x16x32_bf16 v[116:119], v[148:151], v[190:193], v[116:119]
	v_mfma_f32_16x16x32_bf16 v[112:115], v[156:159], v[190:193], v[112:115]
	v_mfma_f32_16x16x32_bf16 v[100:103], v[148:151], v[198:201], v[100:103]
	v_mfma_f32_16x16x32_bf16 v[96:99], v[156:159], v[198:201], v[96:99]
	v_mfma_f32_16x16x32_bf16 v[84:87], v[148:151], v[206:209], v[84:87]
	v_mfma_f32_16x16x32_bf16 v[80:83], v[156:159], v[206:209], v[80:83]
	s_setprio 0
	s_setprio 1
	v_mfma_f32_16x16x32_bf16 v[108:111], v[160:163], v[178:181], 0
	v_mfma_f32_16x16x32_bf16 v[104:107], v[168:171], v[178:181], 0
	v_mfma_f32_16x16x32_bf16 v[92:95], v[160:163], v[186:189], 0
	v_mfma_f32_16x16x32_bf16 v[88:91], v[168:171], v[186:189], 0
	v_mfma_f32_16x16x32_bf16 v[76:79], v[160:163], v[194:197], 0
	v_mfma_f32_16x16x32_bf16 v[72:75], v[168:171], v[194:197], 0
	v_mfma_f32_16x16x32_bf16 v[68:71], v[160:163], v[202:205], 0
	v_mfma_f32_16x16x32_bf16 v[64:67], v[168:171], v[202:205], 0
	v_mfma_f32_16x16x32_bf16 v[108:111], v[164:167], v[182:185], v[108:111]
	v_mfma_f32_16x16x32_bf16 v[104:107], v[172:175], v[182:185], v[104:107]
	v_mfma_f32_16x16x32_bf16 v[92:95], v[164:167], v[190:193], v[92:95]
	v_mfma_f32_16x16x32_bf16 v[88:91], v[172:175], v[190:193], v[88:91]
	v_mfma_f32_16x16x32_bf16 v[76:79], v[164:167], v[198:201], v[76:79]
	v_mfma_f32_16x16x32_bf16 v[72:75], v[172:175], v[198:201], v[72:75]
	v_mfma_f32_16x16x32_bf16 v[68:71], v[164:167], v[206:209], v[68:71]
	v_mfma_f32_16x16x32_bf16 v[64:67], v[172:175], v[206:209], v[64:67]
	s_setprio 0
	s_barrier
	s_add_i32 s38, s38, s26
	s_mov_b32 m0, s38
	ds_read_b128 v[178:181], v143 offset:16384
	ds_read_b128 v[182:185], v143 offset:17408
	ds_read_b128 v[186:189], v143 offset:18432
	ds_read_b128 v[190:193], v143 offset:19456
	ds_read_b128 v[194:197], v143 offset:20480
	ds_read_b128 v[198:201], v143 offset:21504
	ds_read_b128 v[202:205], v143 offset:22528
	ds_read_b128 v[206:209], v143 offset:23552
	global_load_lds_dwordx4 v132, s[18:19]
	s_add_i32 m0, s38, 0x2000
	s_add_u32 s38, s18, 0x800000
	s_addc_u32 s39, s19, 0
	s_add_i32 s40, s40, s26
	global_load_lds_dwordx4 v128, s[18:19]
	s_mov_b32 m0, s40
	s_nop 0
	global_load_lds_dwordx4 v132, s[38:39]
	s_add_i32 m0, s40, 0x2000
	s_nop 0
	global_load_lds_dwordx4 v128, s[38:39]
	s_add_u32 s60, s22, 0x80
	s_addc_u32 s61, s23, 0
	s_mov_b32 m0, s27
	s_nop 0
	global_load_lds_dwordx4 v134, s[22:23]
	s_mov_b32 m0, s8
	s_nop 0
	global_load_lds_dwordx4 v130, s[22:23]
	s_waitcnt vmcnt(8)
	s_waitcnt lgkmcnt(0)
	s_barrier
	s_setprio 1
	s_waitcnt lgkmcnt(0)
	v_mfma_f32_16x16x32_bf16 v[60:63], v[144:147], v[178:181], 0
	v_mfma_f32_16x16x32_bf16 v[56:59], v[152:155], v[178:181], 0
	v_mfma_f32_16x16x32_bf16 v[52:55], v[144:147], v[186:189], 0
	v_mfma_f32_16x16x32_bf16 v[48:51], v[152:155], v[186:189], 0
	v_mfma_f32_16x16x32_bf16 v[36:39], v[144:147], v[194:197], 0
	v_mfma_f32_16x16x32_bf16 v[32:35], v[152:155], v[194:197], 0
	v_mfma_f32_16x16x32_bf16 v[20:23], v[144:147], v[202:205], 0
	v_mfma_f32_16x16x32_bf16 v[16:19], v[152:155], v[202:205], 0
	v_mfma_f32_16x16x32_bf16 v[60:63], v[148:151], v[182:185], v[60:63]
	v_mfma_f32_16x16x32_bf16 v[56:59], v[156:159], v[182:185], v[56:59]
	v_mfma_f32_16x16x32_bf16 v[52:55], v[148:151], v[190:193], v[52:55]
	v_mfma_f32_16x16x32_bf16 v[48:51], v[156:159], v[190:193], v[48:51]
	v_mfma_f32_16x16x32_bf16 v[36:39], v[148:151], v[198:201], v[36:39]
	v_mfma_f32_16x16x32_bf16 v[32:35], v[156:159], v[198:201], v[32:35]
	v_mfma_f32_16x16x32_bf16 v[20:23], v[148:151], v[206:209], v[20:23]
	v_mfma_f32_16x16x32_bf16 v[16:19], v[156:159], v[206:209], v[16:19]
	s_setprio 0
	s_setprio 1
	v_mfma_f32_16x16x32_bf16 v[44:47], v[160:163], v[178:181], 0
	v_mfma_f32_16x16x32_bf16 v[40:43], v[168:171], v[178:181], 0
	v_mfma_f32_16x16x32_bf16 v[28:31], v[160:163], v[186:189], 0
	v_mfma_f32_16x16x32_bf16 v[24:27], v[168:171], v[186:189], 0
	v_mfma_f32_16x16x32_bf16 v[12:15], v[160:163], v[194:197], 0
	v_mfma_f32_16x16x32_bf16 v[8:11], v[168:171], v[194:197], 0
	v_mfma_f32_16x16x32_bf16 v[4:7], v[160:163], v[202:205], 0
	v_mfma_f32_16x16x32_bf16 v[0:3], v[168:171], v[202:205], 0
	v_mfma_f32_16x16x32_bf16 v[44:47], v[164:167], v[182:185], v[44:47]
	v_mfma_f32_16x16x32_bf16 v[40:43], v[172:175], v[182:185], v[40:43]
	v_mfma_f32_16x16x32_bf16 v[28:31], v[164:167], v[190:193], v[28:31]
	v_mfma_f32_16x16x32_bf16 v[24:27], v[172:175], v[190:193], v[24:27]
	v_mfma_f32_16x16x32_bf16 v[12:15], v[164:167], v[198:201], v[12:15]
	v_mfma_f32_16x16x32_bf16 v[8:11], v[172:175], v[198:201], v[8:11]
	v_mfma_f32_16x16x32_bf16 v[4:7], v[164:167], v[206:209], v[4:7]
	v_mfma_f32_16x16x32_bf16 v[0:3], v[172:175], v[206:209], v[0:3]
	s_setprio 0
	s_barrier
	s_add_i32 s38, 0, 0x18000
	s_add_i32 s39, 0, 0x1c000
	v_add_u32_e32 v156, s38, v142
	v_add_u32_e32 v172, s39, v142
	ds_read_b128 v[144:147], v156
	ds_read_b128 v[148:151], v156 offset:1024
	ds_read_b128 v[152:155], v156 offset:2048
	ds_read_b128 v[156:159], v156 offset:3072
	ds_read_b128 v[160:163], v172
	ds_read_b128 v[164:167], v172 offset:1024
	ds_read_b128 v[168:171], v172 offset:2048
	ds_read_b128 v[172:175], v172 offset:3072
	s_add_u32 s22, s22, 0x100000
	s_addc_u32 s23, s23, 0
	s_mov_b32 m0, s9
	ds_read_b128 v[178:181], v143 offset:32768
	ds_read_b128 v[182:185], v143 offset:33792
	ds_read_b128 v[186:189], v143 offset:34816
	ds_read_b128 v[190:193], v143 offset:35840
	ds_read_b128 v[194:197], v143 offset:36864
	ds_read_b128 v[198:201], v143 offset:37888
	ds_read_b128 v[202:205], v143 offset:38912
	ds_read_b128 v[206:209], v143 offset:39936
	global_load_lds_dwordx4 v134, s[22:23]
	s_mov_b32 m0, s28
	s_nop 0
	global_load_lds_dwordx4 v130, s[22:23]
	s_waitcnt vmcnt(8)
	s_waitcnt lgkmcnt(0)
	s_barrier
	s_setprio 1
	s_waitcnt lgkmcnt(0)
	v_mfma_f32_16x16x32_bf16 v[124:127], v[144:147], v[178:181], v[124:127]
	v_mfma_f32_16x16x32_bf16 v[120:123], v[152:155], v[178:181], v[120:123]
	v_mfma_f32_16x16x32_bf16 v[116:119], v[144:147], v[186:189], v[116:119]
	v_mfma_f32_16x16x32_bf16 v[112:115], v[152:155], v[186:189], v[112:115]
	v_mfma_f32_16x16x32_bf16 v[100:103], v[144:147], v[194:197], v[100:103]
	v_mfma_f32_16x16x32_bf16 v[96:99], v[152:155], v[194:197], v[96:99]
	v_mfma_f32_16x16x32_bf16 v[84:87], v[144:147], v[202:205], v[84:87]
	v_mfma_f32_16x16x32_bf16 v[80:83], v[152:155], v[202:205], v[80:83]
	v_mfma_f32_16x16x32_bf16 v[124:127], v[148:151], v[182:185], v[124:127]
	v_mfma_f32_16x16x32_bf16 v[120:123], v[156:159], v[182:185], v[120:123]
	v_mfma_f32_16x16x32_bf16 v[116:119], v[148:151], v[190:193], v[116:119]
	v_mfma_f32_16x16x32_bf16 v[112:115], v[156:159], v[190:193], v[112:115]
	v_mfma_f32_16x16x32_bf16 v[100:103], v[148:151], v[198:201], v[100:103]
	v_mfma_f32_16x16x32_bf16 v[96:99], v[156:159], v[198:201], v[96:99]
	v_mfma_f32_16x16x32_bf16 v[84:87], v[148:151], v[206:209], v[84:87]
	v_mfma_f32_16x16x32_bf16 v[80:83], v[156:159], v[206:209], v[80:83]
	s_setprio 0
	s_setprio 1
	v_mfma_f32_16x16x32_bf16 v[108:111], v[160:163], v[178:181], v[108:111]
	v_mfma_f32_16x16x32_bf16 v[104:107], v[168:171], v[178:181], v[104:107]
	v_mfma_f32_16x16x32_bf16 v[92:95], v[160:163], v[186:189], v[92:95]
	v_mfma_f32_16x16x32_bf16 v[88:91], v[168:171], v[186:189], v[88:91]
	v_mfma_f32_16x16x32_bf16 v[76:79], v[160:163], v[194:197], v[76:79]
	v_mfma_f32_16x16x32_bf16 v[72:75], v[168:171], v[194:197], v[72:75]
	v_mfma_f32_16x16x32_bf16 v[68:71], v[160:163], v[202:205], v[68:71]
	v_mfma_f32_16x16x32_bf16 v[64:67], v[168:171], v[202:205], v[64:67]
	v_mfma_f32_16x16x32_bf16 v[108:111], v[164:167], v[182:185], v[108:111]
	v_mfma_f32_16x16x32_bf16 v[104:107], v[172:175], v[182:185], v[104:107]
	v_mfma_f32_16x16x32_bf16 v[92:95], v[164:167], v[190:193], v[92:95]
	v_mfma_f32_16x16x32_bf16 v[88:91], v[172:175], v[190:193], v[88:91]
	v_mfma_f32_16x16x32_bf16 v[76:79], v[164:167], v[198:201], v[76:79]
	v_mfma_f32_16x16x32_bf16 v[72:75], v[172:175], v[198:201], v[72:75]
	v_mfma_f32_16x16x32_bf16 v[68:71], v[164:167], v[206:209], v[68:71]
	v_mfma_f32_16x16x32_bf16 v[64:67], v[172:175], v[206:209], v[64:67]
	s_setprio 0
	s_barrier
	s_add_i32 s22, s38, s26
	s_mov_b32 m0, s22
	ds_read_b128 v[178:181], v143 offset:49152
	ds_read_b128 v[182:185], v143 offset:50176
	ds_read_b128 v[186:189], v143 offset:51200
	ds_read_b128 v[190:193], v143 offset:52224
	ds_read_b128 v[194:197], v143 offset:53248
	ds_read_b128 v[198:201], v143 offset:54272
	ds_read_b128 v[202:205], v143 offset:55296
	ds_read_b128 v[206:209], v143 offset:56320
	s_add_u32 s98, s18, 0x80
	s_addc_u32 s99, s19, 0
	global_load_lds_dwordx4 v132, s[98:99]
	s_add_i32 m0, s22, 0x2000
	s_add_u32 s18, s18, 0x800080
	s_addc_u32 s19, s19, 0
	s_add_i32 s22, s39, s26
	s_add_u32 s98, s18, 0xff800000
	s_addc_u32 s99, s19, -1
	global_load_lds_dwordx4 v128, s[98:99]
	s_mov_b32 m0, s22
	s_nop 0
	global_load_lds_dwordx4 v132, s[18:19]
	s_add_i32 m0, s22, 0x2000
	s_nop 0
	global_load_lds_dwordx4 v128, s[18:19]
	s_mov_b32 m0, s29
	s_nop 0
	global_load_lds_dwordx4 v134, s[60:61]
	s_mov_b32 m0, s30
	s_nop 0
	global_load_lds_dwordx4 v130, s[60:61]
	s_waitcnt vmcnt(8)
	s_waitcnt lgkmcnt(0)
	s_barrier
	s_setprio 1
	s_waitcnt lgkmcnt(0)
	v_mfma_f32_16x16x32_bf16 v[60:63], v[144:147], v[178:181], v[60:63]
	v_mfma_f32_16x16x32_bf16 v[56:59], v[152:155], v[178:181], v[56:59]
	v_mfma_f32_16x16x32_bf16 v[52:55], v[144:147], v[186:189], v[52:55]
	v_mfma_f32_16x16x32_bf16 v[48:51], v[152:155], v[186:189], v[48:51]
	v_mfma_f32_16x16x32_bf16 v[36:39], v[144:147], v[194:197], v[36:39]
	v_mfma_f32_16x16x32_bf16 v[32:35], v[152:155], v[194:197], v[32:35]
	v_mfma_f32_16x16x32_bf16 v[20:23], v[144:147], v[202:205], v[20:23]
	v_mfma_f32_16x16x32_bf16 v[16:19], v[152:155], v[202:205], v[16:19]
	v_mfma_f32_16x16x32_bf16 v[60:63], v[148:151], v[182:185], v[60:63]
	v_mfma_f32_16x16x32_bf16 v[56:59], v[156:159], v[182:185], v[56:59]
	v_mfma_f32_16x16x32_bf16 v[52:55], v[148:151], v[190:193], v[52:55]
	v_mfma_f32_16x16x32_bf16 v[48:51], v[156:159], v[190:193], v[48:51]
	v_mfma_f32_16x16x32_bf16 v[36:39], v[148:151], v[198:201], v[36:39]
	v_mfma_f32_16x16x32_bf16 v[32:35], v[156:159], v[198:201], v[32:35]
	v_mfma_f32_16x16x32_bf16 v[20:23], v[148:151], v[206:209], v[20:23]
	v_mfma_f32_16x16x32_bf16 v[16:19], v[156:159], v[206:209], v[16:19]
	s_setprio 0
	s_setprio 1
	v_mfma_f32_16x16x32_bf16 v[44:47], v[160:163], v[178:181], v[44:47]
	v_mfma_f32_16x16x32_bf16 v[40:43], v[168:171], v[178:181], v[40:43]
	v_mfma_f32_16x16x32_bf16 v[28:31], v[160:163], v[186:189], v[28:31]
	v_mfma_f32_16x16x32_bf16 v[24:27], v[168:171], v[186:189], v[24:27]
	v_mfma_f32_16x16x32_bf16 v[12:15], v[160:163], v[194:197], v[12:15]
	v_mfma_f32_16x16x32_bf16 v[8:11], v[168:171], v[194:197], v[8:11]
	v_mfma_f32_16x16x32_bf16 v[4:7], v[160:163], v[202:205], v[4:7]
	v_mfma_f32_16x16x32_bf16 v[0:3], v[168:171], v[202:205], v[0:3]
	v_mfma_f32_16x16x32_bf16 v[44:47], v[164:167], v[182:185], v[44:47]
	v_mfma_f32_16x16x32_bf16 v[40:43], v[172:175], v[182:185], v[40:43]
	v_mfma_f32_16x16x32_bf16 v[28:31], v[164:167], v[190:193], v[28:31]
	v_mfma_f32_16x16x32_bf16 v[24:27], v[172:175], v[190:193], v[24:27]
	v_mfma_f32_16x16x32_bf16 v[12:15], v[164:167], v[198:201], v[12:15]
	v_mfma_f32_16x16x32_bf16 v[8:11], v[172:175], v[198:201], v[8:11]
	v_mfma_f32_16x16x32_bf16 v[4:7], v[164:167], v[206:209], v[4:7]
	v_mfma_f32_16x16x32_bf16 v[0:3], v[172:175], v[206:209], v[0:3]
	s_setprio 0
	s_barrier
	s_add_i32 s37, s37, 2
	s_add_u32 s16, s16, 0x100
	s_addc_u32 s17, s17, 0
	s_add_u32 s7, s7, 0x100
	s_addc_u32 s36, s36, 0
	s_cmp_gt_u32 s37, 61

.LBB0_829:
	s_mov_b32 s59, s58
	s_add_i32 s58, s58, 1
	s_cmp_lt_u32 s59, 2
	s_cselect_b64 s[10:11], -1, 0
	s_lshl_b32 s1, s58, 5
	s_add_i32 s1, s90, s1
	s_and_b64 s[12:13], s[10:11], exec
	s_mov_b32 s2, s56
	s_cselect_b32 s56, s1, s56
	s_mov_b32 s0, s54
	s_cselect_b32 s54, s94, s54
	s_ashr_i32 s57, s56, 31
	s_lshl_b64 s[12:13], s[56:57], 20
	s_add_u32 s1, s22, s12
	s_addc_u32 s3, s23, s13
	s_mov_b64 s[6:7], s[30:31]
	s_and_b64 s[12:13], s[10:11], exec
	s_cselect_b32 s31, s3, s7
	s_cselect_b32 s30, s1, s6
	s_ashr_i32 s55, s54, 31
	s_lshl_b64 s[12:13], s[54:55], 20
	s_add_u32 s1, s24, s12
	s_addc_u32 s3, s25, s13
	s_mov_b64 s[8:9], s[18:19]
	s_and_b64 s[10:11], s[10:11], exec
	s_cselect_b32 s19, s3, s9
	s_cselect_b32 s18, s1, s8
	s_add_u32 s6, s6, 0x80080
	s_addc_u32 s7, s7, 0
	s_add_u32 s1, s8, 0x100
	s_addc_u32 s3, s9, 0
	s_mov_b32 s12, -2
	s_waitcnt lgkmcnt(0)
	s_add_u32 s8, s6, 0xfff80080
	s_addc_u32 s9, s7, -1
	s_add_i32 s13, 0, 0x10000
	s_cmp_eq_u32 s12, 28
	s_cselect_b32 s11, s31, s9
	s_cselect_b32 s10, s30, s8
	s_cselect_b32 s9, s19, s3
	s_cselect_b32 s8, s18, s1
	s_add_i32 s20, 0, 0x14000
	v_add_u32_e32 v124, s13, v209
	v_add_u32_e32 v156, s20, v209
	ds_read_b128 v[104:107], v124
	ds_read_b128 v[116:119], v124 offset:1024
	ds_read_b128 v[120:123], v124 offset:2048
	ds_read_b128 v[124:127], v124 offset:3072
	ds_read_b128 v[136:139], v156
	ds_read_b128 v[140:143], v156 offset:1024
	ds_read_b128 v[152:155], v156 offset:2048
	ds_read_b128 v[156:159], v156 offset:3072
	s_add_i32 m0, s28, 0xc000
	ds_read_b128 v[160:163], v228
	ds_read_b128 v[164:167], v228 offset:1024
	ds_read_b128 v[168:171], v228 offset:2048
	ds_read_b128 v[172:175], v228 offset:3072
	ds_read_b128 v[230:233], v228 offset:4096
	ds_read_b128 v[234:237], v228 offset:5120
	ds_read_b128 v[238:241], v228 offset:6144
	ds_read_b128 v[242:245], v228 offset:7168
	global_load_lds_dwordx4 v202, s[6:7]
	s_add_i32 m0, s28, 0xe000
	s_nop 0
	global_load_lds_dwordx4 v204, s[6:7]
	s_waitcnt vmcnt(8)
	s_waitcnt lgkmcnt(0)
	s_barrier
	s_setprio 1
	s_waitcnt lgkmcnt(0)
	v_mfma_f32_16x16x32_bf16 v[148:151], v[104:107], v[160:163], 0
	v_mfma_f32_16x16x32_bf16 v[144:147], v[120:123], v[160:163], 0
	v_mfma_f32_16x16x32_bf16 v[112:115], v[104:107], v[168:171], 0
	v_mfma_f32_16x16x32_bf16 v[108:111], v[120:123], v[168:171], 0
	v_mfma_f32_16x16x32_bf16 v[92:95], v[104:107], v[230:233], 0
	v_mfma_f32_16x16x32_bf16 v[88:91], v[120:123], v[230:233], 0
	v_mfma_f32_16x16x32_bf16 v[76:79], v[104:107], v[238:241], 0
	v_mfma_f32_16x16x32_bf16 v[72:75], v[120:123], v[238:241], 0
	v_mfma_f32_16x16x32_bf16 v[148:151], v[116:119], v[164:167], v[148:151]
	v_mfma_f32_16x16x32_bf16 v[144:147], v[124:127], v[164:167], v[144:147]
	v_mfma_f32_16x16x32_bf16 v[112:115], v[116:119], v[172:175], v[112:115]
	v_mfma_f32_16x16x32_bf16 v[108:111], v[124:127], v[172:175], v[108:111]
	v_mfma_f32_16x16x32_bf16 v[92:95], v[116:119], v[234:237], v[92:95]
	v_mfma_f32_16x16x32_bf16 v[88:91], v[124:127], v[234:237], v[88:91]
	v_mfma_f32_16x16x32_bf16 v[76:79], v[116:119], v[242:245], v[76:79]
	v_mfma_f32_16x16x32_bf16 v[72:75], v[124:127], v[242:245], v[72:75]
	s_setprio 0
	s_setprio 1
	v_mfma_f32_16x16x32_bf16 v[132:135], v[136:139], v[160:163], 0
	v_mfma_f32_16x16x32_bf16 v[128:131], v[152:155], v[160:163], 0
	v_mfma_f32_16x16x32_bf16 v[100:103], v[136:139], v[168:171], 0
	v_mfma_f32_16x16x32_bf16 v[96:99], v[152:155], v[168:171], 0
	v_mfma_f32_16x16x32_bf16 v[84:87], v[136:139], v[230:233], 0
	v_mfma_f32_16x16x32_bf16 v[80:83], v[152:155], v[230:233], 0
	v_mfma_f32_16x16x32_bf16 v[68:71], v[136:139], v[238:241], 0
	v_mfma_f32_16x16x32_bf16 v[64:67], v[152:155], v[238:241], 0
	v_mfma_f32_16x16x32_bf16 v[132:135], v[140:143], v[164:167], v[132:135]
	v_mfma_f32_16x16x32_bf16 v[128:131], v[156:159], v[164:167], v[128:131]
	v_mfma_f32_16x16x32_bf16 v[100:103], v[140:143], v[172:175], v[100:103]
	v_mfma_f32_16x16x32_bf16 v[96:99], v[156:159], v[172:175], v[96:99]
	v_mfma_f32_16x16x32_bf16 v[84:87], v[140:143], v[234:237], v[84:87]
	v_mfma_f32_16x16x32_bf16 v[80:83], v[156:159], v[234:237], v[80:83]
	v_mfma_f32_16x16x32_bf16 v[68:71], v[140:143], v[242:245], v[68:71]
	v_mfma_f32_16x16x32_bf16 v[64:67], v[156:159], v[242:245], v[64:67]
	s_setprio 0
	s_barrier
	s_add_i32 s13, s13, s27
	s_mov_b32 m0, s13
	ds_read_b128 v[160:163], v228 offset:16384
	ds_read_b128 v[164:167], v228 offset:17408
	ds_read_b128 v[168:171], v228 offset:18432
	ds_read_b128 v[172:175], v228 offset:19456
	ds_read_b128 v[230:233], v228 offset:20480
	ds_read_b128 v[234:237], v228 offset:21504
	ds_read_b128 v[238:241], v228 offset:22528
	ds_read_b128 v[242:245], v228 offset:23552
	global_load_lds_dwordx4 v176, s[8:9]
	s_add_i32 m0, s13, 0x2000
	s_add_u32 s14, s8, 0x80000
	s_addc_u32 s15, s9, 0
	s_add_i32 s13, s20, s27
	global_load_lds_dwordx4 v182, s[8:9]
	s_mov_b32 m0, s13
	s_nop 0
	global_load_lds_dwordx4 v176, s[14:15]
	s_add_i32 m0, s13, 0x2000
	s_nop 0
	global_load_lds_dwordx4 v182, s[14:15]
	s_add_u32 s50, s10, 0x80
	s_addc_u32 s51, s11, 0
	s_mov_b32 m0, s28
	s_nop 0
	global_load_lds_dwordx4 v178, s[10:11]
	s_mov_b32 m0, s29
	s_nop 0
	global_load_lds_dwordx4 v180, s[10:11]
	s_waitcnt vmcnt(8)
	s_waitcnt lgkmcnt(0)
	s_barrier
	s_setprio 1
	s_waitcnt lgkmcnt(0)
	v_mfma_f32_16x16x32_bf16 v[60:63], v[104:107], v[160:163], 0
	v_mfma_f32_16x16x32_bf16 v[56:59], v[120:123], v[160:163], 0
	v_mfma_f32_16x16x32_bf16 v[44:47], v[104:107], v[168:171], 0
	v_mfma_f32_16x16x32_bf16 v[40:43], v[120:123], v[168:171], 0
	v_mfma_f32_16x16x32_bf16 v[28:31], v[104:107], v[230:233], 0
	v_mfma_f32_16x16x32_bf16 v[24:27], v[120:123], v[230:233], 0
	v_mfma_f32_16x16x32_bf16 v[12:15], v[104:107], v[238:241], 0
	v_mfma_f32_16x16x32_bf16 v[8:11], v[120:123], v[238:241], 0
	v_mfma_f32_16x16x32_bf16 v[60:63], v[116:119], v[164:167], v[60:63]
	v_mfma_f32_16x16x32_bf16 v[56:59], v[124:127], v[164:167], v[56:59]
	v_mfma_f32_16x16x32_bf16 v[44:47], v[116:119], v[172:175], v[44:47]
	v_mfma_f32_16x16x32_bf16 v[40:43], v[124:127], v[172:175], v[40:43]
	v_mfma_f32_16x16x32_bf16 v[28:31], v[116:119], v[234:237], v[28:31]
	v_mfma_f32_16x16x32_bf16 v[24:27], v[124:127], v[234:237], v[24:27]
	v_mfma_f32_16x16x32_bf16 v[12:15], v[116:119], v[242:245], v[12:15]
	v_mfma_f32_16x16x32_bf16 v[8:11], v[124:127], v[242:245], v[8:11]
	s_setprio 0
	s_setprio 1
	v_mfma_f32_16x16x32_bf16 v[52:55], v[136:139], v[160:163], 0
	v_mfma_f32_16x16x32_bf16 v[48:51], v[152:155], v[160:163], 0
	v_mfma_f32_16x16x32_bf16 v[36:39], v[136:139], v[168:171], 0
	v_mfma_f32_16x16x32_bf16 v[32:35], v[152:155], v[168:171], 0
	v_mfma_f32_16x16x32_bf16 v[20:23], v[136:139], v[230:233], 0
	v_mfma_f32_16x16x32_bf16 v[16:19], v[152:155], v[230:233], 0
	v_mfma_f32_16x16x32_bf16 v[4:7], v[136:139], v[238:241], 0
	v_mfma_f32_16x16x32_bf16 v[0:3], v[152:155], v[238:241], 0
	v_mfma_f32_16x16x32_bf16 v[52:55], v[140:143], v[164:167], v[52:55]
	v_mfma_f32_16x16x32_bf16 v[48:51], v[156:159], v[164:167], v[48:51]
	v_mfma_f32_16x16x32_bf16 v[36:39], v[140:143], v[172:175], v[36:39]
	v_mfma_f32_16x16x32_bf16 v[32:35], v[156:159], v[172:175], v[32:35]
	v_mfma_f32_16x16x32_bf16 v[20:23], v[140:143], v[234:237], v[20:23]
	v_mfma_f32_16x16x32_bf16 v[16:19], v[156:159], v[234:237], v[16:19]
	v_mfma_f32_16x16x32_bf16 v[4:7], v[140:143], v[242:245], v[4:7]
	v_mfma_f32_16x16x32_bf16 v[0:3], v[156:159], v[242:245], v[0:3]
	s_setprio 0
	s_barrier
	s_add_i32 s13, 0, 0x18000
	s_add_i32 s14, 0, 0x1c000
	v_add_u32_e32 v124, s13, v209
	v_add_u32_e32 v156, s14, v209
	ds_read_b128 v[104:107], v124
	ds_read_b128 v[116:119], v124 offset:1024
	ds_read_b128 v[120:123], v124 offset:2048
	ds_read_b128 v[124:127], v124 offset:3072
	ds_read_b128 v[136:139], v156
	ds_read_b128 v[140:143], v156 offset:1024
	ds_read_b128 v[152:155], v156 offset:2048
	ds_read_b128 v[156:159], v156 offset:3072
	s_add_u32 s10, s10, 0x80000
	s_addc_u32 s11, s11, 0
	s_mov_b32 m0, s38
	ds_read_b128 v[160:163], v228 offset:32768
	ds_read_b128 v[164:167], v228 offset:33792
	ds_read_b128 v[168:171], v228 offset:34816
	ds_read_b128 v[172:175], v228 offset:35840
	ds_read_b128 v[230:233], v228 offset:36864
	ds_read_b128 v[234:237], v228 offset:37888
	ds_read_b128 v[238:241], v228 offset:38912
	ds_read_b128 v[242:245], v228 offset:39936
	global_load_lds_dwordx4 v178, s[10:11]
	s_mov_b32 m0, s39
	s_nop 0
	global_load_lds_dwordx4 v180, s[10:11]
	s_waitcnt vmcnt(8)
	s_waitcnt lgkmcnt(0)
	s_barrier
	s_setprio 1
	s_waitcnt lgkmcnt(0)
	v_mfma_f32_16x16x32_bf16 v[148:151], v[104:107], v[160:163], v[148:151]
	v_mfma_f32_16x16x32_bf16 v[144:147], v[120:123], v[160:163], v[144:147]
	v_mfma_f32_16x16x32_bf16 v[112:115], v[104:107], v[168:171], v[112:115]
	v_mfma_f32_16x16x32_bf16 v[108:111], v[120:123], v[168:171], v[108:111]
	v_mfma_f32_16x16x32_bf16 v[92:95], v[104:107], v[230:233], v[92:95]
	v_mfma_f32_16x16x32_bf16 v[88:91], v[120:123], v[230:233], v[88:91]
	v_mfma_f32_16x16x32_bf16 v[76:79], v[104:107], v[238:241], v[76:79]
	v_mfma_f32_16x16x32_bf16 v[72:75], v[120:123], v[238:241], v[72:75]
	v_mfma_f32_16x16x32_bf16 v[148:151], v[116:119], v[164:167], v[148:151]
	v_mfma_f32_16x16x32_bf16 v[144:147], v[124:127], v[164:167], v[144:147]
	v_mfma_f32_16x16x32_bf16 v[112:115], v[116:119], v[172:175], v[112:115]
	v_mfma_f32_16x16x32_bf16 v[108:111], v[124:127], v[172:175], v[108:111]
	v_mfma_f32_16x16x32_bf16 v[92:95], v[116:119], v[234:237], v[92:95]
	v_mfma_f32_16x16x32_bf16 v[88:91], v[124:127], v[234:237], v[88:91]
	v_mfma_f32_16x16x32_bf16 v[76:79], v[116:119], v[242:245], v[76:79]
	v_mfma_f32_16x16x32_bf16 v[72:75], v[124:127], v[242:245], v[72:75]
	s_setprio 0
	s_setprio 1
	v_mfma_f32_16x16x32_bf16 v[132:135], v[136:139], v[160:163], v[132:135]
	v_mfma_f32_16x16x32_bf16 v[128:131], v[152:155], v[160:163], v[128:131]
	v_mfma_f32_16x16x32_bf16 v[100:103], v[136:139], v[168:171], v[100:103]
	v_mfma_f32_16x16x32_bf16 v[96:99], v[152:155], v[168:171], v[96:99]
	v_mfma_f32_16x16x32_bf16 v[84:87], v[136:139], v[230:233], v[84:87]
	v_mfma_f32_16x16x32_bf16 v[80:83], v[152:155], v[230:233], v[80:83]
	v_mfma_f32_16x16x32_bf16 v[68:71], v[136:139], v[238:241], v[68:71]
	v_mfma_f32_16x16x32_bf16 v[64:67], v[152:155], v[238:241], v[64:67]
	v_mfma_f32_16x16x32_bf16 v[132:135], v[140:143], v[164:167], v[132:135]
	v_mfma_f32_16x16x32_bf16 v[128:131], v[156:159], v[164:167], v[128:131]
	v_mfma_f32_16x16x32_bf16 v[100:103], v[140:143], v[172:175], v[100:103]
	v_mfma_f32_16x16x32_bf16 v[96:99], v[156:159], v[172:175], v[96:99]
	v_mfma_f32_16x16x32_bf16 v[84:87], v[140:143], v[234:237], v[84:87]
	v_mfma_f32_16x16x32_bf16 v[80:83], v[156:159], v[234:237], v[80:83]
	v_mfma_f32_16x16x32_bf16 v[68:71], v[140:143], v[242:245], v[68:71]
	v_mfma_f32_16x16x32_bf16 v[64:67], v[156:159], v[242:245], v[64:67]
	s_setprio 0
	s_barrier
	s_add_i32 s10, s13, s27
	s_mov_b32 m0, s10
	ds_read_b128 v[160:163], v228 offset:49152
	ds_read_b128 v[164:167], v228 offset:50176
	ds_read_b128 v[168:171], v228 offset:51200
	ds_read_b128 v[172:175], v228 offset:52224
	ds_read_b128 v[230:233], v228 offset:53248
	ds_read_b128 v[234:237], v228 offset:54272
	ds_read_b128 v[238:241], v228 offset:55296
	ds_read_b128 v[242:245], v228 offset:56320
	s_add_u32 s98, s8, 0x80
	s_addc_u32 s99, s9, 0
	global_load_lds_dwordx4 v176, s[98:99]
	s_add_i32 m0, s10, 0x2000
	s_add_u32 s8, s8, 0x80080
	s_addc_u32 s9, s9, 0
	s_add_i32 s10, s14, s27
	s_add_u32 s98, s8, 0xfff80000
	s_addc_u32 s99, s9, -1
	global_load_lds_dwordx4 v182, s[98:99]
	s_mov_b32 m0, s10
	s_nop 0
	global_load_lds_dwordx4 v176, s[8:9]
	s_add_i32 m0, s10, 0x2000
	s_nop 0
	global_load_lds_dwordx4 v182, s[8:9]
	s_mov_b32 m0, s44
	s_nop 0
	global_load_lds_dwordx4 v178, s[50:51]
	s_mov_b32 m0, s45
	s_nop 0
	global_load_lds_dwordx4 v180, s[50:51]
	s_waitcnt vmcnt(8)
	s_waitcnt lgkmcnt(0)
	s_barrier
	s_setprio 1
	s_waitcnt lgkmcnt(0)
	v_mfma_f32_16x16x32_bf16 v[60:63], v[104:107], v[160:163], v[60:63]
	v_mfma_f32_16x16x32_bf16 v[56:59], v[120:123], v[160:163], v[56:59]
	v_mfma_f32_16x16x32_bf16 v[44:47], v[104:107], v[168:171], v[44:47]
	v_mfma_f32_16x16x32_bf16 v[40:43], v[120:123], v[168:171], v[40:43]
	v_mfma_f32_16x16x32_bf16 v[28:31], v[104:107], v[230:233], v[28:31]
	v_mfma_f32_16x16x32_bf16 v[24:27], v[120:123], v[230:233], v[24:27]
	v_mfma_f32_16x16x32_bf16 v[12:15], v[104:107], v[238:241], v[12:15]
	v_mfma_f32_16x16x32_bf16 v[8:11], v[120:123], v[238:241], v[8:11]
	v_mfma_f32_16x16x32_bf16 v[60:63], v[116:119], v[164:167], v[60:63]
	v_mfma_f32_16x16x32_bf16 v[56:59], v[124:127], v[164:167], v[56:59]
	v_mfma_f32_16x16x32_bf16 v[44:47], v[116:119], v[172:175], v[44:47]
	v_mfma_f32_16x16x32_bf16 v[40:43], v[124:127], v[172:175], v[40:43]
	v_mfma_f32_16x16x32_bf16 v[28:31], v[116:119], v[234:237], v[28:31]
	v_mfma_f32_16x16x32_bf16 v[24:27], v[124:127], v[234:237], v[24:27]
	v_mfma_f32_16x16x32_bf16 v[12:15], v[116:119], v[242:245], v[12:15]
	v_mfma_f32_16x16x32_bf16 v[8:11], v[124:127], v[242:245], v[8:11]
	s_setprio 0
	s_setprio 1
	v_mfma_f32_16x16x32_bf16 v[52:55], v[136:139], v[160:163], v[52:55]
	v_mfma_f32_16x16x32_bf16 v[48:51], v[152:155], v[160:163], v[48:51]
	v_mfma_f32_16x16x32_bf16 v[36:39], v[136:139], v[168:171], v[36:39]
	v_mfma_f32_16x16x32_bf16 v[32:35], v[152:155], v[168:171], v[32:35]
	v_mfma_f32_16x16x32_bf16 v[20:23], v[136:139], v[230:233], v[20:23]
	v_mfma_f32_16x16x32_bf16 v[16:19], v[152:155], v[230:233], v[16:19]
	v_mfma_f32_16x16x32_bf16 v[4:7], v[136:139], v[238:241], v[4:7]
	v_mfma_f32_16x16x32_bf16 v[0:3], v[152:155], v[238:241], v[0:3]
	v_mfma_f32_16x16x32_bf16 v[52:55], v[140:143], v[164:167], v[52:55]
	v_mfma_f32_16x16x32_bf16 v[48:51], v[156:159], v[164:167], v[48:51]
	v_mfma_f32_16x16x32_bf16 v[36:39], v[140:143], v[172:175], v[36:39]
	v_mfma_f32_16x16x32_bf16 v[32:35], v[156:159], v[172:175], v[32:35]
	v_mfma_f32_16x16x32_bf16 v[20:23], v[140:143], v[234:237], v[20:23]
	v_mfma_f32_16x16x32_bf16 v[16:19], v[156:159], v[234:237], v[16:19]
	v_mfma_f32_16x16x32_bf16 v[4:7], v[140:143], v[242:245], v[4:7]
	v_mfma_f32_16x16x32_bf16 v[0:3], v[156:159], v[242:245], v[0:3]
	s_setprio 0
	s_barrier
	s_add_i32 s12, s12, 2
	s_add_u32 s6, s6, 0x100
	s_addc_u32 s7, s7, 0
	s_add_u32 s1, s1, 0x100
	s_addc_u32 s3, s3, 0
	s_cmp_gt_u32 s12, 29

.LBB0_965:
	s_ashr_i32 s17, s16, 31
	s_lshl_b64 s[22:23], s[16:17], 20
	s_add_u32 s22, s2, s22
	s_addc_u32 s23, s3, s23
	s_and_b64 s[28:29], s[12:13], exec
	s_cselect_b32 s17, s23, s5
	s_cselect_b32 s25, s22, s4
	s_cmp_eq_u32 s50, 0
	s_cselect_b32 s34, s21, s33
	s_cselect_b32 s35, s20, s27
	s_ashr_i32 s15, s14, 31
	s_lshl_b64 s[28:29], s[14:15], 20
	s_add_u32 s28, s35, s28
	s_addc_u32 s29, s34, s29
	s_and_b64 s[34:35], s[12:13], exec
	s_cselect_b32 s15, s29, s31
	s_cselect_b32 s36, s28, s30
	s_add_u32 s4, s4, 0x80080
	s_addc_u32 s5, s5, 0
	s_add_u32 s37, s30, 0x100
	s_addc_u32 s51, s31, 0
	s_mov_b32 s52, -2
	s_cmp_lg_u32 s11, 0
	s_cbranch_scc1 .Lf1g_rss_skip
	s_lshl_b32 s60, s24, 10
	s_add_u32 s60, s45, s60
	s_addc_u32 s61, s46, 0
	v_lshl_add_u64 v[240:241], v[136:137], 2, s[60:61]
	global_load_dword v232, v[240:241], off
	global_load_dword v233, v[240:241], off offset:64
	global_load_dword v234, v[240:241], off offset:128
	global_load_dword v235, v[240:241], off offset:192
	global_load_dword v236, v[240:241], off offset:512
	global_load_dword v237, v[240:241], off offset:576
	global_load_dword v238, v[240:241], off offset:640
	global_load_dword v239, v[240:241], off offset:704
.Lf1g_rss_skip:
	s_add_u32 s30, s4, 0xfff80080
	s_addc_u32 s31, s5, -1
	s_add_i32 s53, 0, 0x10000
	s_cmp_eq_u32 s52, 28
	s_cselect_b32 s35, s17, s31
	s_cselect_b32 s34, s25, s30
	v_add_u32_e32 v142, s53, v143
	s_cselect_b32 s31, s15, s51
	s_cselect_b32 s30, s36, s37
	s_add_i32 s56, 0, 0x14000
	ds_read_b128 v[148:151], v142
	ds_read_b128 v[152:155], v142 offset:1024
	ds_read_b128 v[156:159], v142 offset:2048
	ds_read_b128 v[160:163], v142 offset:3072
	v_add_u32_e32 v142, s56, v143
	ds_read_b128 v[164:167], v142
	ds_read_b128 v[168:171], v142 offset:1024
	ds_read_b128 v[172:175], v142 offset:2048
	ds_read_b128 v[178:181], v142 offset:3072
	s_add_i32 m0, s19, 0xc000
	ds_read_b128 v[182:185], v147
	ds_read_b128 v[186:189], v147 offset:1024
	ds_read_b128 v[190:193], v147 offset:2048
	ds_read_b128 v[194:197], v147 offset:3072
	ds_read_b128 v[198:201], v147 offset:4096
	ds_read_b128 v[202:205], v147 offset:5120
	ds_read_b128 v[206:209], v147 offset:6144
	ds_read_b128 v[220:223], v147 offset:7168
	global_load_lds_dwordx4 v138, s[4:5]
	s_add_i32 m0, s19, 0xe000
	s_nop 0
	global_load_lds_dwordx4 v140, s[4:5]
	s_waitcnt vmcnt(8)
	s_waitcnt lgkmcnt(0)
	s_barrier
	s_setprio 1
	s_waitcnt lgkmcnt(0)
	v_mfma_f32_16x16x32_bf16 v[124:127], v[148:151], v[182:185], 0
	v_mfma_f32_16x16x32_bf16 v[120:123], v[156:159], v[182:185], 0
	v_mfma_f32_16x16x32_bf16 v[108:111], v[148:151], v[190:193], 0
	v_mfma_f32_16x16x32_bf16 v[104:107], v[156:159], v[190:193], 0
	v_mfma_f32_16x16x32_bf16 v[92:95], v[148:151], v[198:201], 0
	v_mfma_f32_16x16x32_bf16 v[88:91], v[156:159], v[198:201], 0
	v_mfma_f32_16x16x32_bf16 v[76:79], v[148:151], v[206:209], 0
	v_mfma_f32_16x16x32_bf16 v[72:75], v[156:159], v[206:209], 0
	v_mfma_f32_16x16x32_bf16 v[124:127], v[152:155], v[186:189], v[124:127]
	v_mfma_f32_16x16x32_bf16 v[120:123], v[160:163], v[186:189], v[120:123]
	v_mfma_f32_16x16x32_bf16 v[108:111], v[152:155], v[194:197], v[108:111]
	v_mfma_f32_16x16x32_bf16 v[104:107], v[160:163], v[194:197], v[104:107]
	v_mfma_f32_16x16x32_bf16 v[92:95], v[152:155], v[202:205], v[92:95]
	v_mfma_f32_16x16x32_bf16 v[88:91], v[160:163], v[202:205], v[88:91]
	v_mfma_f32_16x16x32_bf16 v[76:79], v[152:155], v[220:223], v[76:79]
	v_mfma_f32_16x16x32_bf16 v[72:75], v[160:163], v[220:223], v[72:75]
	s_setprio 0
	s_setprio 1
	v_mfma_f32_16x16x32_bf16 v[116:119], v[164:167], v[182:185], 0
	v_mfma_f32_16x16x32_bf16 v[112:115], v[172:175], v[182:185], 0
	v_mfma_f32_16x16x32_bf16 v[100:103], v[164:167], v[190:193], 0
	v_mfma_f32_16x16x32_bf16 v[96:99], v[172:175], v[190:193], 0
	v_mfma_f32_16x16x32_bf16 v[84:87], v[164:167], v[198:201], 0
	v_mfma_f32_16x16x32_bf16 v[80:83], v[172:175], v[198:201], 0
	v_mfma_f32_16x16x32_bf16 v[68:71], v[164:167], v[206:209], 0
	v_mfma_f32_16x16x32_bf16 v[64:67], v[172:175], v[206:209], 0
	v_mfma_f32_16x16x32_bf16 v[116:119], v[168:171], v[186:189], v[116:119]
	v_mfma_f32_16x16x32_bf16 v[112:115], v[178:181], v[186:189], v[112:115]
	v_mfma_f32_16x16x32_bf16 v[100:103], v[168:171], v[194:197], v[100:103]
	v_mfma_f32_16x16x32_bf16 v[96:99], v[178:181], v[194:197], v[96:99]
	v_mfma_f32_16x16x32_bf16 v[84:87], v[168:171], v[202:205], v[84:87]
	v_mfma_f32_16x16x32_bf16 v[80:83], v[178:181], v[202:205], v[80:83]
	v_mfma_f32_16x16x32_bf16 v[68:71], v[168:171], v[220:223], v[68:71]
	v_mfma_f32_16x16x32_bf16 v[64:67], v[178:181], v[220:223], v[64:67]
	s_setprio 0
	s_barrier
	s_add_i32 s53, s53, s26
	s_mov_b32 m0, s53
	ds_read_b128 v[182:185], v147 offset:16384
	ds_read_b128 v[186:189], v147 offset:17408
	ds_read_b128 v[190:193], v147 offset:18432
	ds_read_b128 v[194:197], v147 offset:19456
	ds_read_b128 v[198:201], v147 offset:20480
	ds_read_b128 v[202:205], v147 offset:21504
	ds_read_b128 v[206:209], v147 offset:22528
	ds_read_b128 v[220:223], v147 offset:23552
	global_load_lds_dwordx4 v130, s[30:31]
	s_add_i32 m0, s53, 0x2000
	s_add_u32 s54, s30, 0x80000
	s_addc_u32 s55, s31, 0
	s_add_i32 s53, s56, s26
	global_load_lds_dwordx4 v134, s[30:31]
	s_mov_b32 m0, s53
	s_nop 0
	global_load_lds_dwordx4 v130, s[54:55]
	s_add_i32 m0, s53, 0x2000
	s_nop 0
	global_load_lds_dwordx4 v134, s[54:55]
	s_add_u32 s60, s34, 0x80
	s_addc_u32 s61, s35, 0
	s_mov_b32 m0, s19
	s_nop 0
	global_load_lds_dwordx4 v128, s[34:35]
	s_mov_b32 m0, s38
	s_nop 0
	global_load_lds_dwordx4 v132, s[34:35]
	s_waitcnt vmcnt(8)
	s_waitcnt lgkmcnt(0)
	s_barrier
	s_setprio 1
	s_waitcnt lgkmcnt(0)
	v_mfma_f32_16x16x32_bf16 v[60:63], v[148:151], v[182:185], 0
	v_mfma_f32_16x16x32_bf16 v[56:59], v[156:159], v[182:185], 0
	v_mfma_f32_16x16x32_bf16 v[44:47], v[148:151], v[190:193], 0
	v_mfma_f32_16x16x32_bf16 v[40:43], v[156:159], v[190:193], 0
	v_mfma_f32_16x16x32_bf16 v[28:31], v[148:151], v[198:201], 0
	v_mfma_f32_16x16x32_bf16 v[24:27], v[156:159], v[198:201], 0
	v_mfma_f32_16x16x32_bf16 v[12:15], v[148:151], v[206:209], 0
	v_mfma_f32_16x16x32_bf16 v[8:11], v[156:159], v[206:209], 0
	v_mfma_f32_16x16x32_bf16 v[60:63], v[152:155], v[186:189], v[60:63]
	v_mfma_f32_16x16x32_bf16 v[56:59], v[160:163], v[186:189], v[56:59]
	v_mfma_f32_16x16x32_bf16 v[44:47], v[152:155], v[194:197], v[44:47]
	v_mfma_f32_16x16x32_bf16 v[40:43], v[160:163], v[194:197], v[40:43]
	v_mfma_f32_16x16x32_bf16 v[28:31], v[152:155], v[202:205], v[28:31]
	v_mfma_f32_16x16x32_bf16 v[24:27], v[160:163], v[202:205], v[24:27]
	v_mfma_f32_16x16x32_bf16 v[12:15], v[152:155], v[220:223], v[12:15]
	v_mfma_f32_16x16x32_bf16 v[8:11], v[160:163], v[220:223], v[8:11]
	s_setprio 0
	s_setprio 1
	v_mfma_f32_16x16x32_bf16 v[52:55], v[164:167], v[182:185], 0
	v_mfma_f32_16x16x32_bf16 v[48:51], v[172:175], v[182:185], 0
	v_mfma_f32_16x16x32_bf16 v[36:39], v[164:167], v[190:193], 0
	v_mfma_f32_16x16x32_bf16 v[32:35], v[172:175], v[190:193], 0
	v_mfma_f32_16x16x32_bf16 v[20:23], v[164:167], v[198:201], 0
	v_mfma_f32_16x16x32_bf16 v[16:19], v[172:175], v[198:201], 0
	v_mfma_f32_16x16x32_bf16 v[4:7], v[164:167], v[206:209], 0
	v_mfma_f32_16x16x32_bf16 v[0:3], v[172:175], v[206:209], 0
	v_mfma_f32_16x16x32_bf16 v[52:55], v[168:171], v[186:189], v[52:55]
	v_mfma_f32_16x16x32_bf16 v[48:51], v[178:181], v[186:189], v[48:51]
	v_mfma_f32_16x16x32_bf16 v[36:39], v[168:171], v[194:197], v[36:39]
	v_mfma_f32_16x16x32_bf16 v[32:35], v[178:181], v[194:197], v[32:35]
	v_mfma_f32_16x16x32_bf16 v[20:23], v[168:171], v[202:205], v[20:23]
	v_mfma_f32_16x16x32_bf16 v[16:19], v[178:181], v[202:205], v[16:19]
	v_mfma_f32_16x16x32_bf16 v[4:7], v[168:171], v[220:223], v[4:7]
	v_mfma_f32_16x16x32_bf16 v[0:3], v[178:181], v[220:223], v[0:3]
	s_setprio 0
	s_barrier
	s_add_i32 s53, 0, 0x18000
	v_add_u32_e32 v142, s53, v143
	s_add_i32 s54, 0, 0x1c000
	ds_read_b128 v[148:151], v142
	ds_read_b128 v[152:155], v142 offset:1024
	ds_read_b128 v[156:159], v142 offset:2048
	ds_read_b128 v[160:163], v142 offset:3072
	v_add_u32_e32 v142, s54, v143
	ds_read_b128 v[164:167], v142
	ds_read_b128 v[168:171], v142 offset:1024
	ds_read_b128 v[172:175], v142 offset:2048
	ds_read_b128 v[178:181], v142 offset:3072
	s_add_u32 s34, s34, 0x80000
	s_addc_u32 s35, s35, 0
	s_mov_b32 m0, s39
	ds_read_b128 v[182:185], v147 offset:32768
	ds_read_b128 v[186:189], v147 offset:33792
	ds_read_b128 v[190:193], v147 offset:34816
	ds_read_b128 v[194:197], v147 offset:35840
	ds_read_b128 v[198:201], v147 offset:36864
	ds_read_b128 v[202:205], v147 offset:37888
	ds_read_b128 v[206:209], v147 offset:38912
	ds_read_b128 v[220:223], v147 offset:39936
	global_load_lds_dwordx4 v128, s[34:35]
	s_mov_b32 m0, s40
	s_nop 0
	global_load_lds_dwordx4 v132, s[34:35]
	s_waitcnt vmcnt(8)
	s_waitcnt lgkmcnt(0)
	s_barrier
	s_setprio 1
	s_waitcnt lgkmcnt(0)
	v_mfma_f32_16x16x32_bf16 v[124:127], v[148:151], v[182:185], v[124:127]
	v_mfma_f32_16x16x32_bf16 v[120:123], v[156:159], v[182:185], v[120:123]
	v_mfma_f32_16x16x32_bf16 v[108:111], v[148:151], v[190:193], v[108:111]
	v_mfma_f32_16x16x32_bf16 v[104:107], v[156:159], v[190:193], v[104:107]
	v_mfma_f32_16x16x32_bf16 v[92:95], v[148:151], v[198:201], v[92:95]
	v_mfma_f32_16x16x32_bf16 v[88:91], v[156:159], v[198:201], v[88:91]
	v_mfma_f32_16x16x32_bf16 v[76:79], v[148:151], v[206:209], v[76:79]
	v_mfma_f32_16x16x32_bf16 v[72:75], v[156:159], v[206:209], v[72:75]
	v_mfma_f32_16x16x32_bf16 v[124:127], v[152:155], v[186:189], v[124:127]
	v_mfma_f32_16x16x32_bf16 v[120:123], v[160:163], v[186:189], v[120:123]
	v_mfma_f32_16x16x32_bf16 v[108:111], v[152:155], v[194:197], v[108:111]
	v_mfma_f32_16x16x32_bf16 v[104:107], v[160:163], v[194:197], v[104:107]
	v_mfma_f32_16x16x32_bf16 v[92:95], v[152:155], v[202:205], v[92:95]
	v_mfma_f32_16x16x32_bf16 v[88:91], v[160:163], v[202:205], v[88:91]
	v_mfma_f32_16x16x32_bf16 v[76:79], v[152:155], v[220:223], v[76:79]
	v_mfma_f32_16x16x32_bf16 v[72:75], v[160:163], v[220:223], v[72:75]
	s_setprio 0
	s_setprio 1
	v_mfma_f32_16x16x32_bf16 v[116:119], v[164:167], v[182:185], v[116:119]
	v_mfma_f32_16x16x32_bf16 v[112:115], v[172:175], v[182:185], v[112:115]
	v_mfma_f32_16x16x32_bf16 v[100:103], v[164:167], v[190:193], v[100:103]
	v_mfma_f32_16x16x32_bf16 v[96:99], v[172:175], v[190:193], v[96:99]
	v_mfma_f32_16x16x32_bf16 v[84:87], v[164:167], v[198:201], v[84:87]
	v_mfma_f32_16x16x32_bf16 v[80:83], v[172:175], v[198:201], v[80:83]
	v_mfma_f32_16x16x32_bf16 v[68:71], v[164:167], v[206:209], v[68:71]
	v_mfma_f32_16x16x32_bf16 v[64:67], v[172:175], v[206:209], v[64:67]
	v_mfma_f32_16x16x32_bf16 v[116:119], v[168:171], v[186:189], v[116:119]
	v_mfma_f32_16x16x32_bf16 v[112:115], v[178:181], v[186:189], v[112:115]
	v_mfma_f32_16x16x32_bf16 v[100:103], v[168:171], v[194:197], v[100:103]
	v_mfma_f32_16x16x32_bf16 v[96:99], v[178:181], v[194:197], v[96:99]
	v_mfma_f32_16x16x32_bf16 v[84:87], v[168:171], v[202:205], v[84:87]
	v_mfma_f32_16x16x32_bf16 v[80:83], v[178:181], v[202:205], v[80:83]
	v_mfma_f32_16x16x32_bf16 v[68:71], v[168:171], v[220:223], v[68:71]
	v_mfma_f32_16x16x32_bf16 v[64:67], v[178:181], v[220:223], v[64:67]
	s_setprio 0
	s_barrier
	s_add_i32 s34, s53, s26
	s_mov_b32 m0, s34
	ds_read_b128 v[182:185], v147 offset:49152
	ds_read_b128 v[186:189], v147 offset:50176
	ds_read_b128 v[190:193], v147 offset:51200
	ds_read_b128 v[194:197], v147 offset:52224
	ds_read_b128 v[198:201], v147 offset:53248
	ds_read_b128 v[202:205], v147 offset:54272
	ds_read_b128 v[206:209], v147 offset:55296
	ds_read_b128 v[220:223], v147 offset:56320
	s_add_u32 s98, s30, 0x80
	s_addc_u32 s99, s31, 0
	global_load_lds_dwordx4 v130, s[98:99]
	s_add_i32 m0, s34, 0x2000
	s_add_u32 s30, s30, 0x80080
	s_addc_u32 s31, s31, 0
	s_add_i32 s34, s54, s26
	s_add_u32 s98, s30, 0xfff80000
	s_addc_u32 s99, s31, -1
	global_load_lds_dwordx4 v134, s[98:99]
	s_mov_b32 m0, s34
	s_nop 0
	global_load_lds_dwordx4 v130, s[30:31]
	s_add_i32 m0, s34, 0x2000
	s_nop 0
	global_load_lds_dwordx4 v134, s[30:31]
	s_mov_b32 m0, s47
	s_nop 0
	global_load_lds_dwordx4 v128, s[60:61]
	s_mov_b32 m0, s48
	s_nop 0
	global_load_lds_dwordx4 v132, s[60:61]
	s_waitcnt vmcnt(8)
	s_waitcnt lgkmcnt(0)
	s_barrier
	s_setprio 1
	s_waitcnt lgkmcnt(0)
	v_mfma_f32_16x16x32_bf16 v[60:63], v[148:151], v[182:185], v[60:63]
	v_mfma_f32_16x16x32_bf16 v[56:59], v[156:159], v[182:185], v[56:59]
	v_mfma_f32_16x16x32_bf16 v[44:47], v[148:151], v[190:193], v[44:47]
	v_mfma_f32_16x16x32_bf16 v[40:43], v[156:159], v[190:193], v[40:43]
	v_mfma_f32_16x16x32_bf16 v[28:31], v[148:151], v[198:201], v[28:31]
	v_mfma_f32_16x16x32_bf16 v[24:27], v[156:159], v[198:201], v[24:27]
	v_mfma_f32_16x16x32_bf16 v[12:15], v[148:151], v[206:209], v[12:15]
	v_mfma_f32_16x16x32_bf16 v[8:11], v[156:159], v[206:209], v[8:11]
	v_mfma_f32_16x16x32_bf16 v[60:63], v[152:155], v[186:189], v[60:63]
	v_mfma_f32_16x16x32_bf16 v[56:59], v[160:163], v[186:189], v[56:59]
	v_mfma_f32_16x16x32_bf16 v[44:47], v[152:155], v[194:197], v[44:47]
	v_mfma_f32_16x16x32_bf16 v[40:43], v[160:163], v[194:197], v[40:43]
	v_mfma_f32_16x16x32_bf16 v[28:31], v[152:155], v[202:205], v[28:31]
	v_mfma_f32_16x16x32_bf16 v[24:27], v[160:163], v[202:205], v[24:27]
	v_mfma_f32_16x16x32_bf16 v[12:15], v[152:155], v[220:223], v[12:15]
	v_mfma_f32_16x16x32_bf16 v[8:11], v[160:163], v[220:223], v[8:11]
	s_setprio 0
	s_setprio 1
	v_mfma_f32_16x16x32_bf16 v[52:55], v[164:167], v[182:185], v[52:55]
	v_mfma_f32_16x16x32_bf16 v[48:51], v[172:175], v[182:185], v[48:51]
	v_mfma_f32_16x16x32_bf16 v[36:39], v[164:167], v[190:193], v[36:39]
	v_mfma_f32_16x16x32_bf16 v[32:35], v[172:175], v[190:193], v[32:35]
	v_mfma_f32_16x16x32_bf16 v[20:23], v[164:167], v[198:201], v[20:23]
	v_mfma_f32_16x16x32_bf16 v[16:19], v[172:175], v[198:201], v[16:19]
	v_mfma_f32_16x16x32_bf16 v[4:7], v[164:167], v[206:209], v[4:7]
	v_mfma_f32_16x16x32_bf16 v[0:3], v[172:175], v[206:209], v[0:3]
	v_mfma_f32_16x16x32_bf16 v[52:55], v[168:171], v[186:189], v[52:55]
	v_mfma_f32_16x16x32_bf16 v[48:51], v[178:181], v[186:189], v[48:51]
	v_mfma_f32_16x16x32_bf16 v[36:39], v[168:171], v[194:197], v[36:39]
	v_mfma_f32_16x16x32_bf16 v[32:35], v[178:181], v[194:197], v[32:35]
	v_mfma_f32_16x16x32_bf16 v[20:23], v[168:171], v[202:205], v[20:23]
	v_mfma_f32_16x16x32_bf16 v[16:19], v[178:181], v[202:205], v[16:19]
	v_mfma_f32_16x16x32_bf16 v[4:7], v[168:171], v[220:223], v[4:7]
	v_mfma_f32_16x16x32_bf16 v[0:3], v[178:181], v[220:223], v[0:3]
	s_setprio 0
	s_barrier
	s_add_i32 s52, s52, 2
	s_add_u32 s4, s4, 0x100
	s_addc_u32 s5, s5, 0
	s_add_u32 s37, s37, 0x100
	s_addc_u32 s51, s51, 0
	s_cmp_gt_u32 s52, 29

.LBB0_1056:
	s_ashr_i32 s53, s52, 31
	s_lshl_b64 s[14:15], s[52:53], 20
	s_add_u32 s70, s25, s14
	s_addc_u32 s71, s28, s15
	s_and_b64 s[14:15], s[68:69], exec
	s_cselect_b32 s20, s71, s1
	s_cselect_b32 s21, s70, s0
	s_ashr_i32 s55, s54, 31
	s_lshl_b64 s[14:15], s[54:55], 20
	s_add_u32 s56, s29, s14
	s_addc_u32 s57, s38, s15
	s_and_b64 s[14:15], s[68:69], exec
	s_cselect_b32 s22, s57, s13
	s_cselect_b32 s23, s56, s12
	s_add_u32 s0, s0, 0x80080
	s_addc_u32 s1, s1, 0
	s_add_u32 s26, s12, 0x100
	s_addc_u32 s27, s13, 0
	s_mov_b32 s33, -2
	s_add_u32 s12, s0, 0xfff80080
	s_addc_u32 s13, s1, -1
	s_add_i32 s50, 0, 0x10000
	s_cmp_eq_u32 s33, 28
	s_cselect_b32 s15, s20, s13
	s_cselect_b32 s14, s21, s12
	s_cselect_b32 s13, s22, s27
	s_cselect_b32 s12, s23, s26
	s_add_i32 s53, 0, 0x14000
	v_add_u32_e32 v100, s50, v222
	v_add_u32_e32 v120, s53, v222
	ds_read_b128 v[88:91], v100
	ds_read_b128 v[92:95], v100 offset:1024
	ds_read_b128 v[96:99], v100 offset:2048
	ds_read_b128 v[100:103], v100 offset:3072
	ds_read_b128 v[108:111], v120
	ds_read_b128 v[112:115], v120 offset:1024
	ds_read_b128 v[116:119], v120 offset:2048
	ds_read_b128 v[120:123], v120 offset:3072
	s_add_i32 m0, s42, 0xc000
	ds_read_b128 v[152:155], v224
	ds_read_b128 v[164:167], v224 offset:1024
	ds_read_b128 v[168:171], v224 offset:2048
	ds_read_b128 v[172:175], v224 offset:3072
	ds_read_b128 v[188:191], v224 offset:4096
	ds_read_b128 v[192:195], v224 offset:5120
	ds_read_b128 v[196:199], v224 offset:6144
	ds_read_b128 v[200:203], v224 offset:7168
	global_load_lds_dwordx4 v184, s[0:1]
	s_add_i32 m0, s42, 0xe000
	s_nop 0
	global_load_lds_dwordx4 v186, s[0:1]
	s_waitcnt vmcnt(8)
	s_waitcnt lgkmcnt(0)
	s_barrier
	s_setprio 1
	s_waitcnt lgkmcnt(0)
	v_mfma_f32_16x16x32_bf16 v[160:163], v[88:91], v[152:155], 0
	v_mfma_f32_16x16x32_bf16 v[156:159], v[96:99], v[152:155], 0
	v_mfma_f32_16x16x32_bf16 v[148:151], v[88:91], v[168:171], 0
	v_mfma_f32_16x16x32_bf16 v[144:147], v[96:99], v[168:171], 0
	v_mfma_f32_16x16x32_bf16 v[140:143], v[88:91], v[188:191], 0
	v_mfma_f32_16x16x32_bf16 v[136:139], v[96:99], v[188:191], 0
	v_mfma_f32_16x16x32_bf16 v[132:135], v[88:91], v[196:199], 0
	v_mfma_f32_16x16x32_bf16 v[128:131], v[96:99], v[196:199], 0
	v_mfma_f32_16x16x32_bf16 v[160:163], v[92:95], v[164:167], v[160:163]
	v_mfma_f32_16x16x32_bf16 v[156:159], v[100:103], v[164:167], v[156:159]
	v_mfma_f32_16x16x32_bf16 v[148:151], v[92:95], v[172:175], v[148:151]
	v_mfma_f32_16x16x32_bf16 v[144:147], v[100:103], v[172:175], v[144:147]
	v_mfma_f32_16x16x32_bf16 v[140:143], v[92:95], v[192:195], v[140:143]
	v_mfma_f32_16x16x32_bf16 v[136:139], v[100:103], v[192:195], v[136:139]
	v_mfma_f32_16x16x32_bf16 v[132:135], v[92:95], v[200:203], v[132:135]
	v_mfma_f32_16x16x32_bf16 v[128:131], v[100:103], v[200:203], v[128:131]
	s_setprio 0
	s_setprio 1
	v_mfma_f32_16x16x32_bf16 v[60:63], v[108:111], v[152:155], 0
	v_mfma_f32_16x16x32_bf16 v[56:59], v[116:119], v[152:155], 0
	v_mfma_f32_16x16x32_bf16 v[52:55], v[108:111], v[168:171], 0
	v_mfma_f32_16x16x32_bf16 v[48:51], v[116:119], v[168:171], 0
	v_mfma_f32_16x16x32_bf16 v[44:47], v[108:111], v[188:191], 0
	v_mfma_f32_16x16x32_bf16 v[40:43], v[116:119], v[188:191], 0
	v_mfma_f32_16x16x32_bf16 v[36:39], v[108:111], v[196:199], 0
	v_mfma_f32_16x16x32_bf16 v[32:35], v[116:119], v[196:199], 0
	v_mfma_f32_16x16x32_bf16 v[60:63], v[112:115], v[164:167], v[60:63]
	v_mfma_f32_16x16x32_bf16 v[56:59], v[120:123], v[164:167], v[56:59]
	v_mfma_f32_16x16x32_bf16 v[52:55], v[112:115], v[172:175], v[52:55]
	v_mfma_f32_16x16x32_bf16 v[48:51], v[120:123], v[172:175], v[48:51]
	v_mfma_f32_16x16x32_bf16 v[44:47], v[112:115], v[192:195], v[44:47]
	v_mfma_f32_16x16x32_bf16 v[40:43], v[120:123], v[192:195], v[40:43]
	v_mfma_f32_16x16x32_bf16 v[36:39], v[112:115], v[200:203], v[36:39]
	v_mfma_f32_16x16x32_bf16 v[32:35], v[120:123], v[200:203], v[32:35]
	s_setprio 0
	s_barrier
	s_add_i32 s50, s50, s39
	s_mov_b32 m0, s50
	ds_read_b128 v[152:155], v224 offset:16384
	ds_read_b128 v[164:167], v224 offset:17408
	ds_read_b128 v[168:171], v224 offset:18432
	ds_read_b128 v[172:175], v224 offset:19456
	ds_read_b128 v[188:191], v224 offset:20480
	ds_read_b128 v[192:195], v224 offset:21504
	ds_read_b128 v[196:199], v224 offset:22528
	ds_read_b128 v[200:203], v224 offset:23552
	global_load_lds_dwordx4 v176, s[12:13]
	s_add_i32 m0, s50, 0x2000
	s_add_u32 s50, s12, 0x80000
	s_addc_u32 s51, s13, 0
	s_add_i32 s53, s53, s39
	global_load_lds_dwordx4 v178, s[12:13]
	s_mov_b32 m0, s53
	s_nop 0
	global_load_lds_dwordx4 v176, s[50:51]
	s_add_i32 m0, s53, 0x2000
	s_nop 0
	global_load_lds_dwordx4 v178, s[50:51]
	s_add_u32 s62, s14, 0x80
	s_addc_u32 s63, s15, 0
	s_mov_b32 m0, s42
	s_nop 0
	global_load_lds_dwordx4 v182, s[14:15]
	s_mov_b32 m0, s43
	s_nop 0
	global_load_lds_dwordx4 v180, s[14:15]
	s_waitcnt vmcnt(8)
	s_waitcnt lgkmcnt(0)
	s_barrier
	s_setprio 1
	s_waitcnt lgkmcnt(0)
	v_mfma_f32_16x16x32_bf16 v[124:127], v[88:91], v[152:155], 0
	v_mfma_f32_16x16x32_bf16 v[104:107], v[96:99], v[152:155], 0
	v_mfma_f32_16x16x32_bf16 v[84:87], v[88:91], v[168:171], 0
	v_mfma_f32_16x16x32_bf16 v[80:83], v[96:99], v[168:171], 0
	v_mfma_f32_16x16x32_bf16 v[76:79], v[88:91], v[188:191], 0
	v_mfma_f32_16x16x32_bf16 v[72:75], v[96:99], v[188:191], 0
	v_mfma_f32_16x16x32_bf16 v[68:71], v[88:91], v[196:199], 0
	v_mfma_f32_16x16x32_bf16 v[64:67], v[96:99], v[196:199], 0
	v_mfma_f32_16x16x32_bf16 v[124:127], v[92:95], v[164:167], v[124:127]
	v_mfma_f32_16x16x32_bf16 v[104:107], v[100:103], v[164:167], v[104:107]
	v_mfma_f32_16x16x32_bf16 v[84:87], v[92:95], v[172:175], v[84:87]
	v_mfma_f32_16x16x32_bf16 v[80:83], v[100:103], v[172:175], v[80:83]
	v_mfma_f32_16x16x32_bf16 v[76:79], v[92:95], v[192:195], v[76:79]
	v_mfma_f32_16x16x32_bf16 v[72:75], v[100:103], v[192:195], v[72:75]
	v_mfma_f32_16x16x32_bf16 v[68:71], v[92:95], v[200:203], v[68:71]
	v_mfma_f32_16x16x32_bf16 v[64:67], v[100:103], v[200:203], v[64:67]
	s_setprio 0
	s_setprio 1
	v_mfma_f32_16x16x32_bf16 v[28:31], v[108:111], v[152:155], 0
	v_mfma_f32_16x16x32_bf16 v[24:27], v[116:119], v[152:155], 0
	v_mfma_f32_16x16x32_bf16 v[20:23], v[108:111], v[168:171], 0
	v_mfma_f32_16x16x32_bf16 v[16:19], v[116:119], v[168:171], 0
	v_mfma_f32_16x16x32_bf16 v[12:15], v[108:111], v[188:191], 0
	v_mfma_f32_16x16x32_bf16 v[8:11], v[116:119], v[188:191], 0
	v_mfma_f32_16x16x32_bf16 v[4:7], v[108:111], v[196:199], 0
	v_mfma_f32_16x16x32_bf16 v[0:3], v[116:119], v[196:199], 0
	v_mfma_f32_16x16x32_bf16 v[28:31], v[112:115], v[164:167], v[28:31]
	v_mfma_f32_16x16x32_bf16 v[24:27], v[120:123], v[164:167], v[24:27]
	v_mfma_f32_16x16x32_bf16 v[20:23], v[112:115], v[172:175], v[20:23]
	v_mfma_f32_16x16x32_bf16 v[16:19], v[120:123], v[172:175], v[16:19]
	v_mfma_f32_16x16x32_bf16 v[12:15], v[112:115], v[192:195], v[12:15]
	v_mfma_f32_16x16x32_bf16 v[8:11], v[120:123], v[192:195], v[8:11]
	v_mfma_f32_16x16x32_bf16 v[4:7], v[112:115], v[200:203], v[4:7]
	v_mfma_f32_16x16x32_bf16 v[0:3], v[120:123], v[200:203], v[0:3]
	s_setprio 0
	s_barrier
	s_add_i32 s50, 0, 0x18000
	s_add_i32 s51, 0, 0x1c000
	v_add_u32_e32 v100, s50, v222
	v_add_u32_e32 v120, s51, v222
	ds_read_b128 v[88:91], v100
	ds_read_b128 v[92:95], v100 offset:1024
	ds_read_b128 v[96:99], v100 offset:2048
	ds_read_b128 v[100:103], v100 offset:3072
	ds_read_b128 v[108:111], v120
	ds_read_b128 v[112:115], v120 offset:1024
	ds_read_b128 v[116:119], v120 offset:2048
	ds_read_b128 v[120:123], v120 offset:3072
	s_add_u32 s14, s14, 0x80000
	s_addc_u32 s15, s15, 0
	s_mov_b32 m0, s44
	ds_read_b128 v[152:155], v224 offset:32768
	ds_read_b128 v[164:167], v224 offset:33792
	ds_read_b128 v[168:171], v224 offset:34816
	ds_read_b128 v[172:175], v224 offset:35840
	ds_read_b128 v[188:191], v224 offset:36864
	ds_read_b128 v[192:195], v224 offset:37888
	ds_read_b128 v[196:199], v224 offset:38912
	ds_read_b128 v[200:203], v224 offset:39936
	global_load_lds_dwordx4 v182, s[14:15]
	s_mov_b32 m0, s45
	s_nop 0
	global_load_lds_dwordx4 v180, s[14:15]
	s_waitcnt vmcnt(8)
	s_waitcnt lgkmcnt(0)
	s_barrier
	s_setprio 1
	s_waitcnt lgkmcnt(0)
	v_mfma_f32_16x16x32_bf16 v[160:163], v[88:91], v[152:155], v[160:163]
	v_mfma_f32_16x16x32_bf16 v[156:159], v[96:99], v[152:155], v[156:159]
	v_mfma_f32_16x16x32_bf16 v[148:151], v[88:91], v[168:171], v[148:151]
	v_mfma_f32_16x16x32_bf16 v[144:147], v[96:99], v[168:171], v[144:147]
	v_mfma_f32_16x16x32_bf16 v[140:143], v[88:91], v[188:191], v[140:143]
	v_mfma_f32_16x16x32_bf16 v[136:139], v[96:99], v[188:191], v[136:139]
	v_mfma_f32_16x16x32_bf16 v[132:135], v[88:91], v[196:199], v[132:135]
	v_mfma_f32_16x16x32_bf16 v[128:131], v[96:99], v[196:199], v[128:131]
	v_mfma_f32_16x16x32_bf16 v[160:163], v[92:95], v[164:167], v[160:163]
	v_mfma_f32_16x16x32_bf16 v[156:159], v[100:103], v[164:167], v[156:159]
	v_mfma_f32_16x16x32_bf16 v[148:151], v[92:95], v[172:175], v[148:151]
	v_mfma_f32_16x16x32_bf16 v[144:147], v[100:103], v[172:175], v[144:147]
	v_mfma_f32_16x16x32_bf16 v[140:143], v[92:95], v[192:195], v[140:143]
	v_mfma_f32_16x16x32_bf16 v[136:139], v[100:103], v[192:195], v[136:139]
	v_mfma_f32_16x16x32_bf16 v[132:135], v[92:95], v[200:203], v[132:135]
	v_mfma_f32_16x16x32_bf16 v[128:131], v[100:103], v[200:203], v[128:131]
	s_setprio 0
	s_setprio 1
	v_mfma_f32_16x16x32_bf16 v[60:63], v[108:111], v[152:155], v[60:63]
	v_mfma_f32_16x16x32_bf16 v[56:59], v[116:119], v[152:155], v[56:59]
	v_mfma_f32_16x16x32_bf16 v[52:55], v[108:111], v[168:171], v[52:55]
	v_mfma_f32_16x16x32_bf16 v[48:51], v[116:119], v[168:171], v[48:51]
	v_mfma_f32_16x16x32_bf16 v[44:47], v[108:111], v[188:191], v[44:47]
	v_mfma_f32_16x16x32_bf16 v[40:43], v[116:119], v[188:191], v[40:43]
	v_mfma_f32_16x16x32_bf16 v[36:39], v[108:111], v[196:199], v[36:39]
	v_mfma_f32_16x16x32_bf16 v[32:35], v[116:119], v[196:199], v[32:35]
	v_mfma_f32_16x16x32_bf16 v[60:63], v[112:115], v[164:167], v[60:63]
	v_mfma_f32_16x16x32_bf16 v[56:59], v[120:123], v[164:167], v[56:59]
	v_mfma_f32_16x16x32_bf16 v[52:55], v[112:115], v[172:175], v[52:55]
	v_mfma_f32_16x16x32_bf16 v[48:51], v[120:123], v[172:175], v[48:51]
	v_mfma_f32_16x16x32_bf16 v[44:47], v[112:115], v[192:195], v[44:47]
	v_mfma_f32_16x16x32_bf16 v[40:43], v[120:123], v[192:195], v[40:43]
	v_mfma_f32_16x16x32_bf16 v[36:39], v[112:115], v[200:203], v[36:39]
	v_mfma_f32_16x16x32_bf16 v[32:35], v[120:123], v[200:203], v[32:35]
	s_setprio 0
	s_barrier
	s_add_i32 s14, s50, s39
	s_mov_b32 m0, s14
	ds_read_b128 v[152:155], v224 offset:49152
	ds_read_b128 v[164:167], v224 offset:50176
	ds_read_b128 v[168:171], v224 offset:51200
	ds_read_b128 v[172:175], v224 offset:52224
	ds_read_b128 v[188:191], v224 offset:53248
	ds_read_b128 v[192:195], v224 offset:54272
	ds_read_b128 v[196:199], v224 offset:55296
	ds_read_b128 v[200:203], v224 offset:56320
	s_add_u32 s98, s12, 0x80
	s_addc_u32 s99, s13, 0
	global_load_lds_dwordx4 v176, s[98:99]
	s_add_i32 m0, s14, 0x2000
	s_add_u32 s12, s12, 0x80080
	s_addc_u32 s13, s13, 0
	s_add_i32 s14, s51, s39
	s_add_u32 s98, s12, 0xfff80000
	s_addc_u32 s99, s13, -1
	global_load_lds_dwordx4 v178, s[98:99]
	s_mov_b32 m0, s14
	s_nop 0
	global_load_lds_dwordx4 v176, s[12:13]
	s_add_i32 m0, s14, 0x2000
	s_nop 0
	global_load_lds_dwordx4 v178, s[12:13]
	s_mov_b32 m0, s61
	s_nop 0
	global_load_lds_dwordx4 v182, s[62:63]
	s_mov_b32 m0, s64
	s_nop 0
	global_load_lds_dwordx4 v180, s[62:63]
	s_waitcnt vmcnt(8)
	s_waitcnt lgkmcnt(0)
	s_barrier
	s_setprio 1
	s_waitcnt lgkmcnt(0)
	v_mfma_f32_16x16x32_bf16 v[124:127], v[88:91], v[152:155], v[124:127]
	v_mfma_f32_16x16x32_bf16 v[104:107], v[96:99], v[152:155], v[104:107]
	v_mfma_f32_16x16x32_bf16 v[84:87], v[88:91], v[168:171], v[84:87]
	v_mfma_f32_16x16x32_bf16 v[80:83], v[96:99], v[168:171], v[80:83]
	v_mfma_f32_16x16x32_bf16 v[76:79], v[88:91], v[188:191], v[76:79]
	v_mfma_f32_16x16x32_bf16 v[72:75], v[96:99], v[188:191], v[72:75]
	v_mfma_f32_16x16x32_bf16 v[68:71], v[88:91], v[196:199], v[68:71]
	v_mfma_f32_16x16x32_bf16 v[64:67], v[96:99], v[196:199], v[64:67]
	v_mfma_f32_16x16x32_bf16 v[124:127], v[92:95], v[164:167], v[124:127]
	v_mfma_f32_16x16x32_bf16 v[104:107], v[100:103], v[164:167], v[104:107]
	v_mfma_f32_16x16x32_bf16 v[84:87], v[92:95], v[172:175], v[84:87]
	v_mfma_f32_16x16x32_bf16 v[80:83], v[100:103], v[172:175], v[80:83]
	v_mfma_f32_16x16x32_bf16 v[76:79], v[92:95], v[192:195], v[76:79]
	v_mfma_f32_16x16x32_bf16 v[72:75], v[100:103], v[192:195], v[72:75]
	v_mfma_f32_16x16x32_bf16 v[68:71], v[92:95], v[200:203], v[68:71]
	v_mfma_f32_16x16x32_bf16 v[64:67], v[100:103], v[200:203], v[64:67]
	s_setprio 0
	s_setprio 1
	v_mfma_f32_16x16x32_bf16 v[28:31], v[108:111], v[152:155], v[28:31]
	v_mfma_f32_16x16x32_bf16 v[24:27], v[116:119], v[152:155], v[24:27]
	v_mfma_f32_16x16x32_bf16 v[20:23], v[108:111], v[168:171], v[20:23]
	v_mfma_f32_16x16x32_bf16 v[16:19], v[116:119], v[168:171], v[16:19]
	v_mfma_f32_16x16x32_bf16 v[12:15], v[108:111], v[188:191], v[12:15]
	v_mfma_f32_16x16x32_bf16 v[8:11], v[116:119], v[188:191], v[8:11]
	v_mfma_f32_16x16x32_bf16 v[4:7], v[108:111], v[196:199], v[4:7]
	v_mfma_f32_16x16x32_bf16 v[0:3], v[116:119], v[196:199], v[0:3]
	v_mfma_f32_16x16x32_bf16 v[28:31], v[112:115], v[164:167], v[28:31]
	v_mfma_f32_16x16x32_bf16 v[24:27], v[120:123], v[164:167], v[24:27]
	v_mfma_f32_16x16x32_bf16 v[20:23], v[112:115], v[172:175], v[20:23]
	v_mfma_f32_16x16x32_bf16 v[16:19], v[120:123], v[172:175], v[16:19]
	v_mfma_f32_16x16x32_bf16 v[12:15], v[112:115], v[192:195], v[12:15]
	v_mfma_f32_16x16x32_bf16 v[8:11], v[120:123], v[192:195], v[8:11]
	v_mfma_f32_16x16x32_bf16 v[4:7], v[112:115], v[200:203], v[4:7]
	v_mfma_f32_16x16x32_bf16 v[0:3], v[120:123], v[200:203], v[0:3]
	s_setprio 0
	s_barrier
	s_add_i32 s33, s33, 2
	s_add_u32 s0, s0, 0x100
	s_addc_u32 s1, s1, 0
	s_add_u32 s26, s26, 0x100
	s_addc_u32 s27, s27, 0
	s_cmp_gt_u32 s33, 29

.LBB0_1159:
	s_add_u32 s2, s30, 0x100
	s_addc_u32 s3, s31, 0
	s_mov_b32 s14, -2
	s_waitcnt lgkmcnt(0)
	s_add_u32 s6, s0, 0x100
	s_addc_u32 s7, s1, 0
	s_add_i32 s15, 0, 0x10000
	s_cmpk_eq_i32 s14, 0x54
	s_cselect_b32 s13, s69, s7
	s_cselect_b32 s12, s68, s6
	s_cselect_b32 s9, s31, s3
	s_cselect_b32 s8, s30, s2
	s_add_i32 s20, 0, 0x14000
	v_add_u32_e32 v116, s15, v204
	v_add_u32_e32 v156, s20, v204
	ds_read_b128 v[100:103], v116
	ds_read_b128 v[108:111], v116 offset:1024
	ds_read_b128 v[112:115], v116 offset:2048
	ds_read_b128 v[116:119], v116 offset:3072
	ds_read_b128 v[136:139], v156
	ds_read_b128 v[148:151], v156 offset:1024
	ds_read_b128 v[152:155], v156 offset:2048
	ds_read_b128 v[156:159], v156 offset:3072
	s_add_i32 m0, s28, 0xc000
	ds_read_b128 v[160:163], v223
	ds_read_b128 v[164:167], v223 offset:1024
	ds_read_b128 v[168:171], v223 offset:2048
	ds_read_b128 v[172:175], v223 offset:3072
	ds_read_b128 v[200:203], v223 offset:4096
	ds_read_b128 v[226:229], v223 offset:5120
	ds_read_b128 v[230:233], v223 offset:6144
	ds_read_b128 v[234:237], v223 offset:7168
	global_load_lds_dwordx4 v196, s[0:1]
	s_add_i32 m0, s28, 0xe000
	s_nop 0
	global_load_lds_dwordx4 v198, s[0:1]
	s_waitcnt vmcnt(8)
	s_waitcnt lgkmcnt(0)
	s_barrier
	s_setprio 1
	s_waitcnt lgkmcnt(0)
	v_mfma_f32_16x16x32_bf16 v[144:147], v[100:103], v[160:163], 0
	v_mfma_f32_16x16x32_bf16 v[140:143], v[112:115], v[160:163], 0
	v_mfma_f32_16x16x32_bf16 v[124:127], v[100:103], v[168:171], 0
	v_mfma_f32_16x16x32_bf16 v[120:123], v[112:115], v[168:171], 0
	v_mfma_f32_16x16x32_bf16 v[92:95], v[100:103], v[200:203], 0
	v_mfma_f32_16x16x32_bf16 v[88:91], v[112:115], v[200:203], 0
	v_mfma_f32_16x16x32_bf16 v[76:79], v[100:103], v[230:233], 0
	v_mfma_f32_16x16x32_bf16 v[72:75], v[112:115], v[230:233], 0
	v_mfma_f32_16x16x32_bf16 v[144:147], v[108:111], v[164:167], v[144:147]
	v_mfma_f32_16x16x32_bf16 v[140:143], v[116:119], v[164:167], v[140:143]
	v_mfma_f32_16x16x32_bf16 v[124:127], v[108:111], v[172:175], v[124:127]
	v_mfma_f32_16x16x32_bf16 v[120:123], v[116:119], v[172:175], v[120:123]
	v_mfma_f32_16x16x32_bf16 v[92:95], v[108:111], v[226:229], v[92:95]
	v_mfma_f32_16x16x32_bf16 v[88:91], v[116:119], v[226:229], v[88:91]
	v_mfma_f32_16x16x32_bf16 v[76:79], v[108:111], v[234:237], v[76:79]
	v_mfma_f32_16x16x32_bf16 v[72:75], v[116:119], v[234:237], v[72:75]
	s_setprio 0
	s_setprio 1
	v_mfma_f32_16x16x32_bf16 v[132:135], v[136:139], v[160:163], 0
	v_mfma_f32_16x16x32_bf16 v[128:131], v[152:155], v[160:163], 0
	v_mfma_f32_16x16x32_bf16 v[104:107], v[136:139], v[168:171], 0
	v_mfma_f32_16x16x32_bf16 v[96:99], v[152:155], v[168:171], 0
	v_mfma_f32_16x16x32_bf16 v[84:87], v[136:139], v[200:203], 0
	v_mfma_f32_16x16x32_bf16 v[80:83], v[152:155], v[200:203], 0
	v_mfma_f32_16x16x32_bf16 v[68:71], v[136:139], v[230:233], 0
	v_mfma_f32_16x16x32_bf16 v[64:67], v[152:155], v[230:233], 0
	v_mfma_f32_16x16x32_bf16 v[132:135], v[148:151], v[164:167], v[132:135]
	v_mfma_f32_16x16x32_bf16 v[128:131], v[156:159], v[164:167], v[128:131]
	v_mfma_f32_16x16x32_bf16 v[104:107], v[148:151], v[172:175], v[104:107]
	v_mfma_f32_16x16x32_bf16 v[96:99], v[156:159], v[172:175], v[96:99]
	v_mfma_f32_16x16x32_bf16 v[84:87], v[148:151], v[226:229], v[84:87]
	v_mfma_f32_16x16x32_bf16 v[80:83], v[156:159], v[226:229], v[80:83]
	v_mfma_f32_16x16x32_bf16 v[68:71], v[148:151], v[234:237], v[68:71]
	v_mfma_f32_16x16x32_bf16 v[64:67], v[156:159], v[234:237], v[64:67]
	s_setprio 0
	s_barrier
	s_add_i32 s0, s15, s27
	s_mov_b32 m0, s0
	ds_read_b128 v[160:163], v223 offset:16384
	ds_read_b128 v[164:167], v223 offset:17408
	ds_read_b128 v[168:171], v223 offset:18432
	ds_read_b128 v[172:175], v223 offset:19456
	ds_read_b128 v[200:203], v223 offset:20480
	ds_read_b128 v[226:229], v223 offset:21504
	ds_read_b128 v[230:233], v223 offset:22528
	ds_read_b128 v[234:237], v223 offset:23552
	global_load_lds_dwordx4 v176, s[8:9]
	s_add_i32 m0, s0, 0x2000
	s_add_u32 s0, s8, 0x160000
	s_addc_u32 s1, s9, 0
	s_add_i32 s15, s20, s27
	global_load_lds_dwordx4 v182, s[8:9]
	s_mov_b32 m0, s15
	s_nop 0
	global_load_lds_dwordx4 v176, s[0:1]
	s_add_i32 m0, s15, 0x2000
	s_nop 0
	global_load_lds_dwordx4 v182, s[0:1]
	s_mov_b32 m0, s28
	s_nop 0
	global_load_lds_dwordx4 v178, s[12:13]
	s_mov_b32 m0, s29
	s_nop 0
	global_load_lds_dwordx4 v180, s[12:13]
	s_waitcnt vmcnt(8)
	s_waitcnt lgkmcnt(0)
	s_barrier
	s_setprio 1
	s_waitcnt lgkmcnt(0)
	v_mfma_f32_16x16x32_bf16 v[60:63], v[100:103], v[160:163], 0
	v_mfma_f32_16x16x32_bf16 v[56:59], v[112:115], v[160:163], 0
	v_mfma_f32_16x16x32_bf16 v[44:47], v[100:103], v[168:171], 0
	v_mfma_f32_16x16x32_bf16 v[40:43], v[112:115], v[168:171], 0
	v_mfma_f32_16x16x32_bf16 v[28:31], v[100:103], v[200:203], 0
	v_mfma_f32_16x16x32_bf16 v[24:27], v[112:115], v[200:203], 0
	v_mfma_f32_16x16x32_bf16 v[12:15], v[100:103], v[230:233], 0
	v_mfma_f32_16x16x32_bf16 v[8:11], v[112:115], v[230:233], 0
	v_mfma_f32_16x16x32_bf16 v[60:63], v[108:111], v[164:167], v[60:63]
	v_mfma_f32_16x16x32_bf16 v[56:59], v[116:119], v[164:167], v[56:59]
	v_mfma_f32_16x16x32_bf16 v[44:47], v[108:111], v[172:175], v[44:47]
	v_mfma_f32_16x16x32_bf16 v[40:43], v[116:119], v[172:175], v[40:43]
	v_mfma_f32_16x16x32_bf16 v[28:31], v[108:111], v[226:229], v[28:31]
	v_mfma_f32_16x16x32_bf16 v[24:27], v[116:119], v[226:229], v[24:27]
	v_mfma_f32_16x16x32_bf16 v[12:15], v[108:111], v[234:237], v[12:15]
	v_mfma_f32_16x16x32_bf16 v[8:11], v[116:119], v[234:237], v[8:11]
	s_setprio 0
	s_setprio 1
	v_mfma_f32_16x16x32_bf16 v[52:55], v[136:139], v[160:163], 0
	v_mfma_f32_16x16x32_bf16 v[48:51], v[152:155], v[160:163], 0
	v_mfma_f32_16x16x32_bf16 v[36:39], v[136:139], v[168:171], 0
	v_mfma_f32_16x16x32_bf16 v[32:35], v[152:155], v[168:171], 0
	v_mfma_f32_16x16x32_bf16 v[20:23], v[136:139], v[200:203], 0
	v_mfma_f32_16x16x32_bf16 v[16:19], v[152:155], v[200:203], 0
	v_mfma_f32_16x16x32_bf16 v[4:7], v[136:139], v[230:233], 0
	v_mfma_f32_16x16x32_bf16 v[0:3], v[152:155], v[230:233], 0
	v_mfma_f32_16x16x32_bf16 v[52:55], v[148:151], v[164:167], v[52:55]
	v_mfma_f32_16x16x32_bf16 v[48:51], v[156:159], v[164:167], v[48:51]
	v_mfma_f32_16x16x32_bf16 v[36:39], v[148:151], v[172:175], v[36:39]
	v_mfma_f32_16x16x32_bf16 v[32:35], v[156:159], v[172:175], v[32:35]
	v_mfma_f32_16x16x32_bf16 v[20:23], v[148:151], v[226:229], v[20:23]
	v_mfma_f32_16x16x32_bf16 v[16:19], v[156:159], v[226:229], v[16:19]
	v_mfma_f32_16x16x32_bf16 v[4:7], v[148:151], v[234:237], v[4:7]
	v_mfma_f32_16x16x32_bf16 v[0:3], v[156:159], v[234:237], v[0:3]
	s_setprio 0
	s_barrier
	s_add_i32 s15, 0, 0x18000
	s_add_i32 s20, 0, 0x1c000
	v_add_u32_e32 v116, s15, v204
	v_add_u32_e32 v156, s20, v204
	ds_read_b128 v[100:103], v116
	ds_read_b128 v[108:111], v116 offset:1024
	ds_read_b128 v[112:115], v116 offset:2048
	ds_read_b128 v[116:119], v116 offset:3072
	ds_read_b128 v[136:139], v156
	ds_read_b128 v[148:151], v156 offset:1024
	ds_read_b128 v[152:155], v156 offset:2048
	ds_read_b128 v[156:159], v156 offset:3072
	s_add_u32 s0, s12, 0x160000
	s_addc_u32 s1, s13, 0
	s_mov_b32 m0, s38
	ds_read_b128 v[160:163], v223 offset:32768
	ds_read_b128 v[164:167], v223 offset:33792
	ds_read_b128 v[168:171], v223 offset:34816
	ds_read_b128 v[172:175], v223 offset:35840
	ds_read_b128 v[200:203], v223 offset:36864
	ds_read_b128 v[226:229], v223 offset:37888
	ds_read_b128 v[230:233], v223 offset:38912
	ds_read_b128 v[234:237], v223 offset:39936
	global_load_lds_dwordx4 v178, s[0:1]
	s_mov_b32 m0, s39
	s_nop 0
	global_load_lds_dwordx4 v180, s[0:1]
	s_waitcnt vmcnt(8)
	s_waitcnt lgkmcnt(0)
	s_barrier
	s_setprio 1
	s_waitcnt lgkmcnt(0)
	v_mfma_f32_16x16x32_bf16 v[144:147], v[100:103], v[160:163], v[144:147]
	v_mfma_f32_16x16x32_bf16 v[140:143], v[112:115], v[160:163], v[140:143]
	v_mfma_f32_16x16x32_bf16 v[124:127], v[100:103], v[168:171], v[124:127]
	v_mfma_f32_16x16x32_bf16 v[120:123], v[112:115], v[168:171], v[120:123]
	v_mfma_f32_16x16x32_bf16 v[92:95], v[100:103], v[200:203], v[92:95]
	v_mfma_f32_16x16x32_bf16 v[88:91], v[112:115], v[200:203], v[88:91]
	v_mfma_f32_16x16x32_bf16 v[76:79], v[100:103], v[230:233], v[76:79]
	v_mfma_f32_16x16x32_bf16 v[72:75], v[112:115], v[230:233], v[72:75]
	v_mfma_f32_16x16x32_bf16 v[144:147], v[108:111], v[164:167], v[144:147]
	v_mfma_f32_16x16x32_bf16 v[140:143], v[116:119], v[164:167], v[140:143]
	v_mfma_f32_16x16x32_bf16 v[124:127], v[108:111], v[172:175], v[124:127]
	v_mfma_f32_16x16x32_bf16 v[120:123], v[116:119], v[172:175], v[120:123]
	v_mfma_f32_16x16x32_bf16 v[92:95], v[108:111], v[226:229], v[92:95]
	v_mfma_f32_16x16x32_bf16 v[88:91], v[116:119], v[226:229], v[88:91]
	v_mfma_f32_16x16x32_bf16 v[76:79], v[108:111], v[234:237], v[76:79]
	v_mfma_f32_16x16x32_bf16 v[72:75], v[116:119], v[234:237], v[72:75]
	s_setprio 0
	s_setprio 1
	v_mfma_f32_16x16x32_bf16 v[132:135], v[136:139], v[160:163], v[132:135]
	v_mfma_f32_16x16x32_bf16 v[128:131], v[152:155], v[160:163], v[128:131]
	v_mfma_f32_16x16x32_bf16 v[104:107], v[136:139], v[168:171], v[104:107]
	v_mfma_f32_16x16x32_bf16 v[96:99], v[152:155], v[168:171], v[96:99]
	v_mfma_f32_16x16x32_bf16 v[84:87], v[136:139], v[200:203], v[84:87]
	v_mfma_f32_16x16x32_bf16 v[80:83], v[152:155], v[200:203], v[80:83]
	v_mfma_f32_16x16x32_bf16 v[68:71], v[136:139], v[230:233], v[68:71]
	v_mfma_f32_16x16x32_bf16 v[64:67], v[152:155], v[230:233], v[64:67]
	v_mfma_f32_16x16x32_bf16 v[132:135], v[148:151], v[164:167], v[132:135]
	v_mfma_f32_16x16x32_bf16 v[128:131], v[156:159], v[164:167], v[128:131]
	v_mfma_f32_16x16x32_bf16 v[104:107], v[148:151], v[172:175], v[104:107]
	v_mfma_f32_16x16x32_bf16 v[96:99], v[156:159], v[172:175], v[96:99]
	v_mfma_f32_16x16x32_bf16 v[84:87], v[148:151], v[226:229], v[84:87]
	v_mfma_f32_16x16x32_bf16 v[80:83], v[156:159], v[226:229], v[80:83]
	v_mfma_f32_16x16x32_bf16 v[68:71], v[148:151], v[234:237], v[68:71]
	v_mfma_f32_16x16x32_bf16 v[64:67], v[156:159], v[234:237], v[64:67]
	s_setprio 0
	s_barrier
	s_add_i32 s0, s15, s27
	s_mov_b32 m0, s0
	ds_read_b128 v[160:163], v223 offset:49152
	ds_read_b128 v[164:167], v223 offset:50176
	ds_read_b128 v[168:171], v223 offset:51200
	ds_read_b128 v[172:175], v223 offset:52224
	ds_read_b128 v[200:203], v223 offset:53248
	ds_read_b128 v[226:229], v223 offset:54272
	ds_read_b128 v[230:233], v223 offset:55296
	ds_read_b128 v[234:237], v223 offset:56320
	s_add_u32 s98, s8, 0x80
	s_addc_u32 s99, s9, 0
	global_load_lds_dwordx4 v176, s[98:99]
	s_add_i32 m0, s0, 0x2000
	s_add_u32 s0, s8, 0x160080
	s_addc_u32 s1, s9, 0
	s_add_i32 s8, s20, s27
	s_add_u32 s98, s0, 0xffea0000
	s_addc_u32 s99, s1, -1
	global_load_lds_dwordx4 v182, s[98:99]
	s_mov_b32 m0, s8
	s_nop 0
	global_load_lds_dwordx4 v176, s[0:1]
	s_add_i32 m0, s8, 0x2000
	s_nop 0
	global_load_lds_dwordx4 v182, s[0:1]
	s_mov_b32 m0, s44
	s_nop 0
	s_add_u32 s98, s12, 0x80
	s_addc_u32 s99, s13, 0
	global_load_lds_dwordx4 v178, s[98:99]
	s_mov_b32 m0, s45
	s_nop 0
	s_add_u32 s98, s12, 0x80
	s_addc_u32 s99, s13, 0
	global_load_lds_dwordx4 v180, s[98:99]
	s_waitcnt vmcnt(8)
	s_waitcnt lgkmcnt(0)
	s_barrier
	s_setprio 1
	s_waitcnt lgkmcnt(0)
	v_mfma_f32_16x16x32_bf16 v[60:63], v[100:103], v[160:163], v[60:63]
	v_mfma_f32_16x16x32_bf16 v[56:59], v[112:115], v[160:163], v[56:59]
	v_mfma_f32_16x16x32_bf16 v[44:47], v[100:103], v[168:171], v[44:47]
	v_mfma_f32_16x16x32_bf16 v[40:43], v[112:115], v[168:171], v[40:43]
	v_mfma_f32_16x16x32_bf16 v[28:31], v[100:103], v[200:203], v[28:31]
	v_mfma_f32_16x16x32_bf16 v[24:27], v[112:115], v[200:203], v[24:27]
	v_mfma_f32_16x16x32_bf16 v[12:15], v[100:103], v[230:233], v[12:15]
	v_mfma_f32_16x16x32_bf16 v[8:11], v[112:115], v[230:233], v[8:11]
	v_mfma_f32_16x16x32_bf16 v[60:63], v[108:111], v[164:167], v[60:63]
	v_mfma_f32_16x16x32_bf16 v[56:59], v[116:119], v[164:167], v[56:59]
	v_mfma_f32_16x16x32_bf16 v[44:47], v[108:111], v[172:175], v[44:47]
	v_mfma_f32_16x16x32_bf16 v[40:43], v[116:119], v[172:175], v[40:43]
	v_mfma_f32_16x16x32_bf16 v[28:31], v[108:111], v[226:229], v[28:31]
	v_mfma_f32_16x16x32_bf16 v[24:27], v[116:119], v[226:229], v[24:27]
	v_mfma_f32_16x16x32_bf16 v[12:15], v[108:111], v[234:237], v[12:15]
	v_mfma_f32_16x16x32_bf16 v[8:11], v[116:119], v[234:237], v[8:11]
	s_setprio 0
	s_setprio 1
	v_mfma_f32_16x16x32_bf16 v[52:55], v[136:139], v[160:163], v[52:55]
	v_mfma_f32_16x16x32_bf16 v[48:51], v[152:155], v[160:163], v[48:51]
	v_mfma_f32_16x16x32_bf16 v[36:39], v[136:139], v[168:171], v[36:39]
	v_mfma_f32_16x16x32_bf16 v[32:35], v[152:155], v[168:171], v[32:35]
	v_mfma_f32_16x16x32_bf16 v[20:23], v[136:139], v[200:203], v[20:23]
	v_mfma_f32_16x16x32_bf16 v[16:19], v[152:155], v[200:203], v[16:19]
	v_mfma_f32_16x16x32_bf16 v[4:7], v[136:139], v[230:233], v[4:7]
	v_mfma_f32_16x16x32_bf16 v[0:3], v[152:155], v[230:233], v[0:3]
	v_mfma_f32_16x16x32_bf16 v[52:55], v[148:151], v[164:167], v[52:55]
	v_mfma_f32_16x16x32_bf16 v[48:51], v[156:159], v[164:167], v[48:51]
	v_mfma_f32_16x16x32_bf16 v[36:39], v[148:151], v[172:175], v[36:39]
	v_mfma_f32_16x16x32_bf16 v[32:35], v[156:159], v[172:175], v[32:35]
	v_mfma_f32_16x16x32_bf16 v[20:23], v[148:151], v[226:229], v[20:23]
	v_mfma_f32_16x16x32_bf16 v[16:19], v[156:159], v[226:229], v[16:19]
	v_mfma_f32_16x16x32_bf16 v[4:7], v[148:151], v[234:237], v[4:7]
	v_mfma_f32_16x16x32_bf16 v[0:3], v[156:159], v[234:237], v[0:3]
	s_setprio 0
	s_barrier
	s_add_i32 s14, s14, 2
	s_add_u32 s2, s2, 0x100
	s_addc_u32 s3, s3, 0
	s_cmpk_gt_u32 s14, 0x55
	s_mov_b64 s[0:1], s[6:7]
